# Hyena FFT: pass-2 / inverse pass-1 LDS reads issued in butterfly consumption order
# baseline (speedup 1.0000x reference)
; #define WG_SYNC() do { asm volatile("s_waitcnt lgkmcnt(0)" ::: "memory"); __builtin_amdgcn_s_barrier(); asm volatile("" ::: "memory"); } while (0)
; template <bool INV> __device__ __forceinline__ void dft16(f32x2 (&x)[16]) {
;     constexpr float C1 = 0.92387953251128674f, S1 = 0.38268343236508977f, C2 = 0.70710678118654752f;
; #pragma unroll
;     for (int b = 0; b < 4; ++b) dft4<INV>(x[b], x[4 + b], x[8 + b], x[12 + b]);
; __device__ __forceinline__ void hyena_fft(LAS unsigned char* lds, int layer, int G, const int wave_s) {
;     ...
;         for (int c = c_lo; c < c_hi; ++c) { const int unit = c >> 2, jc = c & 3;
;             WG_SYNC();
;             { f32x2 x[16]; const unsigned* tf = TF + (size_t)c * SEQ; const unsigned* tb = TB + (size_t)c * SEQ;
; #pragma unroll
;               for (int r = 0; r < 8; ++r) { const unsigned w = tf[n2 + 512 * r]; x[r] = (f32x2){bf_lo(w), bf_hi(w)}; }
; #pragma unroll
;               for (int r = 8; r < 16; ++r) { const int l = FN - 512 * r - n2; const unsigned w = l < SEQ ? tb[l] : 0u; x[r] = (f32x2){bf_lo(w), bf_hi(w)}; }
;               __builtin_amdgcn_sched_barrier(0); fft_fwd1<false>(x, Fb, n2, w1p); __builtin_amdgcn_sched_barrier(0); }
;             hy_stage(pl0, PHY, 2 * (HY / 4) + unit, jc, tid); __builtin_amdgcn_sched_barrier(0); hy_stage(pl1, PHY, unit, jc, tid); __builtin_amdgcn_sched_barrier(0);
.Lhfft_loop:
	s_lshr_b32 s43, s80, 2
	s_mul_i32 s73, s43, 0x11000
	s_and_b32 s43, s80, 2
	s_lshl_b32 s43, s43, 1
	s_add_u32 s73, s73, s43
	s_and_b32 s43, s80, 1
	s_mov_b32 s15, 0x1000c0c
	s_cmp_eq_u32 s43, 0
	s_cselect_b32 s15, s15, 0x3020c0c
	s_lshl_b32 s43, s80, 14
	s_add_u32 s46, s36, s43
	s_addc_u32 s47, s37, 0
	s_add_u32 s50, s46, 0x4000000
	s_addc_u32 s51, s47, 0
	s_waitcnt lgkmcnt(0)
	s_barrier
	s_add_u32 s60, s46, 0
	s_addc_u32 s61, s47, 0
	global_load_dword v176, v212, s[60:61]
	global_load_dword v178, v212, s[60:61] offset:2048
	s_add_u32 s60, s46, 0x1000
	s_addc_u32 s61, s47, 0
	global_load_dword v180, v212, s[60:61]
	global_load_dword v182, v212, s[60:61] offset:2048
	s_add_u32 s60, s46, 0x2000
	s_addc_u32 s61, s47, 0
	global_load_dword v184, v212, s[60:61]
	global_load_dword v186, v212, s[60:61] offset:2048
	s_add_u32 s60, s46, 0x3000
	s_addc_u32 s61, s47, 0
	global_load_dword v188, v212, s[60:61]
	global_load_dword v166, v212, s[60:61] offset:2048
	s_add_u32 s62, s50, 0x3000
	s_addc_u32 s63, s51, 0
	global_load_dword v177, v214, s[62:63] offset:2048
	global_load_dword v179, v214, s[62:63]
	s_add_u32 s62, s50, 0x2000
	s_addc_u32 s63, s51, 0
	global_load_dword v181, v214, s[62:63] offset:2048
	global_load_dword v183, v214, s[62:63]
	s_add_u32 s62, s50, 0x1000
	s_addc_u32 s63, s51, 0
	global_load_dword v185, v214, s[62:63] offset:2048
	global_load_dword v187, v214, s[62:63]
	s_add_u32 s62, s50, 0
	s_addc_u32 s63, s51, 0
	global_load_dword v189, v214, s[62:63] offset:2048
	global_load_dword v167, v214, s[62:63]
	s_add_u32 s56, s38, s73
	s_addc_u32 s57, s39, 0
	s_add_u32 s56, s56, 0x2200000
	s_addc_u32 s57, s57, 0
	global_load_dwordx3 v[58:60], v216, s[56:57]
	global_load_dwordx3 v[62:64], v218, s[56:57]
	global_load_dwordx3 v[66:68], v220, s[56:57]
	global_load_dwordx3 v[70:72], v222, s[56:57]
	global_load_dwordx3 v[74:76], v240, s[56:57]
	global_load_dwordx3 v[78:80], v242, s[56:57]
	global_load_dwordx3 v[82:84], v244, s[56:57]
	global_load_dwordx3 v[86:88], v61, s[56:57]
	s_waitcnt vmcnt(23)
	v_and_b32_e32 v101, 0xffff0000, v176
	v_lshlrev_b32_e32 v100, 16, v176
	s_waitcnt vmcnt(22)
	v_and_b32_e32 v103, 0xffff0000, v178
	v_lshlrev_b32_e32 v102, 16, v178
	s_waitcnt vmcnt(21)
	v_and_b32_e32 v105, 0xffff0000, v180
	v_lshlrev_b32_e32 v104, 16, v180
	s_waitcnt vmcnt(20)
	v_and_b32_e32 v107, 0xffff0000, v182
	v_lshlrev_b32_e32 v106, 16, v182
	s_waitcnt vmcnt(19)
	v_and_b32_e32 v109, 0xffff0000, v184
	v_lshlrev_b32_e32 v108, 16, v184
	s_waitcnt vmcnt(18)
	v_and_b32_e32 v111, 0xffff0000, v186
	v_lshlrev_b32_e32 v110, 16, v186
	s_waitcnt vmcnt(17)
	v_and_b32_e32 v113, 0xffff0000, v188
	v_lshlrev_b32_e32 v112, 16, v188
	s_waitcnt vmcnt(16)
	v_and_b32_e32 v115, 0xffff0000, v166
	v_lshlrev_b32_e32 v114, 16, v166
	s_waitcnt vmcnt(15)
	v_cndmask_b32_e64 v177, v177, 0, s[10:11]
	v_and_b32_e32 v117, 0xffff0000, v177
	v_lshlrev_b32_e32 v116, 16, v177
	s_waitcnt vmcnt(14)
	v_and_b32_e32 v119, 0xffff0000, v179
	v_lshlrev_b32_e32 v118, 16, v179
	s_waitcnt vmcnt(13)
	v_and_b32_e32 v121, 0xffff0000, v181
	v_lshlrev_b32_e32 v120, 16, v181
	s_waitcnt vmcnt(12)
	v_and_b32_e32 v123, 0xffff0000, v183
	v_lshlrev_b32_e32 v122, 16, v183
	s_waitcnt vmcnt(11)
	v_and_b32_e32 v125, 0xffff0000, v185
	v_lshlrev_b32_e32 v124, 16, v185
	s_waitcnt vmcnt(10)
	v_and_b32_e32 v127, 0xffff0000, v187
	v_lshlrev_b32_e32 v126, 16, v187
	s_waitcnt vmcnt(9)
	v_and_b32_e32 v129, 0xffff0000, v189
	v_lshlrev_b32_e32 v128, 16, v189
	s_waitcnt vmcnt(8)
	v_and_b32_e32 v131, 0xffff0000, v167
	v_lshlrev_b32_e32 v130, 16, v167
	v_pk_add_f32 v[168:169], v[100:101], v[116:117]
	v_pk_add_f32 v[174:175], v[100:101], v[116:117] neg_lo:[0,1] neg_hi:[0,1]
	v_pk_add_f32 v[176:177], v[108:109], v[124:125]
	v_pk_add_f32 v[178:179], v[108:109], v[124:125] neg_lo:[0,1] neg_hi:[0,1]
	v_pk_add_f32 v[100:101], v[168:169], v[176:177]
	v_pk_add_f32 v[116:117], v[168:169], v[176:177] neg_lo:[0,1] neg_hi:[0,1]
	v_pk_add_f32 v[108:109], v[174:175], v[178:179] op_sel:[0,1] op_sel_hi:[1,0] neg_hi:[0,1]
	v_pk_add_f32 v[124:125], v[174:175], v[178:179] op_sel:[0,1] op_sel_hi:[1,0] neg_lo:[0,1]
	v_pk_add_f32 v[180:181], v[102:103], v[118:119]
	v_pk_add_f32 v[182:183], v[102:103], v[118:119] neg_lo:[0,1] neg_hi:[0,1]
	v_pk_add_f32 v[184:185], v[110:111], v[126:127]
	v_pk_add_f32 v[186:187], v[110:111], v[126:127] neg_lo:[0,1] neg_hi:[0,1]
	v_pk_add_f32 v[102:103], v[180:181], v[184:185]
	v_pk_add_f32 v[118:119], v[180:181], v[184:185] neg_lo:[0,1] neg_hi:[0,1]
	v_pk_add_f32 v[110:111], v[182:183], v[186:187] op_sel:[0,1] op_sel_hi:[1,0] neg_hi:[0,1]
	v_pk_add_f32 v[126:127], v[182:183], v[186:187] op_sel:[0,1] op_sel_hi:[1,0] neg_lo:[0,1]
	v_pk_add_f32 v[188:189], v[104:105], v[120:121]
	v_pk_add_f32 v[166:167], v[104:105], v[120:121] neg_lo:[0,1] neg_hi:[0,1]
	v_pk_add_f32 v[168:169], v[112:113], v[128:129]
	v_pk_add_f32 v[174:175], v[112:113], v[128:129] neg_lo:[0,1] neg_hi:[0,1]
	v_pk_add_f32 v[104:105], v[188:189], v[168:169]
	v_pk_add_f32 v[120:121], v[188:189], v[168:169] neg_lo:[0,1] neg_hi:[0,1]
	v_pk_add_f32 v[112:113], v[166:167], v[174:175] op_sel:[0,1] op_sel_hi:[1,0] neg_hi:[0,1]
	v_pk_add_f32 v[128:129], v[166:167], v[174:175] op_sel:[0,1] op_sel_hi:[1,0] neg_lo:[0,1]
	v_pk_add_f32 v[176:177], v[106:107], v[122:123]
	v_pk_add_f32 v[178:179], v[106:107], v[122:123] neg_lo:[0,1] neg_hi:[0,1]
	v_pk_add_f32 v[180:181], v[114:115], v[130:131]
	v_pk_add_f32 v[182:183], v[114:115], v[130:131] neg_lo:[0,1] neg_hi:[0,1]
	v_pk_add_f32 v[106:107], v[176:177], v[180:181]
	v_pk_add_f32 v[122:123], v[176:177], v[180:181] neg_lo:[0,1] neg_hi:[0,1]
	v_pk_add_f32 v[114:115], v[178:179], v[182:183] op_sel:[0,1] op_sel_hi:[1,0] neg_hi:[0,1]
; #define LAS __attribute__((address_space(3)))
; __device__ __forceinline__ f32x2 cmul(f32x2 a, f32x2 b) { return (f32x2){a.x * b.x - a.y * b.y, a.x * b.y + a.y * b.x}; }
; template <bool INV> __device__ __forceinline__ f32x2 cmul_tw(f32x2 a, f32x2 w) { return INV ? cmulc(a, w) : cmul(a, w); }
; template <bool INV> __device__ __forceinline__ void dft16(f32x2 (&x)[16]) {
;     constexpr float C1 = 0.92387953251128674f, S1 = 0.38268343236508977f, C2 = 0.70710678118654752f;
; #pragma unroll
;     for (int b = 0; b < 4; ++b) dft4<INV>(x[b], x[4 + b], x[8 + b], x[12 + b]);
;     const f32x2 w1 = {C1, -S1}, w2 = {C2, -C2}, w3 = {S1, -C1}, w4 = {0.f, -1.f}, w6 = {-C2, -C2}, w9 = {-C1, S1};
;     x[4 * 1 + 1] = cmul_tw<INV>(x[5], w1); x[4 * 1 + 2] = cmul_tw<INV>(x[6], w2); x[4 * 1 + 3] = cmul_tw<INV>(x[7], w3);
;     x[4 * 2 + 1] = cmul_tw<INV>(x[9], w2); x[4 * 2 + 2] = cmul_tw<INV>(x[10], w4); x[4 * 2 + 3] = cmul_tw<INV>(x[11], w6);
;     x[4 * 3 + 1] = cmul_tw<INV>(x[13], w3); x[4 * 3 + 2] = cmul_tw<INV>(x[14], w6); x[4 * 3 + 3] = cmul_tw<INV>(x[15], w9);
; #pragma unroll
;     for (int c = 0; c < 4; ++c) dft4<INV>(x[4 * c], x[4 * c + 1], x[4 * c + 2], x[4 * c + 3]);
;     f32x2 y[16];
; #pragma unroll
;     for (int k = 0; k < 16; ++k) y[k] = x[4 * (k & 3) + (k >> 2)];
; #pragma unroll
;     for (int k = 0; k < 16; ++k) x[k] = y[k];
; }
; template <bool LO> __device__ __forceinline__ void fft_fwd1(f32x2 (&x)[16], LAS f32x2* B, int n2, const f32x2 (&w)[16]) {
;     asm volatile("" : "+v"(n2));
;     if (LO) dft16_fwd_lo(x); else dft16<false>(x);
;     B[fpad(n2)] = x[0];
; #pragma unroll
;     for (int k = 1; k < 16; ++k) B[fpad(512 * k + n2)] = cmul(x[k], w[k]);
; }
	v_pk_add_f32 v[130:131], v[178:179], v[182:183] op_sel:[0,1] op_sel_hi:[1,0] neg_lo:[0,1]
	v_pk_mul_f32 v[184:185], v[110:111], s[68:69] op_sel:[1,1] op_sel_hi:[0,1]
	v_pk_fma_f32 v[110:111], v[110:111], s[68:69], v[184:185] op_sel_hi:[1,0,1] neg_lo:[0,0,1]
	v_pk_mul_f32 v[186:187], v[112:113], s[84:85] op_sel:[1,1] op_sel_hi:[0,1]
	v_pk_fma_f32 v[112:113], v[112:113], s[84:85], v[186:187] op_sel_hi:[1,0,1] neg_lo:[0,0,1]
	v_pk_mul_f32 v[188:189], v[114:115], s[88:89] op_sel:[1,1] op_sel_hi:[0,1]
	v_pk_fma_f32 v[114:115], v[114:115], s[88:89], v[188:189] op_sel_hi:[1,0,1] neg_lo:[0,0,1]
	v_pk_mul_f32 v[166:167], v[118:119], s[84:85] op_sel:[1,1] op_sel_hi:[0,1]
	v_pk_fma_f32 v[118:119], v[118:119], s[84:85], v[166:167] op_sel_hi:[1,0,1] neg_lo:[0,0,1]
	v_pk_mul_f32 v[168:169], v[122:123], s[90:91] op_sel:[1,1] op_sel_hi:[0,1]
	v_pk_fma_f32 v[122:123], v[122:123], s[90:91], v[168:169] op_sel_hi:[1,0,1] neg_lo:[0,0,1]
	v_pk_mul_f32 v[174:175], v[126:127], s[88:89] op_sel:[1,1] op_sel_hi:[0,1]
	v_pk_fma_f32 v[126:127], v[126:127], s[88:89], v[174:175] op_sel_hi:[1,0,1] neg_lo:[0,0,1]
	v_pk_mul_f32 v[176:177], v[128:129], s[90:91] op_sel:[1,1] op_sel_hi:[0,1]
	v_pk_fma_f32 v[128:129], v[128:129], s[90:91], v[176:177] op_sel_hi:[1,0,1] neg_lo:[0,0,1]
	v_pk_mul_f32 v[178:179], v[130:131], s[98:99] op_sel:[1,1] op_sel_hi:[0,1]
	v_pk_fma_f32 v[130:131], v[130:131], s[98:99], v[178:179] op_sel_hi:[1,0,1] neg_lo:[0,0,1]
	v_pk_add_f32 v[180:181], v[100:101], v[104:105]
	v_pk_add_f32 v[182:183], v[100:101], v[104:105] neg_lo:[0,1] neg_hi:[0,1]
	v_pk_add_f32 v[184:185], v[102:103], v[106:107]
	v_pk_add_f32 v[186:187], v[102:103], v[106:107] neg_lo:[0,1] neg_hi:[0,1]
	v_pk_add_f32 v[100:101], v[180:181], v[184:185]
	v_pk_add_f32 v[104:105], v[180:181], v[184:185] neg_lo:[0,1] neg_hi:[0,1]
	v_pk_add_f32 v[102:103], v[182:183], v[186:187] op_sel:[0,1] op_sel_hi:[1,0] neg_hi:[0,1]
	v_pk_add_f32 v[106:107], v[182:183], v[186:187] op_sel:[0,1] op_sel_hi:[1,0] neg_lo:[0,1]
	v_pk_add_f32 v[188:189], v[108:109], v[112:113]
	v_pk_add_f32 v[166:167], v[108:109], v[112:113] neg_lo:[0,1] neg_hi:[0,1]
	v_pk_add_f32 v[168:169], v[110:111], v[114:115]
	v_pk_add_f32 v[174:175], v[110:111], v[114:115] neg_lo:[0,1] neg_hi:[0,1]
	v_pk_add_f32 v[108:109], v[188:189], v[168:169]
	v_pk_add_f32 v[112:113], v[188:189], v[168:169] neg_lo:[0,1] neg_hi:[0,1]
	v_pk_add_f32 v[110:111], v[166:167], v[174:175] op_sel:[0,1] op_sel_hi:[1,0] neg_hi:[0,1]
	v_pk_add_f32 v[114:115], v[166:167], v[174:175] op_sel:[0,1] op_sel_hi:[1,0] neg_lo:[0,1]
	v_pk_add_f32 v[176:177], v[116:117], v[120:121] op_sel:[0,1] op_sel_hi:[1,0] neg_hi:[0,1]
	v_pk_add_f32 v[178:179], v[116:117], v[120:121] op_sel:[0,1] op_sel_hi:[1,0] neg_lo:[0,1]
	v_pk_add_f32 v[180:181], v[118:119], v[122:123]
	v_pk_add_f32 v[182:183], v[118:119], v[122:123] neg_lo:[0,1] neg_hi:[0,1]
	v_pk_add_f32 v[116:117], v[176:177], v[180:181]
	v_pk_add_f32 v[120:121], v[176:177], v[180:181] neg_lo:[0,1] neg_hi:[0,1]
	v_pk_add_f32 v[118:119], v[178:179], v[182:183] op_sel:[0,1] op_sel_hi:[1,0] neg_hi:[0,1]
	v_pk_add_f32 v[122:123], v[178:179], v[182:183] op_sel:[0,1] op_sel_hi:[1,0] neg_lo:[0,1]
	v_pk_add_f32 v[184:185], v[124:125], v[128:129]
	v_pk_add_f32 v[186:187], v[124:125], v[128:129] neg_lo:[0,1] neg_hi:[0,1]
	v_pk_add_f32 v[188:189], v[126:127], v[130:131]
	v_pk_add_f32 v[166:167], v[126:127], v[130:131] neg_lo:[0,1] neg_hi:[0,1]
	v_pk_add_f32 v[124:125], v[184:185], v[188:189]
	v_pk_add_f32 v[128:129], v[184:185], v[188:189] neg_lo:[0,1] neg_hi:[0,1]
	v_pk_add_f32 v[126:127], v[186:187], v[166:167] op_sel:[0,1] op_sel_hi:[1,0] neg_hi:[0,1]
	v_pk_add_f32 v[130:131], v[186:187], v[166:167] op_sel:[0,1] op_sel_hi:[1,0] neg_lo:[0,1]
	v_add_u32_e32 v65, 0x10800, v3
	ds_write_b64 v65, v[100:101]
	v_pk_mul_f32 v[174:175], v[108:109], v[6:7] op_sel:[1,1] op_sel_hi:[0,1]
	v_pk_fma_f32 v[168:169], v[108:109], v[6:7], v[174:175] op_sel_hi:[1,0,1] neg_lo:[0,0,1]
	ds_write_b64 v65, v[168:169] offset:4224
	v_pk_mul_f32 v[178:179], v[116:117], v[8:9] op_sel:[1,1] op_sel_hi:[0,1]
	v_pk_fma_f32 v[176:177], v[116:117], v[8:9], v[178:179] op_sel_hi:[1,0,1] neg_lo:[0,0,1]
	ds_write_b64 v65, v[176:177] offset:8448
	v_pk_mul_f32 v[182:183], v[124:125], v[10:11] op_sel:[1,1] op_sel_hi:[0,1]
	v_pk_fma_f32 v[180:181], v[124:125], v[10:11], v[182:183] op_sel_hi:[1,0,1] neg_lo:[0,0,1]
	ds_write_b64 v65, v[180:181] offset:12672
	v_pk_mul_f32 v[186:187], v[102:103], v[12:13] op_sel:[1,1] op_sel_hi:[0,1]
	v_pk_fma_f32 v[184:185], v[102:103], v[12:13], v[186:187] op_sel_hi:[1,0,1] neg_lo:[0,0,1]
	ds_write_b64 v65, v[184:185] offset:16896
	v_pk_mul_f32 v[166:167], v[110:111], v[14:15] op_sel:[1,1] op_sel_hi:[0,1]
	v_pk_fma_f32 v[188:189], v[110:111], v[14:15], v[166:167] op_sel_hi:[1,0,1] neg_lo:[0,0,1]
	ds_write_b64 v65, v[188:189] offset:21120
	v_pk_mul_f32 v[168:169], v[118:119], v[16:17] op_sel:[1,1] op_sel_hi:[0,1]
	v_pk_fma_f32 v[174:175], v[118:119], v[16:17], v[168:169] op_sel_hi:[1,0,1] neg_lo:[0,0,1]
	ds_write_b64 v65, v[174:175] offset:25344
	v_pk_mul_f32 v[176:177], v[126:127], v[18:19] op_sel:[1,1] op_sel_hi:[0,1]
	v_pk_fma_f32 v[178:179], v[126:127], v[18:19], v[176:177] op_sel_hi:[1,0,1] neg_lo:[0,0,1]
	ds_write_b64 v65, v[178:179] offset:29568
	v_pk_mul_f32 v[180:181], v[104:105], v[20:21] op_sel:[1,1] op_sel_hi:[0,1]
	v_pk_fma_f32 v[182:183], v[104:105], v[20:21], v[180:181] op_sel_hi:[1,0,1] neg_lo:[0,0,1]
	ds_write_b64 v65, v[182:183] offset:33792
	v_pk_mul_f32 v[184:185], v[112:113], v[22:23] op_sel:[1,1] op_sel_hi:[0,1]
	v_pk_fma_f32 v[186:187], v[112:113], v[22:23], v[184:185] op_sel_hi:[1,0,1] neg_lo:[0,0,1]
	ds_write_b64 v65, v[186:187] offset:38016
	v_pk_mul_f32 v[188:189], v[120:121], v[24:25] op_sel:[1,1] op_sel_hi:[0,1]
	v_pk_fma_f32 v[166:167], v[120:121], v[24:25], v[188:189] op_sel_hi:[1,0,1] neg_lo:[0,0,1]
	ds_write_b64 v65, v[166:167] offset:42240
	v_pk_mul_f32 v[174:175], v[128:129], v[26:27] op_sel:[1,1] op_sel_hi:[0,1]
	v_pk_fma_f32 v[168:169], v[128:129], v[26:27], v[174:175] op_sel_hi:[1,0,1] neg_lo:[0,0,1]
	ds_write_b64 v65, v[168:169] offset:46464
	v_pk_mul_f32 v[178:179], v[106:107], v[28:29] op_sel:[1,1] op_sel_hi:[0,1]
	v_pk_fma_f32 v[176:177], v[106:107], v[28:29], v[178:179] op_sel_hi:[1,0,1] neg_lo:[0,0,1]
	ds_write_b64 v65, v[176:177] offset:50688
	v_pk_mul_f32 v[182:183], v[114:115], v[30:31] op_sel:[1,1] op_sel_hi:[0,1]
	v_pk_fma_f32 v[180:181], v[114:115], v[30:31], v[182:183] op_sel_hi:[1,0,1] neg_lo:[0,0,1]
	ds_write_b64 v65, v[180:181] offset:54912
	v_pk_mul_f32 v[186:187], v[122:123], v[32:33] op_sel:[1,1] op_sel_hi:[0,1]
	v_pk_fma_f32 v[184:185], v[122:123], v[32:33], v[186:187] op_sel_hi:[1,0,1] neg_lo:[0,0,1]
	ds_write_b64 v65, v[184:185] offset:59136
	v_pk_mul_f32 v[166:167], v[130:131], v[34:35] op_sel:[1,1] op_sel_hi:[0,1]
	v_pk_fma_f32 v[188:189], v[130:131], v[34:35], v[166:167] op_sel_hi:[1,0,1] neg_lo:[0,0,1]
	ds_write_b64 v65, v[188:189] offset:63360
	s_waitcnt vmcnt(7)
; #define LAS __attribute__((address_space(3)))
; #define WG_SYNC() do { asm volatile("s_waitcnt lgkmcnt(0)" ::: "memory"); __builtin_amdgcn_s_barrier(); asm volatile("" ::: "memory"); } while (0)
; __device__ __forceinline__ void hy_stage(LAS float* plane, const bf16_t* PHY, int cg, int jc, int tid) {
;     asm volatile("" : "+v"(tid));
;     const u32x4* src = (const u32x4*)(PHY + (size_t)cg * MT * 4);
; #pragma unroll
;     for (int k = 0; k < 8; ++k) { const int i = tid + 512 * k; const u32x4 v = src[i];
;         const unsigned w0 = (jc & 2) ? v.y : v.x, w1 = (jc & 2) ? v.w : v.z;
;         f32x2 o; o.x = (jc & 1) ? bf_hi(w0) : bf_lo(w0); o.y = (jc & 1) ? bf_hi(w1) : bf_lo(w1);
;         *(LAS f32x2*)(plane + 2 * i) = o; }
; }
; __device__ __forceinline__ void hy_sconv(const LAS float* plane, float w0, float w1, float w2, float cb, int n2, float (&u)[8][2]) {
;     asm volatile("" : "+v"(n2));
; #pragma unroll
;     for (int r = 0; r < 8; ++r)
; #pragma unroll
;         for (int b = 0; b < 2; ++b) { const int t = n2 + 512 * r, row = b * SEQ + t;
;             float a = cb + w1 * plane[row];
;             if (t > 0) a += w0 * plane[row - 1];
;             if (t < SEQ - 1) a += w2 * plane[row + 1];
;             u[r][b] = a; }
; }
; __device__ __forceinline__ void hyena_fft(LAS unsigned char* lds, int layer, int G, const int wave_s) {
;     ...
;             hy_stage(pl0, PHY, 2 * (HY / 4) + unit, jc, tid); __builtin_amdgcn_sched_barrier(0); hy_stage(pl1, PHY, unit, jc, tid); __builtin_amdgcn_sched_barrier(0);
;             WG_SYNC();
;             float uz[8][2], ux[8][2];
;             hy_sconv(pl0, cw[2 * HY + c], cw[3 * HY + 2 * HY + c], cw[6 * HY + 2 * HY + c], cb[2 * HY + c], n2, uz);
	v_perm_b32 v174, 0, v58, s15
	v_perm_b32 v175, 0, v60, s15
	ds_write_b64 v206, v[174:175]
	s_waitcnt vmcnt(6)
	v_perm_b32 v168, 0, v62, s15
	v_perm_b32 v169, 0, v64, s15
	ds_write_b64 v206, v[168:169] offset:4096
	s_waitcnt vmcnt(5)
	v_perm_b32 v178, 0, v66, s15
	v_perm_b32 v179, 0, v68, s15
	ds_write_b64 v206, v[178:179] offset:8192
	s_waitcnt vmcnt(4)
	v_perm_b32 v176, 0, v70, s15
	v_perm_b32 v177, 0, v72, s15
	ds_write_b64 v206, v[176:177] offset:12288
	s_waitcnt vmcnt(3)
	v_perm_b32 v182, 0, v74, s15
	v_perm_b32 v183, 0, v76, s15
	ds_write_b64 v206, v[182:183] offset:16384
	s_waitcnt vmcnt(2)
	v_perm_b32 v180, 0, v78, s15
	v_perm_b32 v181, 0, v80, s15
	ds_write_b64 v206, v[180:181] offset:20480
	s_waitcnt vmcnt(1)
	v_perm_b32 v186, 0, v82, s15
	v_perm_b32 v187, 0, v84, s15
	ds_write_b64 v206, v[186:187] offset:24576
	s_waitcnt vmcnt(0)
	v_perm_b32 v184, 0, v86, s15
	v_perm_b32 v185, 0, v88, s15
	ds_write_b64 v206, v[184:185] offset:28672
	s_add_u32 s56, s38, s73
	s_addc_u32 s57, s39, 0
	global_load_dwordx3 v[58:60], v216, s[56:57]
	global_load_dwordx3 v[62:64], v218, s[56:57]
	global_load_dwordx3 v[66:68], v220, s[56:57]
	global_load_dwordx3 v[70:72], v222, s[56:57]
	global_load_dwordx3 v[74:76], v240, s[56:57]
	global_load_dwordx3 v[78:80], v242, s[56:57]
	global_load_dwordx3 v[82:84], v244, s[56:57]
	global_load_dwordx3 v[86:88], v61, s[56:57]
	s_load_dwordx2 s[60:61], s[94:95], 0x48
	s_load_dwordx2 s[62:63], s[94:95], 0x50
	s_load_dwordx2 s[50:51], s[94:95], 0x88
	s_lshl_b32 s43, s80, 2
	s_mul_i32 s53, s76, 0x9000
	s_add_u32 s53, s53, s43
	s_mul_i32 s55, s76, 0x3000
	s_add_u32 s55, s55, s43
	s_waitcnt lgkmcnt(0)
	s_add_u32 s60, s60, s53
	s_addc_u32 s61, s61, 0
	s_add_u32 s62, s62, s55
	s_addc_u32 s63, s63, 0
	s_mul_i32 s53, s76, 0x2000
	s_add_u32 s53, s53, s43
	s_add_u32 s50, s50, s53
	s_addc_u32 s51, s51, 0
	s_load_dword s17, s[60:61], 0x2000
	s_load_dword s23, s[60:61], 0x5000
	s_load_dword s25, s[60:61], 0x8000
	s_load_dword s26, s[62:63], 0x2000
	s_waitcnt lgkmcnt(0)
	s_barrier
	v_mov_b32_e32 v166, s17
	v_mov_b32_e32 v167, s23
	v_mov_b32_e32 v188, s25
	v_mov_b32_e32 v189, s26
	ds_read_b32 v174, v208
	ds_read_b32 v168, v210
	ds_read_b32 v178, v208 offset:4
	ds_read_b32 v175, v208 offset:16384
	ds_read_b32 v169, v210 offset:16384
	ds_read_b32 v179, v208 offset:16388
	ds_read_b32 v176, v208 offset:2048
	ds_read_b32 v182, v208 offset:2044
	ds_read_b32 v180, v208 offset:2052
	ds_read_b32 v177, v208 offset:18432
	ds_read_b32 v183, v208 offset:18428
	ds_read_b32 v181, v208 offset:18436
	s_waitcnt lgkmcnt(10)
	v_cndmask_b32_e64 v168, v168, 0, s[10:11]
	s_waitcnt lgkmcnt(7)
	v_cndmask_b32_e64 v169, v169, 0, s[10:11]
	v_pk_fma_f32 v[132:133], v[166:167], v[174:175], v[188:189] op_sel:[1,0,1]
	v_pk_fma_f32 v[132:133], v[166:167], v[168:169], v[132:133] op_sel_hi:[0,1,1]
	s_waitcnt lgkmcnt(6)
	v_pk_fma_f32 v[132:133], v[188:189], v[178:179], v[132:133] op_sel_hi:[0,1,1]
	s_waitcnt lgkmcnt(2)
	v_pk_fma_f32 v[134:135], v[166:167], v[176:177], v[188:189] op_sel:[1,0,1]
	s_waitcnt lgkmcnt(1)
	v_pk_fma_f32 v[134:135], v[166:167], v[182:183], v[134:135] op_sel_hi:[0,1,1]
	s_waitcnt lgkmcnt(0)
	v_pk_fma_f32 v[134:135], v[188:189], v[180:181], v[134:135] op_sel_hi:[0,1,1]
	ds_read_b32 v186, v208 offset:4096
	ds_read_b32 v184, v208 offset:4092
	ds_read_b32 v174, v208 offset:4100
	ds_read_b32 v187, v208 offset:20480
	ds_read_b32 v185, v208 offset:20476
	ds_read_b32 v175, v208 offset:20484
	ds_read_b32 v168, v208 offset:6144
	ds_read_b32 v178, v208 offset:6140
	ds_read_b32 v176, v208 offset:6148
	ds_read_b32 v169, v208 offset:22528
	ds_read_b32 v179, v208 offset:22524
	ds_read_b32 v177, v208 offset:22532
	s_waitcnt lgkmcnt(8)
	v_pk_fma_f32 v[136:137], v[166:167], v[186:187], v[188:189] op_sel:[1,0,1]
	s_waitcnt lgkmcnt(7)
	v_pk_fma_f32 v[136:137], v[166:167], v[184:185], v[136:137] op_sel_hi:[0,1,1]
	s_waitcnt lgkmcnt(6)
	v_pk_fma_f32 v[136:137], v[188:189], v[174:175], v[136:137] op_sel_hi:[0,1,1]
	s_waitcnt lgkmcnt(2)
	v_pk_fma_f32 v[138:139], v[166:167], v[168:169], v[188:189] op_sel:[1,0,1]
	s_waitcnt lgkmcnt(1)
	v_pk_fma_f32 v[138:139], v[166:167], v[178:179], v[138:139] op_sel_hi:[0,1,1]
	s_waitcnt lgkmcnt(0)
	v_pk_fma_f32 v[138:139], v[188:189], v[176:177], v[138:139] op_sel_hi:[0,1,1]
	ds_read_b32 v182, v208 offset:8192
	ds_read_b32 v180, v208 offset:8188
	ds_read_b32 v186, v208 offset:8196
	ds_read_b32 v183, v208 offset:24576
	ds_read_b32 v181, v208 offset:24572
	ds_read_b32 v187, v208 offset:24580
	ds_read_b32 v184, v208 offset:10240
	ds_read_b32 v174, v208 offset:10236
	ds_read_b32 v168, v208 offset:10244
	ds_read_b32 v185, v208 offset:26624
	ds_read_b32 v175, v208 offset:26620
	ds_read_b32 v169, v208 offset:26628
	s_waitcnt lgkmcnt(8)
	v_pk_fma_f32 v[140:141], v[166:167], v[182:183], v[188:189] op_sel:[1,0,1]
	s_waitcnt lgkmcnt(7)
	v_pk_fma_f32 v[140:141], v[166:167], v[180:181], v[140:141] op_sel_hi:[0,1,1]
	s_waitcnt lgkmcnt(6)
	v_pk_fma_f32 v[140:141], v[188:189], v[186:187], v[140:141] op_sel_hi:[0,1,1]
	s_waitcnt lgkmcnt(2)
	v_pk_fma_f32 v[142:143], v[166:167], v[184:185], v[188:189] op_sel:[1,0,1]
	s_waitcnt lgkmcnt(1)
	v_pk_fma_f32 v[142:143], v[166:167], v[174:175], v[142:143] op_sel_hi:[0,1,1]
	s_waitcnt lgkmcnt(0)
	v_pk_fma_f32 v[142:143], v[188:189], v[168:169], v[142:143] op_sel_hi:[0,1,1]
	ds_read_b32 v178, v208 offset:12288
	ds_read_b32 v176, v208 offset:12284
	ds_read_b32 v182, v208 offset:12292
	ds_read_b32 v179, v208 offset:28672
	ds_read_b32 v177, v208 offset:28668
	ds_read_b32 v183, v208 offset:28676
	ds_read_b32 v180, v208 offset:14336
	ds_read_b32 v186, v208 offset:14332
	ds_read_b32 v184, v208 offset:14340
	ds_read_b32 v181, v208 offset:30720
	ds_read_b32 v187, v208 offset:30716
	ds_read_b32 v185, v208 offset:30724
	s_waitcnt lgkmcnt(8)
; #define LAS __attribute__((address_space(3)))
; __device__ __forceinline__ f32x2 cmul(f32x2 a, f32x2 b) { return (f32x2){a.x * b.x - a.y * b.y, a.x * b.y + a.y * b.x}; }
; __device__ __forceinline__ void fft_fwd2(LAS f32x2* B, const LAS f32x2* TW2, int tid) {
;     asm volatile("" : "+v"(tid));
;     const int b = tid >> 5, n2 = tid & 31, base = 512 * b + n2; f32x2 x[16];
; #pragma unroll
;     for (int r = 0; r < 16; ++r) x[r] = B[fpad(base + 32 * r)];
;     dft16<false>(x);
;     B[fpad(base)] = x[0];
; #pragma unroll
;     for (int k = 1; k < 16; ++k) B[fpad(base + 32 * k)] = cmul(x[k], TW2[k * 32 + n2]);
; }
; __device__ __forceinline__ void hy_stage(LAS float* plane, const bf16_t* PHY, int cg, int jc, int tid) {
;     asm volatile("" : "+v"(tid));
;     const u32x4* src = (const u32x4*)(PHY + (size_t)cg * MT * 4);
; #pragma unroll
;     for (int k = 0; k < 8; ++k) { const int i = tid + 512 * k; const u32x4 v = src[i];
;         const unsigned w0 = (jc & 2) ? v.y : v.x, w1 = (jc & 2) ? v.w : v.z;
;         f32x2 o; o.x = (jc & 1) ? bf_hi(w0) : bf_lo(w0); o.y = (jc & 1) ? bf_hi(w1) : bf_lo(w1);
;         *(LAS f32x2*)(plane + 2 * i) = o; }
; }
	v_pk_fma_f32 v[144:145], v[166:167], v[178:179], v[188:189] op_sel:[1,0,1]
	s_waitcnt lgkmcnt(7)
	v_pk_fma_f32 v[144:145], v[166:167], v[176:177], v[144:145] op_sel_hi:[0,1,1]
	s_waitcnt lgkmcnt(6)
	v_pk_fma_f32 v[144:145], v[188:189], v[182:183], v[144:145] op_sel_hi:[0,1,1]
	s_waitcnt lgkmcnt(3)
	v_cndmask_b32_e64 v184, v184, 0, s[28:29]
	s_waitcnt lgkmcnt(0)
	v_cndmask_b32_e64 v185, v185, 0, s[28:29]
	v_pk_fma_f32 v[146:147], v[166:167], v[180:181], v[188:189] op_sel:[1,0,1]
	v_pk_fma_f32 v[146:147], v[166:167], v[186:187], v[146:147] op_sel_hi:[0,1,1]
	v_pk_fma_f32 v[146:147], v[188:189], v[184:185], v[146:147] op_sel_hi:[0,1,1]
	s_load_dword s17, s[60:61], 0x0
	s_load_dword s23, s[60:61], 0x3000
	s_load_dword s25, s[60:61], 0x6000
	s_load_dword s26, s[62:63], 0x0
	s_waitcnt vmcnt(7)
	v_perm_b32 v174, 0, v58, s15
	v_perm_b32 v175, 0, v60, s15
	ds_write_b64 v206, v[174:175] offset:32768
	s_waitcnt vmcnt(6)
	v_perm_b32 v168, 0, v62, s15
	v_perm_b32 v169, 0, v64, s15
	ds_write_b64 v206, v[168:169] offset:36864
	s_waitcnt vmcnt(5)
	v_perm_b32 v178, 0, v66, s15
	v_perm_b32 v179, 0, v68, s15
	ds_write_b64 v206, v[178:179] offset:40960
	s_waitcnt vmcnt(4)
	v_perm_b32 v176, 0, v70, s15
	v_perm_b32 v177, 0, v72, s15
	ds_write_b64 v206, v[176:177] offset:45056
	s_waitcnt vmcnt(3)
	v_perm_b32 v182, 0, v74, s15
	v_perm_b32 v183, 0, v76, s15
	ds_write_b64 v206, v[182:183] offset:49152
	s_waitcnt vmcnt(2)
	v_perm_b32 v180, 0, v78, s15
	v_perm_b32 v181, 0, v80, s15
	ds_write_b64 v206, v[180:181] offset:53248
	s_waitcnt vmcnt(1)
	v_perm_b32 v186, 0, v82, s15
	v_perm_b32 v187, 0, v84, s15
	ds_write_b64 v206, v[186:187] offset:57344
	s_waitcnt vmcnt(0)
	v_perm_b32 v184, 0, v86, s15
	v_perm_b32 v185, 0, v88, s15
	ds_write_b64 v206, v[184:185] offset:61440
	s_add_u32 s56, s38, s73
	s_addc_u32 s57, s39, 0
	s_add_u32 s56, s56, 0x1100000
	s_addc_u32 s57, s57, 0
	global_load_dwordx3 v[58:60], v216, s[56:57]
	global_load_dwordx3 v[62:64], v218, s[56:57]
	global_load_dwordx3 v[66:68], v220, s[56:57]
	global_load_dwordx3 v[70:72], v222, s[56:57]
	global_load_dwordx3 v[74:76], v240, s[56:57]
	global_load_dwordx3 v[78:80], v242, s[56:57]
	global_load_dwordx3 v[82:84], v244, s[56:57]
	global_load_dwordx3 v[86:88], v61, s[56:57]
	v_add_u32_e32 v65, 0x10800, v5
	ds_read_b64 v[100:101], v65
	ds_read_b64 v[102:103], v65 offset:1056
	ds_read_b64 v[104:105], v65 offset:2112
	ds_read_b64 v[106:107], v65 offset:3168
	ds_read_b64 v[108:109], v65 offset:264
	ds_read_b64 v[110:111], v65 offset:1320
	ds_read_b64 v[112:113], v65 offset:2376
	ds_read_b64 v[114:115], v65 offset:3432
	ds_read_b64 v[116:117], v65 offset:528
	ds_read_b64 v[118:119], v65 offset:1584
	ds_read_b64 v[120:121], v65 offset:2640
	ds_read_b64 v[122:123], v65 offset:3696
	s_waitcnt lgkmcnt(8)
	ds_read_b64 v[124:125], v65 offset:792
	ds_read_b64 v[126:127], v65 offset:1848
	ds_read_b64 v[128:129], v65 offset:2904
	ds_read_b64 v[130:131], v65 offset:3960
	v_pk_add_f32 v[166:167], v[100:101], v[104:105]
	v_pk_add_f32 v[188:189], v[100:101], v[104:105] neg_lo:[0,1] neg_hi:[0,1]
	v_pk_add_f32 v[174:175], v[102:103], v[106:107]
	v_pk_add_f32 v[168:169], v[102:103], v[106:107] neg_lo:[0,1] neg_hi:[0,1]
	v_pk_add_f32 v[100:101], v[166:167], v[174:175]
	v_pk_add_f32 v[104:105], v[166:167], v[174:175] neg_lo:[0,1] neg_hi:[0,1]
	v_pk_add_f32 v[102:103], v[188:189], v[168:169] op_sel:[0,1] op_sel_hi:[1,0] neg_hi:[0,1]
	v_pk_add_f32 v[106:107], v[188:189], v[168:169] op_sel:[0,1] op_sel_hi:[1,0] neg_lo:[0,1]
	s_waitcnt lgkmcnt(9)
	v_pk_add_f32 v[178:179], v[108:109], v[112:113]
	v_pk_add_f32 v[176:177], v[108:109], v[112:113] neg_lo:[0,1] neg_hi:[0,1]
	s_waitcnt lgkmcnt(8)
	v_pk_add_f32 v[182:183], v[110:111], v[114:115]
	v_pk_add_f32 v[180:181], v[110:111], v[114:115] neg_lo:[0,1] neg_hi:[0,1]
	v_pk_add_f32 v[108:109], v[178:179], v[182:183]
	v_pk_add_f32 v[112:113], v[178:179], v[182:183] neg_lo:[0,1] neg_hi:[0,1]
	v_pk_add_f32 v[110:111], v[176:177], v[180:181] op_sel:[0,1] op_sel_hi:[1,0] neg_hi:[0,1]
	v_pk_add_f32 v[114:115], v[176:177], v[180:181] op_sel:[0,1] op_sel_hi:[1,0] neg_lo:[0,1]
	s_waitcnt lgkmcnt(5)
	v_pk_add_f32 v[186:187], v[116:117], v[120:121]
	v_pk_add_f32 v[184:185], v[116:117], v[120:121] neg_lo:[0,1] neg_hi:[0,1]
	s_waitcnt lgkmcnt(4)
	v_pk_add_f32 v[166:167], v[118:119], v[122:123]
	v_pk_add_f32 v[188:189], v[118:119], v[122:123] neg_lo:[0,1] neg_hi:[0,1]
	v_pk_add_f32 v[116:117], v[186:187], v[166:167]
	v_pk_add_f32 v[120:121], v[186:187], v[166:167] neg_lo:[0,1] neg_hi:[0,1]
	v_pk_add_f32 v[118:119], v[184:185], v[188:189] op_sel:[0,1] op_sel_hi:[1,0] neg_hi:[0,1]
	v_pk_add_f32 v[122:123], v[184:185], v[188:189] op_sel:[0,1] op_sel_hi:[1,0] neg_lo:[0,1]
	s_waitcnt lgkmcnt(1)
	v_pk_add_f32 v[174:175], v[124:125], v[128:129]
	v_pk_add_f32 v[168:169], v[124:125], v[128:129] neg_lo:[0,1] neg_hi:[0,1]
	s_waitcnt lgkmcnt(0)
; #define LAS __attribute__((address_space(3)))
; __device__ __forceinline__ f32x2 cmul(f32x2 a, f32x2 b) { return (f32x2){a.x * b.x - a.y * b.y, a.x * b.y + a.y * b.x}; }
; template <bool INV> __device__ __forceinline__ f32x2 cmul_tw(f32x2 a, f32x2 w) { return INV ? cmulc(a, w) : cmul(a, w); }
; template <bool INV> __device__ __forceinline__ void dft16(f32x2 (&x)[16]) {
;     constexpr float C1 = 0.92387953251128674f, S1 = 0.38268343236508977f, C2 = 0.70710678118654752f;
; #pragma unroll
;     for (int b = 0; b < 4; ++b) dft4<INV>(x[b], x[4 + b], x[8 + b], x[12 + b]);
;     const f32x2 w1 = {C1, -S1}, w2 = {C2, -C2}, w3 = {S1, -C1}, w4 = {0.f, -1.f}, w6 = {-C2, -C2}, w9 = {-C1, S1};
;     x[4 * 1 + 1] = cmul_tw<INV>(x[5], w1); x[4 * 1 + 2] = cmul_tw<INV>(x[6], w2); x[4 * 1 + 3] = cmul_tw<INV>(x[7], w3);
;     x[4 * 2 + 1] = cmul_tw<INV>(x[9], w2); x[4 * 2 + 2] = cmul_tw<INV>(x[10], w4); x[4 * 2 + 3] = cmul_tw<INV>(x[11], w6);
;     x[4 * 3 + 1] = cmul_tw<INV>(x[13], w3); x[4 * 3 + 2] = cmul_tw<INV>(x[14], w6); x[4 * 3 + 3] = cmul_tw<INV>(x[15], w9);
; #pragma unroll
;     for (int c = 0; c < 4; ++c) dft4<INV>(x[4 * c], x[4 * c + 1], x[4 * c + 2], x[4 * c + 3]);
;     f32x2 y[16];
; #pragma unroll
;     for (int k = 0; k < 16; ++k) y[k] = x[4 * (k & 3) + (k >> 2)];
; #pragma unroll
;     for (int k = 0; k < 16; ++k) x[k] = y[k];
; }
; __device__ __forceinline__ void fft_fwd2(LAS f32x2* B, const LAS f32x2* TW2, int tid) {
;     asm volatile("" : "+v"(tid));
;     const int b = tid >> 5, n2 = tid & 31, base = 512 * b + n2; f32x2 x[16];
; #pragma unroll
;     for (int r = 0; r < 16; ++r) x[r] = B[fpad(base + 32 * r)];
;     dft16<false>(x);
;     B[fpad(base)] = x[0];
; #pragma unroll
;     for (int k = 1; k < 16; ++k) B[fpad(base + 32 * k)] = cmul(x[k], TW2[k * 32 + n2]);
; }
	v_pk_add_f32 v[178:179], v[126:127], v[130:131]
	v_pk_add_f32 v[176:177], v[126:127], v[130:131] neg_lo:[0,1] neg_hi:[0,1]
	v_pk_add_f32 v[124:125], v[174:175], v[178:179]
	v_pk_add_f32 v[128:129], v[174:175], v[178:179] neg_lo:[0,1] neg_hi:[0,1]
	v_pk_add_f32 v[126:127], v[168:169], v[176:177] op_sel:[0,1] op_sel_hi:[1,0] neg_hi:[0,1]
	v_pk_add_f32 v[130:131], v[168:169], v[176:177] op_sel:[0,1] op_sel_hi:[1,0] neg_lo:[0,1]
	v_pk_mul_f32 v[182:183], v[110:111], s[68:69] op_sel:[1,1] op_sel_hi:[0,1]
	v_pk_fma_f32 v[110:111], v[110:111], s[68:69], v[182:183] op_sel_hi:[1,0,1] neg_lo:[0,0,1]
	v_pk_mul_f32 v[180:181], v[118:119], s[84:85] op_sel:[1,1] op_sel_hi:[0,1]
	v_pk_fma_f32 v[118:119], v[118:119], s[84:85], v[180:181] op_sel_hi:[1,0,1] neg_lo:[0,0,1]
	v_pk_mul_f32 v[186:187], v[126:127], s[88:89] op_sel:[1,1] op_sel_hi:[0,1]
	v_pk_fma_f32 v[126:127], v[126:127], s[88:89], v[186:187] op_sel_hi:[1,0,1] neg_lo:[0,0,1]
	v_pk_mul_f32 v[184:185], v[112:113], s[84:85] op_sel:[1,1] op_sel_hi:[0,1]
	v_pk_fma_f32 v[112:113], v[112:113], s[84:85], v[184:185] op_sel_hi:[1,0,1] neg_lo:[0,0,1]
	v_pk_mul_f32 v[166:167], v[128:129], s[90:91] op_sel:[1,1] op_sel_hi:[0,1]
	v_pk_fma_f32 v[128:129], v[128:129], s[90:91], v[166:167] op_sel_hi:[1,0,1] neg_lo:[0,0,1]
	v_pk_mul_f32 v[188:189], v[114:115], s[88:89] op_sel:[1,1] op_sel_hi:[0,1]
	v_pk_fma_f32 v[114:115], v[114:115], s[88:89], v[188:189] op_sel_hi:[1,0,1] neg_lo:[0,0,1]
	v_pk_mul_f32 v[174:175], v[122:123], s[90:91] op_sel:[1,1] op_sel_hi:[0,1]
	v_pk_fma_f32 v[122:123], v[122:123], s[90:91], v[174:175] op_sel_hi:[1,0,1] neg_lo:[0,0,1]
	v_pk_mul_f32 v[168:169], v[130:131], s[98:99] op_sel:[1,1] op_sel_hi:[0,1]
	v_pk_fma_f32 v[130:131], v[130:131], s[98:99], v[168:169] op_sel_hi:[1,0,1] neg_lo:[0,0,1]
	v_pk_add_f32 v[178:179], v[100:101], v[116:117]
	v_pk_add_f32 v[176:177], v[100:101], v[116:117] neg_lo:[0,1] neg_hi:[0,1]
	v_pk_add_f32 v[182:183], v[108:109], v[124:125]
	v_pk_add_f32 v[180:181], v[108:109], v[124:125] neg_lo:[0,1] neg_hi:[0,1]
	v_pk_add_f32 v[100:101], v[178:179], v[182:183]
	v_pk_add_f32 v[116:117], v[178:179], v[182:183] neg_lo:[0,1] neg_hi:[0,1]
	v_pk_add_f32 v[108:109], v[176:177], v[180:181] op_sel:[0,1] op_sel_hi:[1,0] neg_hi:[0,1]
	v_pk_add_f32 v[124:125], v[176:177], v[180:181] op_sel:[0,1] op_sel_hi:[1,0] neg_lo:[0,1]
	v_pk_add_f32 v[186:187], v[102:103], v[118:119]
	v_pk_add_f32 v[184:185], v[102:103], v[118:119] neg_lo:[0,1] neg_hi:[0,1]
	v_pk_add_f32 v[166:167], v[110:111], v[126:127]
	v_pk_add_f32 v[188:189], v[110:111], v[126:127] neg_lo:[0,1] neg_hi:[0,1]
	v_pk_add_f32 v[102:103], v[186:187], v[166:167]
	v_pk_add_f32 v[118:119], v[186:187], v[166:167] neg_lo:[0,1] neg_hi:[0,1]
	v_pk_add_f32 v[110:111], v[184:185], v[188:189] op_sel:[0,1] op_sel_hi:[1,0] neg_hi:[0,1]
	v_pk_add_f32 v[126:127], v[184:185], v[188:189] op_sel:[0,1] op_sel_hi:[1,0] neg_lo:[0,1]
	v_pk_add_f32 v[174:175], v[104:105], v[120:121] op_sel:[0,1] op_sel_hi:[1,0] neg_hi:[0,1]
	v_pk_add_f32 v[168:169], v[104:105], v[120:121] op_sel:[0,1] op_sel_hi:[1,0] neg_lo:[0,1]
	v_pk_add_f32 v[178:179], v[112:113], v[128:129]
	v_pk_add_f32 v[176:177], v[112:113], v[128:129] neg_lo:[0,1] neg_hi:[0,1]
	v_pk_add_f32 v[104:105], v[174:175], v[178:179]
	v_pk_add_f32 v[120:121], v[174:175], v[178:179] neg_lo:[0,1] neg_hi:[0,1]
	v_pk_add_f32 v[112:113], v[168:169], v[176:177] op_sel:[0,1] op_sel_hi:[1,0] neg_hi:[0,1]
	v_pk_add_f32 v[128:129], v[168:169], v[176:177] op_sel:[0,1] op_sel_hi:[1,0] neg_lo:[0,1]
	v_pk_add_f32 v[182:183], v[106:107], v[122:123]
	v_pk_add_f32 v[180:181], v[106:107], v[122:123] neg_lo:[0,1] neg_hi:[0,1]
	v_pk_add_f32 v[186:187], v[114:115], v[130:131]
	v_pk_add_f32 v[184:185], v[114:115], v[130:131] neg_lo:[0,1] neg_hi:[0,1]
	v_pk_add_f32 v[106:107], v[182:183], v[186:187]
	v_pk_add_f32 v[122:123], v[182:183], v[186:187] neg_lo:[0,1] neg_hi:[0,1]
	v_pk_add_f32 v[114:115], v[180:181], v[184:185] op_sel:[0,1] op_sel_hi:[1,0] neg_hi:[0,1]
	v_pk_add_f32 v[130:131], v[180:181], v[184:185] op_sel:[0,1] op_sel_hi:[1,0] neg_lo:[0,1]
	ds_write_b64 v65, v[100:101]
	ds_read_b64 v[166:167], v56 offset:256
	ds_read_b64 v[188:189], v56 offset:512
	ds_read_b64 v[174:175], v56 offset:768
	ds_read_b64 v[168:169], v56 offset:1024
	s_waitcnt lgkmcnt(3)
	v_pk_mul_f32 v[178:179], v[102:103], v[166:167] op_sel:[1,1] op_sel_hi:[0,1]
	v_pk_fma_f32 v[102:103], v[102:103], v[166:167], v[178:179] op_sel_hi:[1,0,1] neg_lo:[0,0,1]
	ds_write_b64 v65, v[102:103] offset:264
	s_waitcnt lgkmcnt(3)
	v_pk_mul_f32 v[176:177], v[104:105], v[188:189] op_sel:[1,1] op_sel_hi:[0,1]
	v_pk_fma_f32 v[104:105], v[104:105], v[188:189], v[176:177] op_sel_hi:[1,0,1] neg_lo:[0,0,1]
	ds_write_b64 v65, v[104:105] offset:528
	s_waitcnt lgkmcnt(3)
	v_pk_mul_f32 v[182:183], v[106:107], v[174:175] op_sel:[1,1] op_sel_hi:[0,1]
	v_pk_fma_f32 v[106:107], v[106:107], v[174:175], v[182:183] op_sel_hi:[1,0,1] neg_lo:[0,0,1]
	ds_write_b64 v65, v[106:107] offset:792
	s_waitcnt lgkmcnt(3)
	v_pk_mul_f32 v[180:181], v[108:109], v[168:169] op_sel:[1,1] op_sel_hi:[0,1]
	v_pk_fma_f32 v[108:109], v[108:109], v[168:169], v[180:181] op_sel_hi:[1,0,1] neg_lo:[0,0,1]
	ds_write_b64 v65, v[108:109] offset:1056
	ds_read_b64 v[186:187], v56 offset:1280
	ds_read_b64 v[184:185], v56 offset:1536
	ds_read_b64 v[178:179], v56 offset:1792
	ds_read_b64 v[176:177], v56 offset:2048
	s_waitcnt lgkmcnt(3)
	v_pk_mul_f32 v[182:183], v[110:111], v[186:187] op_sel:[1,1] op_sel_hi:[0,1]
	v_pk_fma_f32 v[110:111], v[110:111], v[186:187], v[182:183] op_sel_hi:[1,0,1] neg_lo:[0,0,1]
	ds_write_b64 v65, v[110:111] offset:1320
	s_waitcnt lgkmcnt(3)
; #define LAS __attribute__((address_space(3)))
; __device__ __forceinline__ f32x2 cmul(f32x2 a, f32x2 b) { return (f32x2){a.x * b.x - a.y * b.y, a.x * b.y + a.y * b.x}; }
; __device__ __forceinline__ void fft_fwd2(LAS f32x2* B, const LAS f32x2* TW2, int tid) {
;     ...
;     B[fpad(base)] = x[0];
; #pragma unroll
;     for (int k = 1; k < 16; ++k) B[fpad(base + 32 * k)] = cmul(x[k], TW2[k * 32 + n2]);
; }
; __device__ __forceinline__ void hy_sconv(const LAS float* plane, float w0, float w1, float w2, float cb, int n2, float (&u)[8][2]) {
;     asm volatile("" : "+v"(n2));
; #pragma unroll
;     for (int r = 0; r < 8; ++r)
; #pragma unroll
;         for (int b = 0; b < 2; ++b) { const int t = n2 + 512 * r, row = b * SEQ + t;
;             float a = cb + w1 * plane[row];
;             if (t > 0) a += w0 * plane[row - 1];
;             if (t < SEQ - 1) a += w2 * plane[row + 1];
;             u[r][b] = a; }
; }
	v_pk_mul_f32 v[180:181], v[112:113], v[184:185] op_sel:[1,1] op_sel_hi:[0,1]
	v_pk_fma_f32 v[112:113], v[112:113], v[184:185], v[180:181] op_sel_hi:[1,0,1] neg_lo:[0,0,1]
	ds_write_b64 v65, v[112:113] offset:1584
	s_waitcnt lgkmcnt(3)
	v_pk_mul_f32 v[166:167], v[114:115], v[178:179] op_sel:[1,1] op_sel_hi:[0,1]
	v_pk_fma_f32 v[114:115], v[114:115], v[178:179], v[166:167] op_sel_hi:[1,0,1] neg_lo:[0,0,1]
	ds_write_b64 v65, v[114:115] offset:1848
	s_waitcnt lgkmcnt(3)
	v_pk_mul_f32 v[188:189], v[116:117], v[176:177] op_sel:[1,1] op_sel_hi:[0,1]
	v_pk_fma_f32 v[116:117], v[116:117], v[176:177], v[188:189] op_sel_hi:[1,0,1] neg_lo:[0,0,1]
	ds_write_b64 v65, v[116:117] offset:2112
	ds_read_b64 v[174:175], v56 offset:2304
	ds_read_b64 v[168:169], v56 offset:2560
	ds_read_b64 v[182:183], v56 offset:2816
	ds_read_b64 v[180:181], v56 offset:3072
	s_waitcnt lgkmcnt(3)
	v_pk_mul_f32 v[166:167], v[118:119], v[174:175] op_sel:[1,1] op_sel_hi:[0,1]
	v_pk_fma_f32 v[118:119], v[118:119], v[174:175], v[166:167] op_sel_hi:[1,0,1] neg_lo:[0,0,1]
	ds_write_b64 v65, v[118:119] offset:2376
	s_waitcnt lgkmcnt(3)
	v_pk_mul_f32 v[188:189], v[120:121], v[168:169] op_sel:[1,1] op_sel_hi:[0,1]
	v_pk_fma_f32 v[120:121], v[120:121], v[168:169], v[188:189] op_sel_hi:[1,0,1] neg_lo:[0,0,1]
	ds_write_b64 v65, v[120:121] offset:2640
	s_waitcnt lgkmcnt(3)
	v_pk_mul_f32 v[186:187], v[122:123], v[182:183] op_sel:[1,1] op_sel_hi:[0,1]
	v_pk_fma_f32 v[122:123], v[122:123], v[182:183], v[186:187] op_sel_hi:[1,0,1] neg_lo:[0,0,1]
	ds_write_b64 v65, v[122:123] offset:2904
	s_waitcnt lgkmcnt(3)
	v_pk_mul_f32 v[184:185], v[124:125], v[180:181] op_sel:[1,1] op_sel_hi:[0,1]
	v_pk_fma_f32 v[124:125], v[124:125], v[180:181], v[184:185] op_sel_hi:[1,0,1] neg_lo:[0,0,1]
	ds_write_b64 v65, v[124:125] offset:3168
	ds_read_b64 v[178:179], v56 offset:3328
	ds_read_b64 v[176:177], v56 offset:3584
	ds_read_b64 v[166:167], v56 offset:3840
	s_waitcnt lgkmcnt(2)
	v_pk_mul_f32 v[188:189], v[126:127], v[178:179] op_sel:[1,1] op_sel_hi:[0,1]
	v_pk_fma_f32 v[126:127], v[126:127], v[178:179], v[188:189] op_sel_hi:[1,0,1] neg_lo:[0,0,1]
	ds_write_b64 v65, v[126:127] offset:3432
	s_waitcnt lgkmcnt(2)
	v_pk_mul_f32 v[186:187], v[128:129], v[176:177] op_sel:[1,1] op_sel_hi:[0,1]
	v_pk_fma_f32 v[128:129], v[128:129], v[176:177], v[186:187] op_sel_hi:[1,0,1] neg_lo:[0,0,1]
	ds_write_b64 v65, v[128:129] offset:3696
	s_waitcnt lgkmcnt(2)
	v_pk_mul_f32 v[184:185], v[130:131], v[166:167] op_sel:[1,1] op_sel_hi:[0,1]
	v_pk_fma_f32 v[130:131], v[130:131], v[166:167], v[184:185] op_sel_hi:[1,0,1] neg_lo:[0,0,1]
	ds_write_b64 v65, v[130:131] offset:3960
	s_waitcnt lgkmcnt(0)
	s_barrier
	v_mov_b32_e32 v174, s17
	v_mov_b32_e32 v175, s23
	v_mov_b32_e32 v168, s25
	v_mov_b32_e32 v169, s26
	ds_read_b32 v182, v208 offset:32768
	ds_read_b32 v180, v210 offset:32768
	ds_read_b32 v188, v208 offset:32772
	ds_read_b32 v183, v208 offset:49152
	ds_read_b32 v181, v210 offset:49152
	ds_read_b32 v189, v208 offset:49156
	ds_read_b32 v186, v208 offset:34816
	ds_read_b32 v184, v208 offset:34812
	ds_read_b32 v178, v208 offset:34820
	ds_read_b32 v187, v208 offset:51200
	ds_read_b32 v185, v208 offset:51196
	ds_read_b32 v179, v208 offset:51204
	s_waitcnt lgkmcnt(10)
	v_cndmask_b32_e64 v180, v180, 0, s[10:11]
	s_waitcnt lgkmcnt(7)
	v_cndmask_b32_e64 v181, v181, 0, s[10:11]
	v_pk_fma_f32 v[148:149], v[174:175], v[182:183], v[168:169] op_sel:[1,0,1]
	v_pk_fma_f32 v[148:149], v[174:175], v[180:181], v[148:149] op_sel_hi:[0,1,1]
	s_waitcnt lgkmcnt(6)
	v_pk_fma_f32 v[148:149], v[168:169], v[188:189], v[148:149] op_sel_hi:[0,1,1]
	s_waitcnt lgkmcnt(2)
	v_pk_fma_f32 v[150:151], v[174:175], v[186:187], v[168:169] op_sel:[1,0,1]
	s_waitcnt lgkmcnt(1)
	v_pk_fma_f32 v[150:151], v[174:175], v[184:185], v[150:151] op_sel_hi:[0,1,1]
	s_waitcnt lgkmcnt(0)
	v_pk_fma_f32 v[150:151], v[168:169], v[178:179], v[150:151] op_sel_hi:[0,1,1]
	ds_read_b32 v176, v208 offset:36864
	ds_read_b32 v166, v208 offset:36860
	ds_read_b32 v182, v208 offset:36868
	ds_read_b32 v177, v208 offset:53248
	ds_read_b32 v167, v208 offset:53244
	ds_read_b32 v183, v208 offset:53252
	ds_read_b32 v180, v208 offset:38912
	ds_read_b32 v188, v208 offset:38908
	ds_read_b32 v186, v208 offset:38916
	ds_read_b32 v181, v208 offset:55296
	ds_read_b32 v189, v208 offset:55292
	ds_read_b32 v187, v208 offset:55300
	s_waitcnt lgkmcnt(8)
	v_pk_fma_f32 v[152:153], v[174:175], v[176:177], v[168:169] op_sel:[1,0,1]
	s_waitcnt lgkmcnt(7)
	v_pk_fma_f32 v[152:153], v[174:175], v[166:167], v[152:153] op_sel_hi:[0,1,1]
	s_waitcnt lgkmcnt(6)
	v_pk_fma_f32 v[152:153], v[168:169], v[182:183], v[152:153] op_sel_hi:[0,1,1]
	s_waitcnt lgkmcnt(2)
	v_pk_fma_f32 v[154:155], v[174:175], v[180:181], v[168:169] op_sel:[1,0,1]
	s_waitcnt lgkmcnt(1)
	v_pk_fma_f32 v[154:155], v[174:175], v[188:189], v[154:155] op_sel_hi:[0,1,1]
	s_waitcnt lgkmcnt(0)
	v_pk_fma_f32 v[154:155], v[168:169], v[186:187], v[154:155] op_sel_hi:[0,1,1]
	ds_read_b32 v184, v208 offset:40960
	ds_read_b32 v178, v208 offset:40956
	ds_read_b32 v176, v208 offset:40964
	ds_read_b32 v185, v208 offset:57344
	ds_read_b32 v179, v208 offset:57340
	ds_read_b32 v177, v208 offset:57348
	ds_read_b32 v166, v208 offset:43008
	ds_read_b32 v182, v208 offset:43004
	ds_read_b32 v180, v208 offset:43012
	ds_read_b32 v167, v208 offset:59392
	ds_read_b32 v183, v208 offset:59388
	ds_read_b32 v181, v208 offset:59396
	s_waitcnt lgkmcnt(8)
	v_pk_fma_f32 v[158:159], v[174:175], v[184:185], v[168:169] op_sel:[1,0,1]
	s_waitcnt lgkmcnt(7)
	v_pk_fma_f32 v[158:159], v[174:175], v[178:179], v[158:159] op_sel_hi:[0,1,1]
	s_waitcnt lgkmcnt(6)
; #define LAS __attribute__((address_space(3)))
; __device__ __forceinline__ f32x2 cmul(f32x2 a, f32x2 b) { return (f32x2){a.x * b.x - a.y * b.y, a.x * b.y + a.y * b.x}; }
; template <int MODE> __device__ __forceinline__ void fft_pair32(LAS f32x2* B, const LAS f32x2* F, int wave, int lane) {
;     asm volatile("" : "+v"(lane));
;     constexpr float CS[16] = {1.f, 0.98078528040323043f, 0.92387953251128674f, 0.83146961230254524f, 0.70710678118654752f, 0.55557023301960218f, 0.38268343236508977f, 0.19509032201612825f,
;                               0.f, -0.19509032201612825f, -0.38268343236508977f, -0.55557023301960218f, -0.70710678118654752f, -0.83146961230254524f, -0.92387953251128674f, -0.98078528040323043f};
;     constexpr float SN[16] = {0.f, 0.19509032201612825f, 0.38268343236508977f, 0.55557023301960218f, 0.70710678118654752f, 0.83146961230254524f, 0.92387953251128674f, 0.98078528040323043f,
;                               1.f, 0.98078528040323043f, 0.92387953251128674f, 0.83146961230254524f, 0.70710678118654752f, 0.55557023301960218f, 0.38268343236508977f, 0.19509032201612825f};
;     const int hi = lane >> 5, blk = 32 * wave + (lane & 31); const float sg = hi ? -1.f : 1.f;
;     LAS f32x2* p = B + 33 * blk; f32x2 v[16];
; #pragma unroll
;     for (int j = 0; j < 16; ++j) { const f32x2 d = p[j] + p[j + 16] * sg;
;         const f32x2 w = {hi ? CS[j] : 1.f, hi ? -SN[j] : 0.f}; v[j] = j == 0 ? d : cmul(d, w); }
;     dft16<false>(v);
; __device__ __forceinline__ void hy_sconv(const LAS float* plane, float w0, float w1, float w2, float cb, int n2, float (&u)[8][2]) {
;     asm volatile("" : "+v"(n2));
; #pragma unroll
;     for (int r = 0; r < 8; ++r)
; #pragma unroll
;         for (int b = 0; b < 2; ++b) { const int t = n2 + 512 * r, row = b * SEQ + t;
;             float a = cb + w1 * plane[row];
;             if (t > 0) a += w0 * plane[row - 1];
;             if (t < SEQ - 1) a += w2 * plane[row + 1];
;             u[r][b] = a; }
; }
	v_pk_fma_f32 v[158:159], v[168:169], v[176:177], v[158:159] op_sel_hi:[0,1,1]
	s_waitcnt lgkmcnt(2)
	v_pk_fma_f32 v[160:161], v[174:175], v[166:167], v[168:169] op_sel:[1,0,1]
	s_waitcnt lgkmcnt(1)
	v_pk_fma_f32 v[160:161], v[174:175], v[182:183], v[160:161] op_sel_hi:[0,1,1]
	s_waitcnt lgkmcnt(0)
	v_pk_fma_f32 v[160:161], v[168:169], v[180:181], v[160:161] op_sel_hi:[0,1,1]
	ds_read_b32 v188, v208 offset:45056
	ds_read_b32 v186, v208 offset:45052
	ds_read_b32 v184, v208 offset:45060
	ds_read_b32 v189, v208 offset:61440
	ds_read_b32 v187, v208 offset:61436
	ds_read_b32 v185, v208 offset:61444
	ds_read_b32 v178, v208 offset:47104
	ds_read_b32 v176, v208 offset:47100
	ds_read_b32 v166, v208 offset:47108
	ds_read_b32 v179, v208 offset:63488
	ds_read_b32 v177, v208 offset:63484
	ds_read_b32 v167, v208 offset:63492
	s_waitcnt lgkmcnt(8)
	v_pk_fma_f32 v[162:163], v[174:175], v[188:189], v[168:169] op_sel:[1,0,1]
	s_waitcnt lgkmcnt(7)
	v_pk_fma_f32 v[162:163], v[174:175], v[186:187], v[162:163] op_sel_hi:[0,1,1]
	s_waitcnt lgkmcnt(6)
	v_pk_fma_f32 v[162:163], v[168:169], v[184:185], v[162:163] op_sel_hi:[0,1,1]
	s_waitcnt lgkmcnt(3)
	v_cndmask_b32_e64 v166, v166, 0, s[28:29]
	s_waitcnt lgkmcnt(0)
	v_cndmask_b32_e64 v167, v167, 0, s[28:29]
	v_pk_fma_f32 v[164:165], v[174:175], v[178:179], v[168:169] op_sel:[1,0,1]
	v_pk_fma_f32 v[164:165], v[174:175], v[176:177], v[164:165] op_sel_hi:[0,1,1]
	v_pk_fma_f32 v[164:165], v[168:169], v[166:167], v[164:165] op_sel_hi:[0,1,1]
	s_load_dword s17, s[60:61], 0x1000
	s_load_dword s23, s[60:61], 0x4000
	s_load_dword s25, s[60:61], 0x7000
	s_load_dword s26, s[62:63], 0x1000
	v_add_u32_e32 v65, 0x10800, v156
	v_add_u32_e32 v69, 0x10800, v196
	ds_read_b64 v[100:101], v65
	ds_read_b64 v[182:183], v65 offset:128
	ds_read_b64 v[102:103], v65 offset:8
	ds_read_b64 v[180:181], v65 offset:136
	ds_read_b64 v[104:105], v65 offset:16
	ds_read_b64 v[188:189], v65 offset:144
	ds_read_b64 v[106:107], v65 offset:24
	ds_read_b64 v[186:187], v65 offset:152
	s_waitcnt lgkmcnt(0)
	v_pk_fma_f32 v[100:101], v[182:183], v[190:191], v[100:101] op_sel_hi:[1,0,1]
	v_pk_fma_f32 v[102:103], v[180:181], v[190:191], v[102:103] op_sel_hi:[1,0,1]
	v_pk_mul_f32 v[184:185], v[102:103], v[36:37] op_sel:[1,1] op_sel_hi:[0,1]
	v_pk_fma_f32 v[102:103], v[102:103], v[36:37], v[184:185] op_sel_hi:[1,0,1] neg_lo:[0,0,1]
	v_pk_fma_f32 v[104:105], v[188:189], v[190:191], v[104:105] op_sel_hi:[1,0,1]
	v_pk_mul_f32 v[178:179], v[104:105], v[38:39] op_sel:[1,1] op_sel_hi:[0,1]
	v_pk_fma_f32 v[104:105], v[104:105], v[38:39], v[178:179] op_sel_hi:[1,0,1] neg_lo:[0,0,1]
	v_pk_fma_f32 v[106:107], v[186:187], v[190:191], v[106:107] op_sel_hi:[1,0,1]
	v_pk_mul_f32 v[176:177], v[106:107], v[40:41] op_sel:[1,1] op_sel_hi:[0,1]
	v_pk_fma_f32 v[106:107], v[106:107], v[40:41], v[176:177] op_sel_hi:[1,0,1] neg_lo:[0,0,1]
	ds_read_b64 v[108:109], v65 offset:32
	ds_read_b64 v[166:167], v65 offset:160
	ds_read_b64 v[110:111], v65 offset:40
	ds_read_b64 v[174:175], v65 offset:168
	ds_read_b64 v[112:113], v65 offset:48
	ds_read_b64 v[168:169], v65 offset:176
	ds_read_b64 v[114:115], v65 offset:56
	ds_read_b64 v[184:185], v65 offset:184
	s_waitcnt lgkmcnt(6)
	v_pk_fma_f32 v[108:109], v[166:167], v[190:191], v[108:109] op_sel_hi:[1,0,1]
	v_pk_mul_f32 v[178:179], v[108:109], v[42:43] op_sel:[1,1] op_sel_hi:[0,1]
	v_pk_fma_f32 v[108:109], v[108:109], v[42:43], v[178:179] op_sel_hi:[1,0,1] neg_lo:[0,0,1]
	s_waitcnt lgkmcnt(4)
	v_pk_fma_f32 v[110:111], v[174:175], v[190:191], v[110:111] op_sel_hi:[1,0,1]
	v_pk_mul_f32 v[176:177], v[110:111], v[44:45] op_sel:[1,1] op_sel_hi:[0,1]
	v_pk_fma_f32 v[110:111], v[110:111], v[44:45], v[176:177] op_sel_hi:[1,0,1] neg_lo:[0,0,1]
	s_waitcnt lgkmcnt(2)
	v_pk_fma_f32 v[112:113], v[168:169], v[190:191], v[112:113] op_sel_hi:[1,0,1]
	v_pk_mul_f32 v[182:183], v[112:113], v[46:47] op_sel:[1,1] op_sel_hi:[0,1]
	v_pk_fma_f32 v[112:113], v[112:113], v[46:47], v[182:183] op_sel_hi:[1,0,1] neg_lo:[0,0,1]
	s_waitcnt lgkmcnt(0)
	v_pk_fma_f32 v[114:115], v[184:185], v[190:191], v[114:115] op_sel_hi:[1,0,1]
	v_pk_mul_f32 v[180:181], v[114:115], v[48:49] op_sel:[1,1] op_sel_hi:[0,1]
	v_pk_fma_f32 v[114:115], v[114:115], v[48:49], v[180:181] op_sel_hi:[1,0,1] neg_lo:[0,0,1]
	ds_read_b64 v[116:117], v65 offset:64
	ds_read_b64 v[188:189], v65 offset:192
	ds_read_b64 v[118:119], v65 offset:72
	ds_read_b64 v[186:187], v65 offset:200
	ds_read_b64 v[120:121], v65 offset:80
	ds_read_b64 v[178:179], v65 offset:208
	ds_read_b64 v[122:123], v65 offset:88
	ds_read_b64 v[176:177], v65 offset:216
	s_waitcnt lgkmcnt(6)
	v_pk_fma_f32 v[116:117], v[188:189], v[190:191], v[116:117] op_sel_hi:[1,0,1]
	v_pk_mul_f32 v[182:183], v[116:117], v[50:51] op_sel:[1,1] op_sel_hi:[0,1]
	v_pk_fma_f32 v[116:117], v[116:117], v[50:51], v[182:183] op_sel_hi:[1,0,1] neg_lo:[0,0,1]
	s_waitcnt lgkmcnt(4)
	v_pk_fma_f32 v[118:119], v[186:187], v[190:191], v[118:119] op_sel_hi:[1,0,1]
	v_pk_mul_f32 v[180:181], v[118:119], v[52:53] op_sel:[1,1] op_sel_hi:[0,1]
	v_pk_fma_f32 v[118:119], v[118:119], v[52:53], v[180:181] op_sel_hi:[1,0,1] neg_lo:[0,0,1]
	s_waitcnt lgkmcnt(2)
	v_pk_fma_f32 v[120:121], v[178:179], v[190:191], v[120:121] op_sel_hi:[1,0,1]
	v_pk_mul_f32 v[166:167], v[120:121], v[54:55] op_sel:[1,1] op_sel_hi:[0,1]
	v_pk_fma_f32 v[120:121], v[120:121], v[54:55], v[166:167] op_sel_hi:[1,0,1] neg_lo:[0,0,1]
	s_waitcnt lgkmcnt(0)
; __device__ __forceinline__ f32x2 cmul(f32x2 a, f32x2 b) { return (f32x2){a.x * b.x - a.y * b.y, a.x * b.y + a.y * b.x}; }
; template <bool INV> __device__ __forceinline__ f32x2 cmul_tw(f32x2 a, f32x2 w) { return INV ? cmulc(a, w) : cmul(a, w); }
; template <bool INV> __device__ __forceinline__ void dft16(f32x2 (&x)[16]) {
;     constexpr float C1 = 0.92387953251128674f, S1 = 0.38268343236508977f, C2 = 0.70710678118654752f;
; #pragma unroll
;     for (int b = 0; b < 4; ++b) dft4<INV>(x[b], x[4 + b], x[8 + b], x[12 + b]);
;     const f32x2 w1 = {C1, -S1}, w2 = {C2, -C2}, w3 = {S1, -C1}, w4 = {0.f, -1.f}, w6 = {-C2, -C2}, w9 = {-C1, S1};
;     x[4 * 1 + 1] = cmul_tw<INV>(x[5], w1); x[4 * 1 + 2] = cmul_tw<INV>(x[6], w2); x[4 * 1 + 3] = cmul_tw<INV>(x[7], w3);
;     x[4 * 2 + 1] = cmul_tw<INV>(x[9], w2); x[4 * 2 + 2] = cmul_tw<INV>(x[10], w4); x[4 * 2 + 3] = cmul_tw<INV>(x[11], w6);
;     x[4 * 3 + 1] = cmul_tw<INV>(x[13], w3); x[4 * 3 + 2] = cmul_tw<INV>(x[14], w6); x[4 * 3 + 3] = cmul_tw<INV>(x[15], w9);
; #pragma unroll
;     for (int c = 0; c < 4; ++c) dft4<INV>(x[4 * c], x[4 * c + 1], x[4 * c + 2], x[4 * c + 3]);
;     f32x2 y[16];
; #pragma unroll
;     for (int k = 0; k < 16; ++k) y[k] = x[4 * (k & 3) + (k >> 2)];
; #pragma unroll
;     for (int k = 0; k < 16; ++k) x[k] = y[k];
; }
; template <int MODE> __device__ __forceinline__ void fft_pair32(LAS f32x2* B, const LAS f32x2* F, int wave, int lane) {
;     ...
;     for (int j = 0; j < 16; ++j) { const f32x2 d = p[j] + p[j + 16] * sg;
;         const f32x2 w = {hi ? CS[j] : 1.f, hi ? -SN[j] : 0.f}; v[j] = j == 0 ? d : cmul(d, w); }
;     dft16<false>(v);
	v_pk_fma_f32 v[122:123], v[176:177], v[190:191], v[122:123] op_sel_hi:[1,0,1]
	v_pk_mul_f32 v[174:175], v[122:123], v[90:91] op_sel:[1,1] op_sel_hi:[0,1]
	v_pk_fma_f32 v[122:123], v[122:123], v[90:91], v[174:175] op_sel_hi:[1,0,1] neg_lo:[0,0,1]
	ds_read_b64 v[124:125], v65 offset:96
	ds_read_b64 v[168:169], v65 offset:224
	ds_read_b64 v[126:127], v65 offset:104
	ds_read_b64 v[184:185], v65 offset:232
	ds_read_b64 v[128:129], v65 offset:112
	ds_read_b64 v[182:183], v65 offset:240
	ds_read_b64 v[130:131], v65 offset:120
	ds_read_b64 v[180:181], v65 offset:248
	s_waitcnt lgkmcnt(6)
	v_pk_fma_f32 v[124:125], v[168:169], v[190:191], v[124:125] op_sel_hi:[1,0,1]
	v_pk_mul_f32 v[166:167], v[124:125], v[92:93] op_sel:[1,1] op_sel_hi:[0,1]
	v_pk_fma_f32 v[124:125], v[124:125], v[92:93], v[166:167] op_sel_hi:[1,0,1] neg_lo:[0,0,1]
	s_waitcnt lgkmcnt(4)
	v_pk_fma_f32 v[126:127], v[184:185], v[190:191], v[126:127] op_sel_hi:[1,0,1]
	v_pk_mul_f32 v[174:175], v[126:127], v[94:95] op_sel:[1,1] op_sel_hi:[0,1]
	v_pk_fma_f32 v[126:127], v[126:127], v[94:95], v[174:175] op_sel_hi:[1,0,1] neg_lo:[0,0,1]
	s_waitcnt lgkmcnt(2)
	v_pk_fma_f32 v[128:129], v[182:183], v[190:191], v[128:129] op_sel_hi:[1,0,1]
	v_pk_mul_f32 v[188:189], v[128:129], v[96:97] op_sel:[1,1] op_sel_hi:[0,1]
	v_pk_fma_f32 v[128:129], v[128:129], v[96:97], v[188:189] op_sel_hi:[1,0,1] neg_lo:[0,0,1]
	s_waitcnt lgkmcnt(0)
	v_pk_fma_f32 v[130:131], v[180:181], v[190:191], v[130:131] op_sel_hi:[1,0,1]
	v_pk_mul_f32 v[186:187], v[130:131], v[98:99] op_sel:[1,1] op_sel_hi:[0,1]
	v_pk_fma_f32 v[130:131], v[130:131], v[98:99], v[186:187] op_sel_hi:[1,0,1] neg_lo:[0,0,1]
	v_pk_add_f32 v[178:179], v[100:101], v[116:117]
	v_pk_add_f32 v[176:177], v[100:101], v[116:117] neg_lo:[0,1] neg_hi:[0,1]
	v_pk_add_f32 v[166:167], v[108:109], v[124:125]
	v_pk_add_f32 v[174:175], v[108:109], v[124:125] neg_lo:[0,1] neg_hi:[0,1]
	v_pk_add_f32 v[100:101], v[178:179], v[166:167]
	v_pk_add_f32 v[116:117], v[178:179], v[166:167] neg_lo:[0,1] neg_hi:[0,1]
	v_pk_add_f32 v[108:109], v[176:177], v[174:175] op_sel:[0,1] op_sel_hi:[1,0] neg_hi:[0,1]
	v_pk_add_f32 v[124:125], v[176:177], v[174:175] op_sel:[0,1] op_sel_hi:[1,0] neg_lo:[0,1]
	v_pk_add_f32 v[188:189], v[102:103], v[118:119]
	v_pk_add_f32 v[186:187], v[102:103], v[118:119] neg_lo:[0,1] neg_hi:[0,1]
	v_pk_add_f32 v[168:169], v[110:111], v[126:127]
	v_pk_add_f32 v[184:185], v[110:111], v[126:127] neg_lo:[0,1] neg_hi:[0,1]
	v_pk_add_f32 v[102:103], v[188:189], v[168:169]
	v_pk_add_f32 v[118:119], v[188:189], v[168:169] neg_lo:[0,1] neg_hi:[0,1]
	v_pk_add_f32 v[110:111], v[186:187], v[184:185] op_sel:[0,1] op_sel_hi:[1,0] neg_hi:[0,1]
	v_pk_add_f32 v[126:127], v[186:187], v[184:185] op_sel:[0,1] op_sel_hi:[1,0] neg_lo:[0,1]
	v_pk_add_f32 v[182:183], v[104:105], v[120:121]
	v_pk_add_f32 v[180:181], v[104:105], v[120:121] neg_lo:[0,1] neg_hi:[0,1]
	v_pk_add_f32 v[178:179], v[112:113], v[128:129]
	v_pk_add_f32 v[176:177], v[112:113], v[128:129] neg_lo:[0,1] neg_hi:[0,1]
	v_pk_add_f32 v[104:105], v[182:183], v[178:179]
	v_pk_add_f32 v[120:121], v[182:183], v[178:179] neg_lo:[0,1] neg_hi:[0,1]
	v_pk_add_f32 v[112:113], v[180:181], v[176:177] op_sel:[0,1] op_sel_hi:[1,0] neg_hi:[0,1]
	v_pk_add_f32 v[128:129], v[180:181], v[176:177] op_sel:[0,1] op_sel_hi:[1,0] neg_lo:[0,1]
	v_pk_add_f32 v[166:167], v[106:107], v[122:123]
	v_pk_add_f32 v[174:175], v[106:107], v[122:123] neg_lo:[0,1] neg_hi:[0,1]
	v_pk_add_f32 v[188:189], v[114:115], v[130:131]
	v_pk_add_f32 v[186:187], v[114:115], v[130:131] neg_lo:[0,1] neg_hi:[0,1]
	v_pk_add_f32 v[106:107], v[166:167], v[188:189]
	v_pk_add_f32 v[122:123], v[166:167], v[188:189] neg_lo:[0,1] neg_hi:[0,1]
	v_pk_add_f32 v[114:115], v[174:175], v[186:187] op_sel:[0,1] op_sel_hi:[1,0] neg_hi:[0,1]
	v_pk_add_f32 v[130:131], v[174:175], v[186:187] op_sel:[0,1] op_sel_hi:[1,0] neg_lo:[0,1]
	v_pk_mul_f32 v[168:169], v[110:111], s[68:69] op_sel:[1,1] op_sel_hi:[0,1]
	v_pk_fma_f32 v[110:111], v[110:111], s[68:69], v[168:169] op_sel_hi:[1,0,1] neg_lo:[0,0,1]
	v_pk_mul_f32 v[184:185], v[112:113], s[84:85] op_sel:[1,1] op_sel_hi:[0,1]
	v_pk_fma_f32 v[112:113], v[112:113], s[84:85], v[184:185] op_sel_hi:[1,0,1] neg_lo:[0,0,1]
	v_pk_mul_f32 v[182:183], v[114:115], s[88:89] op_sel:[1,1] op_sel_hi:[0,1]
	v_pk_fma_f32 v[114:115], v[114:115], s[88:89], v[182:183] op_sel_hi:[1,0,1] neg_lo:[0,0,1]
	v_pk_mul_f32 v[180:181], v[118:119], s[84:85] op_sel:[1,1] op_sel_hi:[0,1]
	v_pk_fma_f32 v[118:119], v[118:119], s[84:85], v[180:181] op_sel_hi:[1,0,1] neg_lo:[0,0,1]
	v_pk_mul_f32 v[178:179], v[122:123], s[90:91] op_sel:[1,1] op_sel_hi:[0,1]
	v_pk_fma_f32 v[122:123], v[122:123], s[90:91], v[178:179] op_sel_hi:[1,0,1] neg_lo:[0,0,1]
	v_pk_mul_f32 v[176:177], v[126:127], s[88:89] op_sel:[1,1] op_sel_hi:[0,1]
	v_pk_fma_f32 v[126:127], v[126:127], s[88:89], v[176:177] op_sel_hi:[1,0,1] neg_lo:[0,0,1]
	v_pk_mul_f32 v[166:167], v[128:129], s[90:91] op_sel:[1,1] op_sel_hi:[0,1]
	v_pk_fma_f32 v[128:129], v[128:129], s[90:91], v[166:167] op_sel_hi:[1,0,1] neg_lo:[0,0,1]
	v_pk_mul_f32 v[174:175], v[130:131], s[98:99] op_sel:[1,1] op_sel_hi:[0,1]
	v_pk_fma_f32 v[130:131], v[130:131], s[98:99], v[174:175] op_sel_hi:[1,0,1] neg_lo:[0,0,1]
	v_pk_add_f32 v[188:189], v[100:101], v[104:105]
	v_pk_add_f32 v[186:187], v[100:101], v[104:105] neg_lo:[0,1] neg_hi:[0,1]
	v_pk_add_f32 v[168:169], v[102:103], v[106:107]
	v_pk_add_f32 v[184:185], v[102:103], v[106:107] neg_lo:[0,1] neg_hi:[0,1]
	v_pk_add_f32 v[100:101], v[188:189], v[168:169]
	v_pk_add_f32 v[104:105], v[188:189], v[168:169] neg_lo:[0,1] neg_hi:[0,1]
	v_pk_add_f32 v[102:103], v[186:187], v[184:185] op_sel:[0,1] op_sel_hi:[1,0] neg_hi:[0,1]
; __device__ __forceinline__ f32x2 cmul(f32x2 a, f32x2 b) { return (f32x2){a.x * b.x - a.y * b.y, a.x * b.y + a.y * b.x}; }
; __device__ __forceinline__ void dft16_fwd_lo(f32x2 (&x)[16]) {
;     constexpr float C1 = 0.92387953251128674f, S1 = 0.38268343236508977f, C2 = 0.70710678118654752f;
; #pragma unroll
;     for (int b = 0; b < 4; ++b) { const f32x2 x0 = x[b], x1 = x[4 + b]; const f32x2 j1 = {x1.y, -x1.x};
;         x[b] = x0 + x1; x[4 + b] = x0 + j1; x[8 + b] = x0 - x1; x[12 + b] = x0 - j1; }
;     const f32x2 w1 = {C1, -S1}, w2 = {C2, -C2}, w3 = {S1, -C1}, w4 = {0.f, -1.f}, w6 = {-C2, -C2}, w9 = {-C1, S1};
;     x[5] = cmul(x[5], w1); x[6] = cmul(x[6], w2); x[7] = cmul(x[7], w3);
;     x[9] = cmul(x[9], w2); x[10] = cmul(x[10], w4); x[11] = cmul(x[11], w6);
;     x[13] = cmul(x[13], w3); x[14] = cmul(x[14], w6); x[15] = cmul(x[15], w9);
; template <int MODE> __device__ __forceinline__ void fft_pair32(LAS f32x2* B, const LAS f32x2* F, int wave, int lane) {
;     ...
;     if (MODE == 2) {
; #pragma unroll
;         for (int k = 0; k < 16; ++k) p[2 * k + hi] = v[k];
;         return; }
	v_pk_add_f32 v[106:107], v[186:187], v[184:185] op_sel:[0,1] op_sel_hi:[1,0] neg_lo:[0,1]
	v_pk_add_f32 v[182:183], v[108:109], v[112:113]
	v_pk_add_f32 v[180:181], v[108:109], v[112:113] neg_lo:[0,1] neg_hi:[0,1]
	v_pk_add_f32 v[178:179], v[110:111], v[114:115]
	v_pk_add_f32 v[176:177], v[110:111], v[114:115] neg_lo:[0,1] neg_hi:[0,1]
	v_pk_add_f32 v[108:109], v[182:183], v[178:179]
	v_pk_add_f32 v[112:113], v[182:183], v[178:179] neg_lo:[0,1] neg_hi:[0,1]
	v_pk_add_f32 v[110:111], v[180:181], v[176:177] op_sel:[0,1] op_sel_hi:[1,0] neg_hi:[0,1]
	v_pk_add_f32 v[114:115], v[180:181], v[176:177] op_sel:[0,1] op_sel_hi:[1,0] neg_lo:[0,1]
	v_pk_add_f32 v[166:167], v[116:117], v[120:121] op_sel:[0,1] op_sel_hi:[1,0] neg_hi:[0,1]
	v_pk_add_f32 v[174:175], v[116:117], v[120:121] op_sel:[0,1] op_sel_hi:[1,0] neg_lo:[0,1]
	v_pk_add_f32 v[188:189], v[118:119], v[122:123]
	v_pk_add_f32 v[186:187], v[118:119], v[122:123] neg_lo:[0,1] neg_hi:[0,1]
	v_pk_add_f32 v[116:117], v[166:167], v[188:189]
	v_pk_add_f32 v[120:121], v[166:167], v[188:189] neg_lo:[0,1] neg_hi:[0,1]
	v_pk_add_f32 v[118:119], v[174:175], v[186:187] op_sel:[0,1] op_sel_hi:[1,0] neg_hi:[0,1]
	v_pk_add_f32 v[122:123], v[174:175], v[186:187] op_sel:[0,1] op_sel_hi:[1,0] neg_lo:[0,1]
	v_pk_add_f32 v[168:169], v[124:125], v[128:129]
	v_pk_add_f32 v[184:185], v[124:125], v[128:129] neg_lo:[0,1] neg_hi:[0,1]
	v_pk_add_f32 v[182:183], v[126:127], v[130:131]
	v_pk_add_f32 v[180:181], v[126:127], v[130:131] neg_lo:[0,1] neg_hi:[0,1]
	v_pk_add_f32 v[124:125], v[168:169], v[182:183]
	v_pk_add_f32 v[128:129], v[168:169], v[182:183] neg_lo:[0,1] neg_hi:[0,1]
	v_pk_add_f32 v[126:127], v[184:185], v[180:181] op_sel:[0,1] op_sel_hi:[1,0] neg_hi:[0,1]
	v_pk_add_f32 v[130:131], v[184:185], v[180:181] op_sel:[0,1] op_sel_hi:[1,0] neg_lo:[0,1]
	v_pk_mul_f32 v[100:101], v[100:101], v[192:193] op_sel_hi:[1,0]
	ds_write_b64 v69, v[100:101]
	v_pk_mul_f32 v[108:109], v[108:109], v[192:193] op_sel_hi:[1,0]
	ds_write_b64 v69, v[108:109] offset:16
	v_pk_mul_f32 v[116:117], v[116:117], v[192:193] op_sel_hi:[1,0]
	ds_write_b64 v69, v[116:117] offset:32
	v_pk_mul_f32 v[124:125], v[124:125], v[192:193] op_sel_hi:[1,0]
	ds_write_b64 v69, v[124:125] offset:48
	v_pk_mul_f32 v[102:103], v[102:103], v[192:193] op_sel_hi:[1,0]
	ds_write_b64 v69, v[102:103] offset:64
	v_pk_mul_f32 v[110:111], v[110:111], v[192:193] op_sel_hi:[1,0]
	ds_write_b64 v69, v[110:111] offset:80
	v_pk_mul_f32 v[118:119], v[118:119], v[192:193] op_sel_hi:[1,0]
	ds_write_b64 v69, v[118:119] offset:96
	v_pk_mul_f32 v[126:127], v[126:127], v[192:193] op_sel_hi:[1,0]
	ds_write_b64 v69, v[126:127] offset:112
	v_pk_mul_f32 v[104:105], v[104:105], v[192:193] op_sel_hi:[1,0]
	ds_write_b64 v69, v[104:105] offset:128
	v_pk_mul_f32 v[112:113], v[112:113], v[192:193] op_sel_hi:[1,0]
	ds_write_b64 v69, v[112:113] offset:144
	v_pk_mul_f32 v[120:121], v[120:121], v[192:193] op_sel_hi:[1,0]
	ds_write_b64 v69, v[120:121] offset:160
	v_pk_mul_f32 v[128:129], v[128:129], v[192:193] op_sel_hi:[1,0]
	ds_write_b64 v69, v[128:129] offset:176
	v_pk_mul_f32 v[106:107], v[106:107], v[192:193] op_sel_hi:[1,0]
	ds_write_b64 v69, v[106:107] offset:192
	v_pk_mul_f32 v[114:115], v[114:115], v[192:193] op_sel_hi:[1,0]
	ds_write_b64 v69, v[114:115] offset:208
	v_pk_mul_f32 v[122:123], v[122:123], v[192:193] op_sel_hi:[1,0]
	ds_write_b64 v69, v[122:123] offset:224
	v_pk_mul_f32 v[130:131], v[130:131], v[192:193] op_sel_hi:[1,0]
	ds_write_b64 v69, v[130:131] offset:240
	s_waitcnt lgkmcnt(0)
	s_barrier
	v_pk_add_f32 v[104:105], v[132:133], v[140:141] neg_lo:[0,1] neg_hi:[0,1]
	v_pk_add_f32 v[106:107], v[132:133], v[140:141] op_sel:[0,1] op_sel_hi:[1,0] neg_lo:[0,1]
	v_pk_add_f32 v[178:179], v[132:133], v[140:141] op_sel:[0,1] op_sel_hi:[1,0] neg_hi:[0,1]
	v_pk_add_f32 v[100:101], v[132:133], v[140:141]
	v_pk_add_f32 v[112:113], v[134:135], v[142:143] neg_lo:[0,1] neg_hi:[0,1]
	v_pk_add_f32 v[114:115], v[134:135], v[142:143] op_sel:[0,1] op_sel_hi:[1,0] neg_lo:[0,1]
	v_pk_add_f32 v[176:177], v[134:135], v[142:143] op_sel:[0,1] op_sel_hi:[1,0] neg_hi:[0,1]
	v_pk_add_f32 v[108:109], v[134:135], v[142:143]
	v_pk_add_f32 v[120:121], v[136:137], v[144:145] neg_lo:[0,1] neg_hi:[0,1]
	v_pk_add_f32 v[122:123], v[136:137], v[144:145] op_sel:[0,1] op_sel_hi:[1,0] neg_lo:[0,1]
	v_pk_add_f32 v[166:167], v[136:137], v[144:145] op_sel:[0,1] op_sel_hi:[1,0] neg_hi:[0,1]
	v_pk_add_f32 v[116:117], v[136:137], v[144:145]
	v_pk_add_f32 v[128:129], v[138:139], v[146:147] neg_lo:[0,1] neg_hi:[0,1]
	v_pk_add_f32 v[130:131], v[138:139], v[146:147] op_sel:[0,1] op_sel_hi:[1,0] neg_lo:[0,1]
	v_pk_add_f32 v[174:175], v[138:139], v[146:147] op_sel:[0,1] op_sel_hi:[1,0] neg_hi:[0,1]
	v_pk_add_f32 v[124:125], v[138:139], v[146:147]
	v_pk_mul_f32 v[188:189], v[176:177], s[68:69] op_sel:[1,1] op_sel_hi:[0,1]
	v_pk_fma_f32 v[176:177], v[176:177], s[68:69], v[188:189] op_sel_hi:[1,0,1] neg_lo:[0,0,1]
	v_pk_mul_f32 v[186:187], v[166:167], s[84:85] op_sel:[1,1] op_sel_hi:[0,1]
	v_pk_fma_f32 v[166:167], v[166:167], s[84:85], v[186:187] op_sel_hi:[1,0,1] neg_lo:[0,0,1]
	v_pk_mul_f32 v[168:169], v[174:175], s[88:89] op_sel:[1,1] op_sel_hi:[0,1]
	v_pk_fma_f32 v[174:175], v[174:175], s[88:89], v[168:169] op_sel_hi:[1,0,1] neg_lo:[0,0,1]
	v_pk_mul_f32 v[184:185], v[112:113], s[84:85] op_sel:[1,1] op_sel_hi:[0,1]
	v_pk_fma_f32 v[112:113], v[112:113], s[84:85], v[184:185] op_sel_hi:[1,0,1] neg_lo:[0,0,1]
	v_pk_mul_f32 v[182:183], v[128:129], s[90:91] op_sel:[1,1] op_sel_hi:[0,1]
	v_pk_fma_f32 v[128:129], v[128:129], s[90:91], v[182:183] op_sel_hi:[1,0,1] neg_lo:[0,0,1]
	v_pk_mul_f32 v[180:181], v[114:115], s[88:89] op_sel:[1,1] op_sel_hi:[0,1]
; #define LAS __attribute__((address_space(3)))
; __device__ __forceinline__ f32x2 cmul(f32x2 a, f32x2 b) { return (f32x2){a.x * b.x - a.y * b.y, a.x * b.y + a.y * b.x}; }
; __device__ __forceinline__ void dft16_fwd_lo(f32x2 (&x)[16]) {
;     constexpr float C1 = 0.92387953251128674f, S1 = 0.38268343236508977f, C2 = 0.70710678118654752f;
; #pragma unroll
;     for (int b = 0; b < 4; ++b) { const f32x2 x0 = x[b], x1 = x[4 + b]; const f32x2 j1 = {x1.y, -x1.x};
;         x[b] = x0 + x1; x[4 + b] = x0 + j1; x[8 + b] = x0 - x1; x[12 + b] = x0 - j1; }
;     const f32x2 w1 = {C1, -S1}, w2 = {C2, -C2}, w3 = {S1, -C1}, w4 = {0.f, -1.f}, w6 = {-C2, -C2}, w9 = {-C1, S1};
;     x[5] = cmul(x[5], w1); x[6] = cmul(x[6], w2); x[7] = cmul(x[7], w3);
;     x[9] = cmul(x[9], w2); x[10] = cmul(x[10], w4); x[11] = cmul(x[11], w6);
;     x[13] = cmul(x[13], w3); x[14] = cmul(x[14], w6); x[15] = cmul(x[15], w9);
; #pragma unroll
;     for (int c = 0; c < 4; ++c) dft4<false>(x[4 * c], x[4 * c + 1], x[4 * c + 2], x[4 * c + 3]);
;     f32x2 y[16];
; #pragma unroll
;     for (int k = 0; k < 16; ++k) y[k] = x[4 * (k & 3) + (k >> 2)];
; #pragma unroll
;     for (int k = 0; k < 16; ++k) x[k] = y[k];
; }
; template <bool LO> __device__ __forceinline__ void fft_fwd1(f32x2 (&x)[16], LAS f32x2* B, int n2, const f32x2 (&w)[16]) {
;     asm volatile("" : "+v"(n2));
;     if (LO) dft16_fwd_lo(x); else dft16<false>(x);
;     B[fpad(n2)] = x[0];
; #pragma unroll
;     for (int k = 1; k < 16; ++k) B[fpad(512 * k + n2)] = cmul(x[k], w[k]);
; }
	v_pk_fma_f32 v[114:115], v[114:115], s[88:89], v[180:181] op_sel_hi:[1,0,1] neg_lo:[0,0,1]
	v_pk_mul_f32 v[102:103], v[122:123], s[90:91] op_sel:[1,1] op_sel_hi:[0,1]
	v_pk_fma_f32 v[122:123], v[122:123], s[90:91], v[102:103] op_sel_hi:[1,0,1] neg_lo:[0,0,1]
	v_pk_mul_f32 v[110:111], v[130:131], s[98:99] op_sel:[1,1] op_sel_hi:[0,1]
	v_pk_fma_f32 v[130:131], v[130:131], s[98:99], v[110:111] op_sel_hi:[1,0,1] neg_lo:[0,0,1]
	v_pk_add_f32 v[118:119], v[100:101], v[116:117]
	v_pk_add_f32 v[126:127], v[100:101], v[116:117] neg_lo:[0,1] neg_hi:[0,1]
	v_pk_add_f32 v[188:189], v[108:109], v[124:125]
	v_pk_add_f32 v[186:187], v[108:109], v[124:125] neg_lo:[0,1] neg_hi:[0,1]
	v_pk_add_f32 v[100:101], v[118:119], v[188:189]
	v_pk_add_f32 v[116:117], v[118:119], v[188:189] neg_lo:[0,1] neg_hi:[0,1]
	v_pk_add_f32 v[108:109], v[126:127], v[186:187] op_sel:[0,1] op_sel_hi:[1,0] neg_hi:[0,1]
	v_pk_add_f32 v[124:125], v[126:127], v[186:187] op_sel:[0,1] op_sel_hi:[1,0] neg_lo:[0,1]
	v_pk_add_f32 v[168:169], v[178:179], v[166:167]
	v_pk_add_f32 v[184:185], v[178:179], v[166:167] neg_lo:[0,1] neg_hi:[0,1]
	v_pk_add_f32 v[182:183], v[176:177], v[174:175]
	v_pk_add_f32 v[180:181], v[176:177], v[174:175] neg_lo:[0,1] neg_hi:[0,1]
	v_pk_add_f32 v[178:179], v[168:169], v[182:183]
	v_pk_add_f32 v[166:167], v[168:169], v[182:183] neg_lo:[0,1] neg_hi:[0,1]
	v_pk_add_f32 v[176:177], v[184:185], v[180:181] op_sel:[0,1] op_sel_hi:[1,0] neg_hi:[0,1]
	v_pk_add_f32 v[174:175], v[184:185], v[180:181] op_sel:[0,1] op_sel_hi:[1,0] neg_lo:[0,1]
	v_pk_add_f32 v[102:103], v[104:105], v[120:121] op_sel:[0,1] op_sel_hi:[1,0] neg_hi:[0,1]
	v_pk_add_f32 v[110:111], v[104:105], v[120:121] op_sel:[0,1] op_sel_hi:[1,0] neg_lo:[0,1]
	v_pk_add_f32 v[118:119], v[112:113], v[128:129]
	v_pk_add_f32 v[126:127], v[112:113], v[128:129] neg_lo:[0,1] neg_hi:[0,1]
	v_pk_add_f32 v[104:105], v[102:103], v[118:119]
	v_pk_add_f32 v[120:121], v[102:103], v[118:119] neg_lo:[0,1] neg_hi:[0,1]
	v_pk_add_f32 v[112:113], v[110:111], v[126:127] op_sel:[0,1] op_sel_hi:[1,0] neg_hi:[0,1]
	v_pk_add_f32 v[128:129], v[110:111], v[126:127] op_sel:[0,1] op_sel_hi:[1,0] neg_lo:[0,1]
	v_pk_add_f32 v[188:189], v[106:107], v[122:123]
	v_pk_add_f32 v[186:187], v[106:107], v[122:123] neg_lo:[0,1] neg_hi:[0,1]
	v_pk_add_f32 v[168:169], v[114:115], v[130:131]
	v_pk_add_f32 v[184:185], v[114:115], v[130:131] neg_lo:[0,1] neg_hi:[0,1]
	v_pk_add_f32 v[106:107], v[188:189], v[168:169]
	v_pk_add_f32 v[122:123], v[188:189], v[168:169] neg_lo:[0,1] neg_hi:[0,1]
	v_pk_add_f32 v[114:115], v[186:187], v[184:185] op_sel:[0,1] op_sel_hi:[1,0] neg_hi:[0,1]
	v_pk_add_f32 v[130:131], v[186:187], v[184:185] op_sel:[0,1] op_sel_hi:[1,0] neg_lo:[0,1]
	ds_write_b64 v3, v[100:101]
	v_pk_mul_f32 v[180:181], v[178:179], v[6:7] op_sel:[1,1] op_sel_hi:[0,1]
	v_pk_fma_f32 v[182:183], v[178:179], v[6:7], v[180:181] op_sel_hi:[1,0,1] neg_lo:[0,0,1]
	ds_write_b64 v3, v[182:183] offset:4224
	v_pk_mul_f32 v[110:111], v[104:105], v[8:9] op_sel:[1,1] op_sel_hi:[0,1]
	v_pk_fma_f32 v[102:103], v[104:105], v[8:9], v[110:111] op_sel_hi:[1,0,1] neg_lo:[0,0,1]
	ds_write_b64 v3, v[102:103] offset:8448
	v_pk_mul_f32 v[126:127], v[106:107], v[10:11] op_sel:[1,1] op_sel_hi:[0,1]
	v_pk_fma_f32 v[118:119], v[106:107], v[10:11], v[126:127] op_sel_hi:[1,0,1] neg_lo:[0,0,1]
	ds_write_b64 v3, v[118:119] offset:12672
	v_pk_mul_f32 v[186:187], v[108:109], v[12:13] op_sel:[1,1] op_sel_hi:[0,1]
	v_pk_fma_f32 v[188:189], v[108:109], v[12:13], v[186:187] op_sel_hi:[1,0,1] neg_lo:[0,0,1]
	ds_write_b64 v3, v[188:189] offset:16896
	v_pk_mul_f32 v[184:185], v[176:177], v[14:15] op_sel:[1,1] op_sel_hi:[0,1]
	v_pk_fma_f32 v[168:169], v[176:177], v[14:15], v[184:185] op_sel_hi:[1,0,1] neg_lo:[0,0,1]
	ds_write_b64 v3, v[168:169] offset:21120
	v_pk_mul_f32 v[182:183], v[112:113], v[16:17] op_sel:[1,1] op_sel_hi:[0,1]
	v_pk_fma_f32 v[180:181], v[112:113], v[16:17], v[182:183] op_sel_hi:[1,0,1] neg_lo:[0,0,1]
	ds_write_b64 v3, v[180:181] offset:25344
	v_pk_mul_f32 v[102:103], v[114:115], v[18:19] op_sel:[1,1] op_sel_hi:[0,1]
	v_pk_fma_f32 v[110:111], v[114:115], v[18:19], v[102:103] op_sel_hi:[1,0,1] neg_lo:[0,0,1]
	ds_write_b64 v3, v[110:111] offset:29568
	v_pk_mul_f32 v[118:119], v[116:117], v[20:21] op_sel:[1,1] op_sel_hi:[0,1]
	v_pk_fma_f32 v[126:127], v[116:117], v[20:21], v[118:119] op_sel_hi:[1,0,1] neg_lo:[0,0,1]
	ds_write_b64 v3, v[126:127] offset:33792
	v_pk_mul_f32 v[188:189], v[166:167], v[22:23] op_sel:[1,1] op_sel_hi:[0,1]
	v_pk_fma_f32 v[186:187], v[166:167], v[22:23], v[188:189] op_sel_hi:[1,0,1] neg_lo:[0,0,1]
	ds_write_b64 v3, v[186:187] offset:38016
	v_pk_mul_f32 v[168:169], v[120:121], v[24:25] op_sel:[1,1] op_sel_hi:[0,1]
	v_pk_fma_f32 v[184:185], v[120:121], v[24:25], v[168:169] op_sel_hi:[1,0,1] neg_lo:[0,0,1]
	ds_write_b64 v3, v[184:185] offset:42240
	v_pk_mul_f32 v[180:181], v[122:123], v[26:27] op_sel:[1,1] op_sel_hi:[0,1]
	v_pk_fma_f32 v[182:183], v[122:123], v[26:27], v[180:181] op_sel_hi:[1,0,1] neg_lo:[0,0,1]
	ds_write_b64 v3, v[182:183] offset:46464
	v_pk_mul_f32 v[110:111], v[124:125], v[28:29] op_sel:[1,1] op_sel_hi:[0,1]
	v_pk_fma_f32 v[102:103], v[124:125], v[28:29], v[110:111] op_sel_hi:[1,0,1] neg_lo:[0,0,1]
	ds_write_b64 v3, v[102:103] offset:50688
	v_pk_mul_f32 v[126:127], v[174:175], v[30:31] op_sel:[1,1] op_sel_hi:[0,1]
	v_pk_fma_f32 v[118:119], v[174:175], v[30:31], v[126:127] op_sel_hi:[1,0,1] neg_lo:[0,0,1]
	ds_write_b64 v3, v[118:119] offset:54912
	v_pk_mul_f32 v[186:187], v[128:129], v[32:33] op_sel:[1,1] op_sel_hi:[0,1]
	v_pk_fma_f32 v[188:189], v[128:129], v[32:33], v[186:187] op_sel_hi:[1,0,1] neg_lo:[0,0,1]
	ds_write_b64 v3, v[188:189] offset:59136
	v_pk_mul_f32 v[184:185], v[130:131], v[34:35] op_sel:[1,1] op_sel_hi:[0,1]
	v_pk_fma_f32 v[168:169], v[130:131], v[34:35], v[184:185] op_sel_hi:[1,0,1] neg_lo:[0,0,1]
	ds_write_b64 v3, v[168:169] offset:63360
	s_waitcnt lgkmcnt(0)
	s_barrier
; #define LAS __attribute__((address_space(3)))
; __device__ __forceinline__ f32x2 cmul(f32x2 a, f32x2 b) { return (f32x2){a.x * b.x - a.y * b.y, a.x * b.y + a.y * b.x}; }
; template <bool INV> __device__ __forceinline__ f32x2 cmul_tw(f32x2 a, f32x2 w) { return INV ? cmulc(a, w) : cmul(a, w); }
; template <bool INV> __device__ __forceinline__ void dft16(f32x2 (&x)[16]) {
;     constexpr float C1 = 0.92387953251128674f, S1 = 0.38268343236508977f, C2 = 0.70710678118654752f;
; #pragma unroll
;     for (int b = 0; b < 4; ++b) dft4<INV>(x[b], x[4 + b], x[8 + b], x[12 + b]);
;     const f32x2 w1 = {C1, -S1}, w2 = {C2, -C2}, w3 = {S1, -C1}, w4 = {0.f, -1.f}, w6 = {-C2, -C2}, w9 = {-C1, S1};
;     x[4 * 1 + 1] = cmul_tw<INV>(x[5], w1); x[4 * 1 + 2] = cmul_tw<INV>(x[6], w2); x[4 * 1 + 3] = cmul_tw<INV>(x[7], w3);
;     x[4 * 2 + 1] = cmul_tw<INV>(x[9], w2); x[4 * 2 + 2] = cmul_tw<INV>(x[10], w4); x[4 * 2 + 3] = cmul_tw<INV>(x[11], w6);
;     x[4 * 3 + 1] = cmul_tw<INV>(x[13], w3); x[4 * 3 + 2] = cmul_tw<INV>(x[14], w6); x[4 * 3 + 3] = cmul_tw<INV>(x[15], w9);
; #pragma unroll
;     for (int c = 0; c < 4; ++c) dft4<INV>(x[4 * c], x[4 * c + 1], x[4 * c + 2], x[4 * c + 3]);
;     f32x2 y[16];
; #pragma unroll
;     for (int k = 0; k < 16; ++k) y[k] = x[4 * (k & 3) + (k >> 2)];
; #pragma unroll
;     for (int k = 0; k < 16; ++k) x[k] = y[k];
; }
; __device__ __forceinline__ void fft_fwd2(LAS f32x2* B, const LAS f32x2* TW2, int tid) {
;     asm volatile("" : "+v"(tid));
;     const int b = tid >> 5, n2 = tid & 31, base = 512 * b + n2; f32x2 x[16];
; #pragma unroll
;     for (int r = 0; r < 16; ++r) x[r] = B[fpad(base + 32 * r)];
;     dft16<false>(x);
;     B[fpad(base)] = x[0];
; #pragma unroll
;     for (int k = 1; k < 16; ++k) B[fpad(base + 32 * k)] = cmul(x[k], TW2[k * 32 + n2]);
; }
	ds_read_b64 v[100:101], v5
	ds_read_b64 v[108:109], v5 offset:1056
	ds_read_b64 v[116:117], v5 offset:2112
	ds_read_b64 v[124:125], v5 offset:3168
	ds_read_b64 v[178:179], v5 offset:264
	ds_read_b64 v[176:177], v5 offset:1320
	ds_read_b64 v[166:167], v5 offset:2376
	ds_read_b64 v[174:175], v5 offset:3432
	ds_read_b64 v[104:105], v5 offset:528
	ds_read_b64 v[112:113], v5 offset:1584
	ds_read_b64 v[120:121], v5 offset:2640
	ds_read_b64 v[128:129], v5 offset:3696
	s_waitcnt lgkmcnt(8)
	ds_read_b64 v[106:107], v5 offset:792
	ds_read_b64 v[114:115], v5 offset:1848
	ds_read_b64 v[122:123], v5 offset:2904
	ds_read_b64 v[130:131], v5 offset:3960
	v_pk_add_f32 v[180:181], v[100:101], v[116:117]
	v_pk_add_f32 v[182:183], v[100:101], v[116:117] neg_lo:[0,1] neg_hi:[0,1]
	v_pk_add_f32 v[110:111], v[108:109], v[124:125]
	v_pk_add_f32 v[102:103], v[108:109], v[124:125] neg_lo:[0,1] neg_hi:[0,1]
	v_pk_add_f32 v[100:101], v[180:181], v[110:111]
	v_pk_add_f32 v[116:117], v[180:181], v[110:111] neg_lo:[0,1] neg_hi:[0,1]
	v_pk_add_f32 v[108:109], v[182:183], v[102:103] op_sel:[0,1] op_sel_hi:[1,0] neg_hi:[0,1]
	v_pk_add_f32 v[124:125], v[182:183], v[102:103] op_sel:[0,1] op_sel_hi:[1,0] neg_lo:[0,1]
	s_waitcnt lgkmcnt(9)
	v_pk_add_f32 v[126:127], v[178:179], v[166:167]
	v_pk_add_f32 v[118:119], v[178:179], v[166:167] neg_lo:[0,1] neg_hi:[0,1]
	s_waitcnt lgkmcnt(8)
	v_pk_add_f32 v[186:187], v[176:177], v[174:175]
	v_pk_add_f32 v[188:189], v[176:177], v[174:175] neg_lo:[0,1] neg_hi:[0,1]
	v_pk_add_f32 v[178:179], v[126:127], v[186:187]
	v_pk_add_f32 v[166:167], v[126:127], v[186:187] neg_lo:[0,1] neg_hi:[0,1]
	v_pk_add_f32 v[176:177], v[118:119], v[188:189] op_sel:[0,1] op_sel_hi:[1,0] neg_hi:[0,1]
	v_pk_add_f32 v[174:175], v[118:119], v[188:189] op_sel:[0,1] op_sel_hi:[1,0] neg_lo:[0,1]
	s_waitcnt lgkmcnt(5)
	v_pk_add_f32 v[184:185], v[104:105], v[120:121]
	v_pk_add_f32 v[168:169], v[104:105], v[120:121] neg_lo:[0,1] neg_hi:[0,1]
	s_waitcnt lgkmcnt(4)
	v_pk_add_f32 v[180:181], v[112:113], v[128:129]
	v_pk_add_f32 v[182:183], v[112:113], v[128:129] neg_lo:[0,1] neg_hi:[0,1]
	v_pk_add_f32 v[104:105], v[184:185], v[180:181]
	v_pk_add_f32 v[120:121], v[184:185], v[180:181] neg_lo:[0,1] neg_hi:[0,1]
	v_pk_add_f32 v[112:113], v[168:169], v[182:183] op_sel:[0,1] op_sel_hi:[1,0] neg_hi:[0,1]
	v_pk_add_f32 v[128:129], v[168:169], v[182:183] op_sel:[0,1] op_sel_hi:[1,0] neg_lo:[0,1]
	s_waitcnt lgkmcnt(1)
	v_pk_add_f32 v[110:111], v[106:107], v[122:123]
	v_pk_add_f32 v[102:103], v[106:107], v[122:123] neg_lo:[0,1] neg_hi:[0,1]
	s_waitcnt lgkmcnt(0)
	v_pk_add_f32 v[126:127], v[114:115], v[130:131]
	v_pk_add_f32 v[118:119], v[114:115], v[130:131] neg_lo:[0,1] neg_hi:[0,1]
	v_pk_add_f32 v[106:107], v[110:111], v[126:127]
	v_pk_add_f32 v[122:123], v[110:111], v[126:127] neg_lo:[0,1] neg_hi:[0,1]
	v_pk_add_f32 v[114:115], v[102:103], v[118:119] op_sel:[0,1] op_sel_hi:[1,0] neg_hi:[0,1]
	v_pk_add_f32 v[130:131], v[102:103], v[118:119] op_sel:[0,1] op_sel_hi:[1,0] neg_lo:[0,1]
	v_pk_mul_f32 v[186:187], v[176:177], s[68:69] op_sel:[1,1] op_sel_hi:[0,1]
	v_pk_fma_f32 v[176:177], v[176:177], s[68:69], v[186:187] op_sel_hi:[1,0,1] neg_lo:[0,0,1]
	v_pk_mul_f32 v[188:189], v[112:113], s[84:85] op_sel:[1,1] op_sel_hi:[0,1]
	v_pk_fma_f32 v[112:113], v[112:113], s[84:85], v[188:189] op_sel_hi:[1,0,1] neg_lo:[0,0,1]
	v_pk_mul_f32 v[184:185], v[114:115], s[88:89] op_sel:[1,1] op_sel_hi:[0,1]
	v_pk_fma_f32 v[114:115], v[114:115], s[88:89], v[184:185] op_sel_hi:[1,0,1] neg_lo:[0,0,1]
	v_pk_mul_f32 v[168:169], v[166:167], s[84:85] op_sel:[1,1] op_sel_hi:[0,1]
	v_pk_fma_f32 v[166:167], v[166:167], s[84:85], v[168:169] op_sel_hi:[1,0,1] neg_lo:[0,0,1]
	v_pk_mul_f32 v[180:181], v[122:123], s[90:91] op_sel:[1,1] op_sel_hi:[0,1]
	v_pk_fma_f32 v[122:123], v[122:123], s[90:91], v[180:181] op_sel_hi:[1,0,1] neg_lo:[0,0,1]
	v_pk_mul_f32 v[182:183], v[174:175], s[88:89] op_sel:[1,1] op_sel_hi:[0,1]
	v_pk_fma_f32 v[174:175], v[174:175], s[88:89], v[182:183] op_sel_hi:[1,0,1] neg_lo:[0,0,1]
	v_pk_mul_f32 v[110:111], v[128:129], s[90:91] op_sel:[1,1] op_sel_hi:[0,1]
	v_pk_fma_f32 v[128:129], v[128:129], s[90:91], v[110:111] op_sel_hi:[1,0,1] neg_lo:[0,0,1]
	v_pk_mul_f32 v[102:103], v[130:131], s[98:99] op_sel:[1,1] op_sel_hi:[0,1]
	v_pk_fma_f32 v[130:131], v[130:131], s[98:99], v[102:103] op_sel_hi:[1,0,1] neg_lo:[0,0,1]
	v_pk_add_f32 v[126:127], v[100:101], v[104:105]
	v_pk_add_f32 v[118:119], v[100:101], v[104:105] neg_lo:[0,1] neg_hi:[0,1]
	v_pk_add_f32 v[186:187], v[178:179], v[106:107]
	v_pk_add_f32 v[188:189], v[178:179], v[106:107] neg_lo:[0,1] neg_hi:[0,1]
	v_pk_add_f32 v[100:101], v[126:127], v[186:187]
	v_pk_add_f32 v[104:105], v[126:127], v[186:187] neg_lo:[0,1] neg_hi:[0,1]
	v_pk_add_f32 v[178:179], v[118:119], v[188:189] op_sel:[0,1] op_sel_hi:[1,0] neg_hi:[0,1]
	v_pk_add_f32 v[106:107], v[118:119], v[188:189] op_sel:[0,1] op_sel_hi:[1,0] neg_lo:[0,1]
	v_pk_add_f32 v[184:185], v[108:109], v[112:113]
	v_pk_add_f32 v[168:169], v[108:109], v[112:113] neg_lo:[0,1] neg_hi:[0,1]
	v_pk_add_f32 v[180:181], v[176:177], v[114:115]
	v_pk_add_f32 v[182:183], v[176:177], v[114:115] neg_lo:[0,1] neg_hi:[0,1]
	v_pk_add_f32 v[108:109], v[184:185], v[180:181]
	v_pk_add_f32 v[112:113], v[184:185], v[180:181] neg_lo:[0,1] neg_hi:[0,1]
	v_pk_add_f32 v[176:177], v[168:169], v[182:183] op_sel:[0,1] op_sel_hi:[1,0] neg_hi:[0,1]
	v_pk_add_f32 v[114:115], v[168:169], v[182:183] op_sel:[0,1] op_sel_hi:[1,0] neg_lo:[0,1]
	v_pk_add_f32 v[110:111], v[116:117], v[120:121] op_sel:[0,1] op_sel_hi:[1,0] neg_hi:[0,1]
	v_pk_add_f32 v[102:103], v[116:117], v[120:121] op_sel:[0,1] op_sel_hi:[1,0] neg_lo:[0,1]
	v_pk_add_f32 v[126:127], v[166:167], v[122:123]
	v_pk_add_f32 v[118:119], v[166:167], v[122:123] neg_lo:[0,1] neg_hi:[0,1]
	v_pk_add_f32 v[116:117], v[110:111], v[126:127]
	v_pk_add_f32 v[120:121], v[110:111], v[126:127] neg_lo:[0,1] neg_hi:[0,1]
	v_pk_add_f32 v[166:167], v[102:103], v[118:119] op_sel:[0,1] op_sel_hi:[1,0] neg_hi:[0,1]
	v_pk_add_f32 v[122:123], v[102:103], v[118:119] op_sel:[0,1] op_sel_hi:[1,0] neg_lo:[0,1]
	v_pk_add_f32 v[186:187], v[124:125], v[128:129]
	v_pk_add_f32 v[188:189], v[124:125], v[128:129] neg_lo:[0,1] neg_hi:[0,1]
	v_pk_add_f32 v[184:185], v[174:175], v[130:131]
	v_pk_add_f32 v[168:169], v[174:175], v[130:131] neg_lo:[0,1] neg_hi:[0,1]
	v_pk_add_f32 v[124:125], v[186:187], v[184:185]
	v_pk_add_f32 v[128:129], v[186:187], v[184:185] neg_lo:[0,1] neg_hi:[0,1]
	v_pk_add_f32 v[174:175], v[188:189], v[168:169] op_sel:[0,1] op_sel_hi:[1,0] neg_hi:[0,1]
	v_pk_add_f32 v[130:131], v[188:189], v[168:169] op_sel:[0,1] op_sel_hi:[1,0] neg_lo:[0,1]
	ds_write_b64 v5, v[100:101]
	ds_read_b64 v[180:181], v56 offset:256
	ds_read_b64 v[182:183], v56 offset:512
	ds_read_b64 v[110:111], v56 offset:768
	ds_read_b64 v[102:103], v56 offset:1024
	s_waitcnt lgkmcnt(3)
; #define LAS __attribute__((address_space(3)))
; __device__ __forceinline__ f32x2 cmul(f32x2 a, f32x2 b) { return (f32x2){a.x * b.x - a.y * b.y, a.x * b.y + a.y * b.x}; }
; __device__ __forceinline__ void fft_fwd2(LAS f32x2* B, const LAS f32x2* TW2, int tid) {
;     asm volatile("" : "+v"(tid));
;     const int b = tid >> 5, n2 = tid & 31, base = 512 * b + n2; f32x2 x[16];
; #pragma unroll
;     for (int r = 0; r < 16; ++r) x[r] = B[fpad(base + 32 * r)];
;     dft16<false>(x);
;     B[fpad(base)] = x[0];
; #pragma unroll
;     for (int k = 1; k < 16; ++k) B[fpad(base + 32 * k)] = cmul(x[k], TW2[k * 32 + n2]);
; }
; template <int MODE> __device__ __forceinline__ void fft_pair32(LAS f32x2* B, const LAS f32x2* F, int wave, int lane) {
;     asm volatile("" : "+v"(lane));
;     constexpr float CS[16] = {1.f, 0.98078528040323043f, 0.92387953251128674f, 0.83146961230254524f, 0.70710678118654752f, 0.55557023301960218f, 0.38268343236508977f, 0.19509032201612825f,
;                               0.f, -0.19509032201612825f, -0.38268343236508977f, -0.55557023301960218f, -0.70710678118654752f, -0.83146961230254524f, -0.92387953251128674f, -0.98078528040323043f};
;     constexpr float SN[16] = {0.f, 0.19509032201612825f, 0.38268343236508977f, 0.55557023301960218f, 0.70710678118654752f, 0.83146961230254524f, 0.92387953251128674f, 0.98078528040323043f,
;                               1.f, 0.98078528040323043f, 0.92387953251128674f, 0.83146961230254524f, 0.70710678118654752f, 0.55557023301960218f, 0.38268343236508977f, 0.19509032201612825f};
;     const int hi = lane >> 5, blk = 32 * wave + (lane & 31); const float sg = hi ? -1.f : 1.f;
;     LAS f32x2* p = B + 33 * blk; f32x2 v[16];
; #pragma unroll
;     for (int j = 0; j < 16; ++j) { const f32x2 d = p[j] + p[j + 16] * sg;
;         const f32x2 w = {hi ? CS[j] : 1.f, hi ? -SN[j] : 0.f}; v[j] = j == 0 ? d : cmul(d, w); }
;     dft16<false>(v);
	v_pk_mul_f32 v[126:127], v[108:109], v[180:181] op_sel:[1,1] op_sel_hi:[0,1]
	v_pk_fma_f32 v[108:109], v[108:109], v[180:181], v[126:127] op_sel_hi:[1,0,1] neg_lo:[0,0,1]
	ds_write_b64 v5, v[108:109] offset:264
	s_waitcnt lgkmcnt(3)
	v_pk_mul_f32 v[118:119], v[116:117], v[182:183] op_sel:[1,1] op_sel_hi:[0,1]
	v_pk_fma_f32 v[116:117], v[116:117], v[182:183], v[118:119] op_sel_hi:[1,0,1] neg_lo:[0,0,1]
	ds_write_b64 v5, v[116:117] offset:528
	s_waitcnt lgkmcnt(3)
	v_pk_mul_f32 v[186:187], v[124:125], v[110:111] op_sel:[1,1] op_sel_hi:[0,1]
	v_pk_fma_f32 v[124:125], v[124:125], v[110:111], v[186:187] op_sel_hi:[1,0,1] neg_lo:[0,0,1]
	ds_write_b64 v5, v[124:125] offset:792
	s_waitcnt lgkmcnt(3)
	v_pk_mul_f32 v[188:189], v[178:179], v[102:103] op_sel:[1,1] op_sel_hi:[0,1]
	v_pk_fma_f32 v[178:179], v[178:179], v[102:103], v[188:189] op_sel_hi:[1,0,1] neg_lo:[0,0,1]
	ds_write_b64 v5, v[178:179] offset:1056
	ds_read_b64 v[184:185], v56 offset:1280
	ds_read_b64 v[168:169], v56 offset:1536
	ds_read_b64 v[126:127], v56 offset:1792
	ds_read_b64 v[118:119], v56 offset:2048
	s_waitcnt lgkmcnt(3)
	v_pk_mul_f32 v[186:187], v[176:177], v[184:185] op_sel:[1,1] op_sel_hi:[0,1]
	v_pk_fma_f32 v[176:177], v[176:177], v[184:185], v[186:187] op_sel_hi:[1,0,1] neg_lo:[0,0,1]
	ds_write_b64 v5, v[176:177] offset:1320
	s_waitcnt lgkmcnt(3)
	v_pk_mul_f32 v[188:189], v[166:167], v[168:169] op_sel:[1,1] op_sel_hi:[0,1]
	v_pk_fma_f32 v[166:167], v[166:167], v[168:169], v[188:189] op_sel_hi:[1,0,1] neg_lo:[0,0,1]
	ds_write_b64 v5, v[166:167] offset:1584
	s_waitcnt lgkmcnt(3)
	v_pk_mul_f32 v[180:181], v[174:175], v[126:127] op_sel:[1,1] op_sel_hi:[0,1]
	v_pk_fma_f32 v[174:175], v[174:175], v[126:127], v[180:181] op_sel_hi:[1,0,1] neg_lo:[0,0,1]
	ds_write_b64 v5, v[174:175] offset:1848
	s_waitcnt lgkmcnt(3)
	v_pk_mul_f32 v[182:183], v[104:105], v[118:119] op_sel:[1,1] op_sel_hi:[0,1]
	v_pk_fma_f32 v[104:105], v[104:105], v[118:119], v[182:183] op_sel_hi:[1,0,1] neg_lo:[0,0,1]
	ds_write_b64 v5, v[104:105] offset:2112
	ds_read_b64 v[110:111], v56 offset:2304
	ds_read_b64 v[102:103], v56 offset:2560
	ds_read_b64 v[186:187], v56 offset:2816
	ds_read_b64 v[188:189], v56 offset:3072
	s_waitcnt lgkmcnt(3)
	v_pk_mul_f32 v[180:181], v[112:113], v[110:111] op_sel:[1,1] op_sel_hi:[0,1]
	v_pk_fma_f32 v[112:113], v[112:113], v[110:111], v[180:181] op_sel_hi:[1,0,1] neg_lo:[0,0,1]
	ds_write_b64 v5, v[112:113] offset:2376
	s_waitcnt lgkmcnt(3)
	v_pk_mul_f32 v[182:183], v[120:121], v[102:103] op_sel:[1,1] op_sel_hi:[0,1]
	v_pk_fma_f32 v[120:121], v[120:121], v[102:103], v[182:183] op_sel_hi:[1,0,1] neg_lo:[0,0,1]
	ds_write_b64 v5, v[120:121] offset:2640
	s_waitcnt lgkmcnt(3)
	v_pk_mul_f32 v[184:185], v[128:129], v[186:187] op_sel:[1,1] op_sel_hi:[0,1]
	v_pk_fma_f32 v[128:129], v[128:129], v[186:187], v[184:185] op_sel_hi:[1,0,1] neg_lo:[0,0,1]
	ds_write_b64 v5, v[128:129] offset:2904
	s_waitcnt lgkmcnt(3)
	v_pk_mul_f32 v[168:169], v[106:107], v[188:189] op_sel:[1,1] op_sel_hi:[0,1]
	v_pk_fma_f32 v[106:107], v[106:107], v[188:189], v[168:169] op_sel_hi:[1,0,1] neg_lo:[0,0,1]
	ds_write_b64 v5, v[106:107] offset:3168
	ds_read_b64 v[126:127], v56 offset:3328
	ds_read_b64 v[118:119], v56 offset:3584
	ds_read_b64 v[180:181], v56 offset:3840
	s_waitcnt lgkmcnt(2)
	v_pk_mul_f32 v[182:183], v[114:115], v[126:127] op_sel:[1,1] op_sel_hi:[0,1]
	v_pk_fma_f32 v[114:115], v[114:115], v[126:127], v[182:183] op_sel_hi:[1,0,1] neg_lo:[0,0,1]
	ds_write_b64 v5, v[114:115] offset:3432
	s_waitcnt lgkmcnt(2)
	v_pk_mul_f32 v[184:185], v[122:123], v[118:119] op_sel:[1,1] op_sel_hi:[0,1]
	v_pk_fma_f32 v[122:123], v[122:123], v[118:119], v[184:185] op_sel_hi:[1,0,1] neg_lo:[0,0,1]
	ds_write_b64 v5, v[122:123] offset:3696
	s_waitcnt lgkmcnt(2)
	v_pk_mul_f32 v[168:169], v[130:131], v[180:181] op_sel:[1,1] op_sel_hi:[0,1]
	v_pk_fma_f32 v[130:131], v[130:131], v[180:181], v[168:169] op_sel_hi:[1,0,1] neg_lo:[0,0,1]
	ds_write_b64 v5, v[130:131] offset:3960
	s_waitcnt lgkmcnt(0)
	ds_read_b64 v[100:101], v156
	ds_read_b64 v[110:111], v156 offset:128
	ds_read_b64 v[108:109], v156 offset:8
	ds_read_b64 v[102:103], v156 offset:136
	ds_read_b64 v[116:117], v156 offset:16
	ds_read_b64 v[186:187], v156 offset:144
	ds_read_b64 v[124:125], v156 offset:24
	ds_read_b64 v[188:189], v156 offset:152
	s_waitcnt lgkmcnt(6)
	v_pk_fma_f32 v[100:101], v[110:111], v[190:191], v[100:101] op_sel_hi:[1,0,1]
	s_waitcnt lgkmcnt(4)
	v_pk_fma_f32 v[108:109], v[102:103], v[190:191], v[108:109] op_sel_hi:[1,0,1]
	v_pk_mul_f32 v[182:183], v[108:109], v[36:37] op_sel:[1,1] op_sel_hi:[0,1]
	v_pk_fma_f32 v[108:109], v[108:109], v[36:37], v[182:183] op_sel_hi:[1,0,1] neg_lo:[0,0,1]
	s_waitcnt lgkmcnt(2)
	v_pk_fma_f32 v[116:117], v[186:187], v[190:191], v[116:117] op_sel_hi:[1,0,1]
	v_pk_mul_f32 v[184:185], v[116:117], v[38:39] op_sel:[1,1] op_sel_hi:[0,1]
	v_pk_fma_f32 v[116:117], v[116:117], v[38:39], v[184:185] op_sel_hi:[1,0,1] neg_lo:[0,0,1]
	s_waitcnt lgkmcnt(0)
	v_pk_fma_f32 v[124:125], v[188:189], v[190:191], v[124:125] op_sel_hi:[1,0,1]
	v_pk_mul_f32 v[168:169], v[124:125], v[40:41] op_sel:[1,1] op_sel_hi:[0,1]
	v_pk_fma_f32 v[124:125], v[124:125], v[40:41], v[168:169] op_sel_hi:[1,0,1] neg_lo:[0,0,1]
	ds_read_b64 v[178:179], v156 offset:32
	ds_read_b64 v[126:127], v156 offset:160
	ds_read_b64 v[176:177], v156 offset:40
	ds_read_b64 v[118:119], v156 offset:168
	ds_read_b64 v[166:167], v156 offset:48
	ds_read_b64 v[180:181], v156 offset:176
	ds_read_b64 v[174:175], v156 offset:56
	ds_read_b64 v[182:183], v156 offset:184
	s_waitcnt lgkmcnt(6)
; __device__ __forceinline__ f32x2 cmul(f32x2 a, f32x2 b) { return (f32x2){a.x * b.x - a.y * b.y, a.x * b.y + a.y * b.x}; }
; template <bool INV> __device__ __forceinline__ f32x2 cmul_tw(f32x2 a, f32x2 w) { return INV ? cmulc(a, w) : cmul(a, w); }
; template <bool INV> __device__ __forceinline__ void dft16(f32x2 (&x)[16]) {
;     constexpr float C1 = 0.92387953251128674f, S1 = 0.38268343236508977f, C2 = 0.70710678118654752f;
; #pragma unroll
;     for (int b = 0; b < 4; ++b) dft4<INV>(x[b], x[4 + b], x[8 + b], x[12 + b]);
;     const f32x2 w1 = {C1, -S1}, w2 = {C2, -C2}, w3 = {S1, -C1}, w4 = {0.f, -1.f}, w6 = {-C2, -C2}, w9 = {-C1, S1};
;     x[4 * 1 + 1] = cmul_tw<INV>(x[5], w1); x[4 * 1 + 2] = cmul_tw<INV>(x[6], w2); x[4 * 1 + 3] = cmul_tw<INV>(x[7], w3);
;     x[4 * 2 + 1] = cmul_tw<INV>(x[9], w2); x[4 * 2 + 2] = cmul_tw<INV>(x[10], w4); x[4 * 2 + 3] = cmul_tw<INV>(x[11], w6);
;     x[4 * 3 + 1] = cmul_tw<INV>(x[13], w3); x[4 * 3 + 2] = cmul_tw<INV>(x[14], w6); x[4 * 3 + 3] = cmul_tw<INV>(x[15], w9);
; #pragma unroll
;     for (int c = 0; c < 4; ++c) dft4<INV>(x[4 * c], x[4 * c + 1], x[4 * c + 2], x[4 * c + 3]);
;     f32x2 y[16];
; #pragma unroll
;     for (int k = 0; k < 16; ++k) y[k] = x[4 * (k & 3) + (k >> 2)];
; #pragma unroll
;     for (int k = 0; k < 16; ++k) x[k] = y[k];
; }
; template <int MODE> __device__ __forceinline__ void fft_pair32(LAS f32x2* B, const LAS f32x2* F, int wave, int lane) {
;     ...
;     for (int j = 0; j < 16; ++j) { const f32x2 d = p[j] + p[j + 16] * sg;
;         const f32x2 w = {hi ? CS[j] : 1.f, hi ? -SN[j] : 0.f}; v[j] = j == 0 ? d : cmul(d, w); }
;     dft16<false>(v);
	v_pk_fma_f32 v[178:179], v[126:127], v[190:191], v[178:179] op_sel_hi:[1,0,1]
	v_pk_mul_f32 v[184:185], v[178:179], v[42:43] op_sel:[1,1] op_sel_hi:[0,1]
	v_pk_fma_f32 v[178:179], v[178:179], v[42:43], v[184:185] op_sel_hi:[1,0,1] neg_lo:[0,0,1]
	s_waitcnt lgkmcnt(4)
	v_pk_fma_f32 v[176:177], v[118:119], v[190:191], v[176:177] op_sel_hi:[1,0,1]
	v_pk_mul_f32 v[168:169], v[176:177], v[44:45] op_sel:[1,1] op_sel_hi:[0,1]
	v_pk_fma_f32 v[176:177], v[176:177], v[44:45], v[168:169] op_sel_hi:[1,0,1] neg_lo:[0,0,1]
	s_waitcnt lgkmcnt(2)
	v_pk_fma_f32 v[166:167], v[180:181], v[190:191], v[166:167] op_sel_hi:[1,0,1]
	v_pk_mul_f32 v[110:111], v[166:167], v[46:47] op_sel:[1,1] op_sel_hi:[0,1]
	v_pk_fma_f32 v[166:167], v[166:167], v[46:47], v[110:111] op_sel_hi:[1,0,1] neg_lo:[0,0,1]
	s_waitcnt lgkmcnt(0)
	v_pk_fma_f32 v[174:175], v[182:183], v[190:191], v[174:175] op_sel_hi:[1,0,1]
	v_pk_mul_f32 v[102:103], v[174:175], v[48:49] op_sel:[1,1] op_sel_hi:[0,1]
	v_pk_fma_f32 v[174:175], v[174:175], v[48:49], v[102:103] op_sel_hi:[1,0,1] neg_lo:[0,0,1]
	ds_read_b64 v[104:105], v156 offset:64
	ds_read_b64 v[186:187], v156 offset:192
	ds_read_b64 v[112:113], v156 offset:72
	ds_read_b64 v[188:189], v156 offset:200
	ds_read_b64 v[120:121], v156 offset:80
	ds_read_b64 v[184:185], v156 offset:208
	ds_read_b64 v[128:129], v156 offset:88
	ds_read_b64 v[168:169], v156 offset:216
	s_waitcnt lgkmcnt(6)
	v_pk_fma_f32 v[104:105], v[186:187], v[190:191], v[104:105] op_sel_hi:[1,0,1]
	v_pk_mul_f32 v[110:111], v[104:105], v[50:51] op_sel:[1,1] op_sel_hi:[0,1]
	v_pk_fma_f32 v[104:105], v[104:105], v[50:51], v[110:111] op_sel_hi:[1,0,1] neg_lo:[0,0,1]
	s_waitcnt lgkmcnt(4)
	v_pk_fma_f32 v[112:113], v[188:189], v[190:191], v[112:113] op_sel_hi:[1,0,1]
	v_pk_mul_f32 v[102:103], v[112:113], v[52:53] op_sel:[1,1] op_sel_hi:[0,1]
	v_pk_fma_f32 v[112:113], v[112:113], v[52:53], v[102:103] op_sel_hi:[1,0,1] neg_lo:[0,0,1]
	s_waitcnt lgkmcnt(2)
	v_pk_fma_f32 v[120:121], v[184:185], v[190:191], v[120:121] op_sel_hi:[1,0,1]
	v_pk_mul_f32 v[126:127], v[120:121], v[54:55] op_sel:[1,1] op_sel_hi:[0,1]
	v_pk_fma_f32 v[120:121], v[120:121], v[54:55], v[126:127] op_sel_hi:[1,0,1] neg_lo:[0,0,1]
	s_waitcnt lgkmcnt(0)
	v_pk_fma_f32 v[128:129], v[168:169], v[190:191], v[128:129] op_sel_hi:[1,0,1]
	v_pk_mul_f32 v[118:119], v[128:129], v[90:91] op_sel:[1,1] op_sel_hi:[0,1]
	v_pk_fma_f32 v[128:129], v[128:129], v[90:91], v[118:119] op_sel_hi:[1,0,1] neg_lo:[0,0,1]
	ds_read_b64 v[106:107], v156 offset:96
	ds_read_b64 v[180:181], v156 offset:224
	ds_read_b64 v[114:115], v156 offset:104
	ds_read_b64 v[182:183], v156 offset:232
	ds_read_b64 v[122:123], v156 offset:112
	ds_read_b64 v[110:111], v156 offset:240
	ds_read_b64 v[130:131], v156 offset:120
	ds_read_b64 v[102:103], v156 offset:248
	s_waitcnt lgkmcnt(6)
	v_pk_fma_f32 v[106:107], v[180:181], v[190:191], v[106:107] op_sel_hi:[1,0,1]
	v_pk_mul_f32 v[126:127], v[106:107], v[92:93] op_sel:[1,1] op_sel_hi:[0,1]
	v_pk_fma_f32 v[106:107], v[106:107], v[92:93], v[126:127] op_sel_hi:[1,0,1] neg_lo:[0,0,1]
	s_waitcnt lgkmcnt(4)
	v_pk_fma_f32 v[114:115], v[182:183], v[190:191], v[114:115] op_sel_hi:[1,0,1]
	v_pk_mul_f32 v[118:119], v[114:115], v[94:95] op_sel:[1,1] op_sel_hi:[0,1]
	v_pk_fma_f32 v[114:115], v[114:115], v[94:95], v[118:119] op_sel_hi:[1,0,1] neg_lo:[0,0,1]
	s_waitcnt lgkmcnt(2)
	v_pk_fma_f32 v[122:123], v[110:111], v[190:191], v[122:123] op_sel_hi:[1,0,1]
	v_pk_mul_f32 v[186:187], v[122:123], v[96:97] op_sel:[1,1] op_sel_hi:[0,1]
	v_pk_fma_f32 v[122:123], v[122:123], v[96:97], v[186:187] op_sel_hi:[1,0,1] neg_lo:[0,0,1]
	s_waitcnt lgkmcnt(0)
	v_pk_fma_f32 v[130:131], v[102:103], v[190:191], v[130:131] op_sel_hi:[1,0,1]
	v_pk_mul_f32 v[188:189], v[130:131], v[98:99] op_sel:[1,1] op_sel_hi:[0,1]
	v_pk_fma_f32 v[130:131], v[130:131], v[98:99], v[188:189] op_sel_hi:[1,0,1] neg_lo:[0,0,1]
	v_pk_add_f32 v[184:185], v[100:101], v[104:105]
	v_pk_add_f32 v[168:169], v[100:101], v[104:105] neg_lo:[0,1] neg_hi:[0,1]
	v_pk_add_f32 v[126:127], v[178:179], v[106:107]
	v_pk_add_f32 v[118:119], v[178:179], v[106:107] neg_lo:[0,1] neg_hi:[0,1]
	v_pk_add_f32 v[100:101], v[184:185], v[126:127]
	v_pk_add_f32 v[104:105], v[184:185], v[126:127] neg_lo:[0,1] neg_hi:[0,1]
	v_pk_add_f32 v[178:179], v[168:169], v[118:119] op_sel:[0,1] op_sel_hi:[1,0] neg_hi:[0,1]
	v_pk_add_f32 v[106:107], v[168:169], v[118:119] op_sel:[0,1] op_sel_hi:[1,0] neg_lo:[0,1]
	v_pk_add_f32 v[186:187], v[108:109], v[112:113]
	v_pk_add_f32 v[188:189], v[108:109], v[112:113] neg_lo:[0,1] neg_hi:[0,1]
	v_pk_add_f32 v[180:181], v[176:177], v[114:115]
	v_pk_add_f32 v[182:183], v[176:177], v[114:115] neg_lo:[0,1] neg_hi:[0,1]
	v_pk_add_f32 v[108:109], v[186:187], v[180:181]
	v_pk_add_f32 v[112:113], v[186:187], v[180:181] neg_lo:[0,1] neg_hi:[0,1]
	v_pk_add_f32 v[176:177], v[188:189], v[182:183] op_sel:[0,1] op_sel_hi:[1,0] neg_hi:[0,1]
	v_pk_add_f32 v[114:115], v[188:189], v[182:183] op_sel:[0,1] op_sel_hi:[1,0] neg_lo:[0,1]
	v_pk_add_f32 v[110:111], v[116:117], v[120:121]
	v_pk_add_f32 v[102:103], v[116:117], v[120:121] neg_lo:[0,1] neg_hi:[0,1]
	v_pk_add_f32 v[184:185], v[166:167], v[122:123]
	v_pk_add_f32 v[168:169], v[166:167], v[122:123] neg_lo:[0,1] neg_hi:[0,1]
	v_pk_add_f32 v[116:117], v[110:111], v[184:185]
	v_pk_add_f32 v[120:121], v[110:111], v[184:185] neg_lo:[0,1] neg_hi:[0,1]
	v_pk_add_f32 v[166:167], v[102:103], v[168:169] op_sel:[0,1] op_sel_hi:[1,0] neg_hi:[0,1]
	v_pk_add_f32 v[122:123], v[102:103], v[168:169] op_sel:[0,1] op_sel_hi:[1,0] neg_lo:[0,1]
	v_pk_add_f32 v[126:127], v[124:125], v[128:129]
	v_pk_add_f32 v[118:119], v[124:125], v[128:129] neg_lo:[0,1] neg_hi:[0,1]
; #define LAS __attribute__((address_space(3)))
; __device__ __forceinline__ f32x2 cmul(f32x2 a, f32x2 b) { return (f32x2){a.x * b.x - a.y * b.y, a.x * b.y + a.y * b.x}; }
; template <bool INV> __device__ __forceinline__ f32x2 cmul_tw(f32x2 a, f32x2 w) { return INV ? cmulc(a, w) : cmul(a, w); }
; template <bool INV> __device__ __forceinline__ void dft16(f32x2 (&x)[16]) {
;     constexpr float C1 = 0.92387953251128674f, S1 = 0.38268343236508977f, C2 = 0.70710678118654752f;
; #pragma unroll
;     for (int b = 0; b < 4; ++b) dft4<INV>(x[b], x[4 + b], x[8 + b], x[12 + b]);
;     const f32x2 w1 = {C1, -S1}, w2 = {C2, -C2}, w3 = {S1, -C1}, w4 = {0.f, -1.f}, w6 = {-C2, -C2}, w9 = {-C1, S1};
;     x[4 * 1 + 1] = cmul_tw<INV>(x[5], w1); x[4 * 1 + 2] = cmul_tw<INV>(x[6], w2); x[4 * 1 + 3] = cmul_tw<INV>(x[7], w3);
;     x[4 * 2 + 1] = cmul_tw<INV>(x[9], w2); x[4 * 2 + 2] = cmul_tw<INV>(x[10], w4); x[4 * 2 + 3] = cmul_tw<INV>(x[11], w6);
;     x[4 * 3 + 1] = cmul_tw<INV>(x[13], w3); x[4 * 3 + 2] = cmul_tw<INV>(x[14], w6); x[4 * 3 + 3] = cmul_tw<INV>(x[15], w9);
; #pragma unroll
;     for (int c = 0; c < 4; ++c) dft4<INV>(x[4 * c], x[4 * c + 1], x[4 * c + 2], x[4 * c + 3]);
;     f32x2 y[16];
; #pragma unroll
;     for (int k = 0; k < 16; ++k) y[k] = x[4 * (k & 3) + (k >> 2)];
; #pragma unroll
;     for (int k = 0; k < 16; ++k) x[k] = y[k];
; }
; template <int MODE> __device__ __forceinline__ void fft_pair32(LAS f32x2* B, const LAS f32x2* F, int wave, int lane) {
;     ...
;     const int k1 = blk >> 4, k2 = blk & 15, kb1 = (16 - k1) & 15, b1 = k1 != 0 ? 1 : 0, kb2 = (16 - k2 - b1) & 15, b2 = (k2 != 0 || b1) ? 1 : 0;
;     const LAS f32x2* fa = F + 33 * blk; const LAS f32x2* fb = F + 33 * (16 * kb1 + kb2);
;     const LAS f32x2* fah = fa + hi; const LAS f32x2* fbh = fb + (1 - b2) - hi;
;     constexpr float SC = 1.0f / (2.0f * (float)FN);
; #pragma unroll
;     for (int k = 0; k < 16; ++k) { const f32x2 A = fah[2 * k]; f32x2 Bm = fbh[31 - 2 * k];
;         if (k == 0) { const f32x2 m0 = b2 ? fb[31] : fa[0]; Bm = hi ? Bm : m0; }
;         const f32x2 H = MODE == 0 ? (f32x2){(A.x + Bm.x) * SC, (A.y - Bm.y) * SC} : (f32x2){(A.y + Bm.y) * SC, (Bm.x - A.x) * SC};
;         v[k] = cmul(v[k], H); }
	v_pk_add_f32 v[186:187], v[174:175], v[130:131]
	v_pk_add_f32 v[188:189], v[174:175], v[130:131] neg_lo:[0,1] neg_hi:[0,1]
	v_pk_add_f32 v[124:125], v[126:127], v[186:187]
	v_pk_add_f32 v[128:129], v[126:127], v[186:187] neg_lo:[0,1] neg_hi:[0,1]
	v_pk_add_f32 v[174:175], v[118:119], v[188:189] op_sel:[0,1] op_sel_hi:[1,0] neg_hi:[0,1]
	v_pk_add_f32 v[130:131], v[118:119], v[188:189] op_sel:[0,1] op_sel_hi:[1,0] neg_lo:[0,1]
	v_pk_mul_f32 v[180:181], v[176:177], s[68:69] op_sel:[1,1] op_sel_hi:[0,1]
	v_pk_fma_f32 v[176:177], v[176:177], s[68:69], v[180:181] op_sel_hi:[1,0,1] neg_lo:[0,0,1]
	v_pk_mul_f32 v[182:183], v[166:167], s[84:85] op_sel:[1,1] op_sel_hi:[0,1]
	v_pk_fma_f32 v[166:167], v[166:167], s[84:85], v[182:183] op_sel_hi:[1,0,1] neg_lo:[0,0,1]
	v_pk_mul_f32 v[110:111], v[174:175], s[88:89] op_sel:[1,1] op_sel_hi:[0,1]
	v_pk_fma_f32 v[174:175], v[174:175], s[88:89], v[110:111] op_sel_hi:[1,0,1] neg_lo:[0,0,1]
	v_pk_mul_f32 v[102:103], v[112:113], s[84:85] op_sel:[1,1] op_sel_hi:[0,1]
	v_pk_fma_f32 v[112:113], v[112:113], s[84:85], v[102:103] op_sel_hi:[1,0,1] neg_lo:[0,0,1]
	v_pk_mul_f32 v[184:185], v[128:129], s[90:91] op_sel:[1,1] op_sel_hi:[0,1]
	v_pk_fma_f32 v[128:129], v[128:129], s[90:91], v[184:185] op_sel_hi:[1,0,1] neg_lo:[0,0,1]
	v_pk_mul_f32 v[168:169], v[114:115], s[88:89] op_sel:[1,1] op_sel_hi:[0,1]
	v_pk_fma_f32 v[114:115], v[114:115], s[88:89], v[168:169] op_sel_hi:[1,0,1] neg_lo:[0,0,1]
	v_pk_mul_f32 v[126:127], v[122:123], s[90:91] op_sel:[1,1] op_sel_hi:[0,1]
	v_pk_fma_f32 v[122:123], v[122:123], s[90:91], v[126:127] op_sel_hi:[1,0,1] neg_lo:[0,0,1]
	v_pk_mul_f32 v[118:119], v[130:131], s[98:99] op_sel:[1,1] op_sel_hi:[0,1]
	v_pk_fma_f32 v[130:131], v[130:131], s[98:99], v[118:119] op_sel_hi:[1,0,1] neg_lo:[0,0,1]
	v_pk_add_f32 v[186:187], v[100:101], v[116:117]
	v_pk_add_f32 v[188:189], v[100:101], v[116:117] neg_lo:[0,1] neg_hi:[0,1]
	v_pk_add_f32 v[180:181], v[108:109], v[124:125]
	v_pk_add_f32 v[182:183], v[108:109], v[124:125] neg_lo:[0,1] neg_hi:[0,1]
	v_pk_add_f32 v[100:101], v[186:187], v[180:181]
	v_pk_add_f32 v[116:117], v[186:187], v[180:181] neg_lo:[0,1] neg_hi:[0,1]
	v_pk_add_f32 v[108:109], v[188:189], v[182:183] op_sel:[0,1] op_sel_hi:[1,0] neg_hi:[0,1]
	v_pk_add_f32 v[124:125], v[188:189], v[182:183] op_sel:[0,1] op_sel_hi:[1,0] neg_lo:[0,1]
	v_pk_add_f32 v[110:111], v[178:179], v[166:167]
	v_pk_add_f32 v[102:103], v[178:179], v[166:167] neg_lo:[0,1] neg_hi:[0,1]
	v_pk_add_f32 v[184:185], v[176:177], v[174:175]
	v_pk_add_f32 v[168:169], v[176:177], v[174:175] neg_lo:[0,1] neg_hi:[0,1]
	v_pk_add_f32 v[178:179], v[110:111], v[184:185]
	v_pk_add_f32 v[166:167], v[110:111], v[184:185] neg_lo:[0,1] neg_hi:[0,1]
	v_pk_add_f32 v[176:177], v[102:103], v[168:169] op_sel:[0,1] op_sel_hi:[1,0] neg_hi:[0,1]
	v_pk_add_f32 v[174:175], v[102:103], v[168:169] op_sel:[0,1] op_sel_hi:[1,0] neg_lo:[0,1]
	v_pk_add_f32 v[126:127], v[104:105], v[120:121] op_sel:[0,1] op_sel_hi:[1,0] neg_hi:[0,1]
	v_pk_add_f32 v[118:119], v[104:105], v[120:121] op_sel:[0,1] op_sel_hi:[1,0] neg_lo:[0,1]
	v_pk_add_f32 v[186:187], v[112:113], v[128:129]
	v_pk_add_f32 v[188:189], v[112:113], v[128:129] neg_lo:[0,1] neg_hi:[0,1]
	v_pk_add_f32 v[104:105], v[126:127], v[186:187]
	v_pk_add_f32 v[120:121], v[126:127], v[186:187] neg_lo:[0,1] neg_hi:[0,1]
	v_pk_add_f32 v[112:113], v[118:119], v[188:189] op_sel:[0,1] op_sel_hi:[1,0] neg_hi:[0,1]
	v_pk_add_f32 v[128:129], v[118:119], v[188:189] op_sel:[0,1] op_sel_hi:[1,0] neg_lo:[0,1]
	v_pk_add_f32 v[180:181], v[106:107], v[122:123]
	v_pk_add_f32 v[182:183], v[106:107], v[122:123] neg_lo:[0,1] neg_hi:[0,1]
	v_pk_add_f32 v[110:111], v[114:115], v[130:131]
	v_pk_add_f32 v[102:103], v[114:115], v[130:131] neg_lo:[0,1] neg_hi:[0,1]
	v_pk_add_f32 v[106:107], v[180:181], v[110:111]
	v_pk_add_f32 v[122:123], v[180:181], v[110:111] neg_lo:[0,1] neg_hi:[0,1]
	v_pk_add_f32 v[114:115], v[182:183], v[102:103] op_sel:[0,1] op_sel_hi:[1,0] neg_hi:[0,1]
	v_pk_add_f32 v[130:131], v[182:183], v[102:103] op_sel:[0,1] op_sel_hi:[1,0] neg_lo:[0,1]
	ds_read_b64 v[184:185], v200
	ds_read_b64 v[186:187], v204
	ds_read_b64 v[168:169], v200 offset:16
	ds_read_b64 v[188:189], v202 offset:232
	ds_read_b64 v[126:127], v200 offset:32
	ds_read_b64 v[180:181], v202 offset:216
	ds_read_b64 v[118:119], v200 offset:48
	ds_read_b64 v[182:183], v202 offset:200
	s_waitcnt lgkmcnt(6)
	v_pk_add_f32 v[184:185], v[184:185], v[186:187] neg_hi:[0,1]
	v_pk_mul_f32 v[110:111], v[100:101], v[184:185] op_sel:[1,1] op_sel_hi:[0,1]
	v_pk_fma_f32 v[100:101], v[100:101], v[184:185], v[110:111] op_sel_hi:[1,0,1] neg_lo:[0,0,1]
	s_waitcnt lgkmcnt(4)
	v_pk_add_f32 v[168:169], v[168:169], v[188:189] neg_hi:[0,1]
	v_pk_mul_f32 v[102:103], v[178:179], v[168:169] op_sel:[1,1] op_sel_hi:[0,1]
	v_pk_fma_f32 v[178:179], v[178:179], v[168:169], v[102:103] op_sel_hi:[1,0,1] neg_lo:[0,0,1]
	s_waitcnt lgkmcnt(2)
	v_pk_add_f32 v[126:127], v[126:127], v[180:181] neg_hi:[0,1]
	v_pk_mul_f32 v[110:111], v[104:105], v[126:127] op_sel:[1,1] op_sel_hi:[0,1]
	v_pk_fma_f32 v[104:105], v[104:105], v[126:127], v[110:111] op_sel_hi:[1,0,1] neg_lo:[0,0,1]
	s_waitcnt lgkmcnt(0)
	v_pk_add_f32 v[118:119], v[118:119], v[182:183] neg_hi:[0,1]
	v_pk_mul_f32 v[102:103], v[106:107], v[118:119] op_sel:[1,1] op_sel_hi:[0,1]
	v_pk_fma_f32 v[106:107], v[106:107], v[118:119], v[102:103] op_sel_hi:[1,0,1] neg_lo:[0,0,1]
	ds_read_b64 v[110:111], v200 offset:64
	ds_read_b64 v[126:127], v202 offset:184
	ds_read_b64 v[102:103], v200 offset:80
	ds_read_b64 v[118:119], v202 offset:168
	ds_read_b64 v[184:185], v200 offset:96
	ds_read_b64 v[186:187], v202 offset:152
	ds_read_b64 v[168:169], v200 offset:112
	ds_read_b64 v[188:189], v202 offset:136
	s_waitcnt lgkmcnt(6)
; __device__ __forceinline__ f32x2 cmul(f32x2 a, f32x2 b) { return (f32x2){a.x * b.x - a.y * b.y, a.x * b.y + a.y * b.x}; }
; template <bool INV> __device__ __forceinline__ f32x2 cmul_tw(f32x2 a, f32x2 w) { return INV ? cmulc(a, w) : cmul(a, w); }
; template <bool INV> __device__ __forceinline__ void dft16(f32x2 (&x)[16]) {
;     constexpr float C1 = 0.92387953251128674f, S1 = 0.38268343236508977f, C2 = 0.70710678118654752f;
; #pragma unroll
;     for (int b = 0; b < 4; ++b) dft4<INV>(x[b], x[4 + b], x[8 + b], x[12 + b]);
;     const f32x2 w1 = {C1, -S1}, w2 = {C2, -C2}, w3 = {S1, -C1}, w4 = {0.f, -1.f}, w6 = {-C2, -C2}, w9 = {-C1, S1};
;     x[4 * 1 + 1] = cmul_tw<INV>(x[5], w1); x[4 * 1 + 2] = cmul_tw<INV>(x[6], w2); x[4 * 1 + 3] = cmul_tw<INV>(x[7], w3);
;     x[4 * 2 + 1] = cmul_tw<INV>(x[9], w2); x[4 * 2 + 2] = cmul_tw<INV>(x[10], w4); x[4 * 2 + 3] = cmul_tw<INV>(x[11], w6);
;     x[4 * 3 + 1] = cmul_tw<INV>(x[13], w3); x[4 * 3 + 2] = cmul_tw<INV>(x[14], w6); x[4 * 3 + 3] = cmul_tw<INV>(x[15], w9);
; #pragma unroll
;     for (int c = 0; c < 4; ++c) dft4<INV>(x[4 * c], x[4 * c + 1], x[4 * c + 2], x[4 * c + 3]);
;     f32x2 y[16];
; #pragma unroll
;     for (int k = 0; k < 16; ++k) y[k] = x[4 * (k & 3) + (k >> 2)];
; #pragma unroll
;     for (int k = 0; k < 16; ++k) x[k] = y[k];
; }
; template <int MODE> __device__ __forceinline__ void fft_pair32(LAS f32x2* B, const LAS f32x2* F, int wave, int lane) {
;     ...
;     for (int k = 0; k < 16; ++k) { const f32x2 A = fah[2 * k]; f32x2 Bm = fbh[31 - 2 * k];
;         if (k == 0) { const f32x2 m0 = b2 ? fb[31] : fa[0]; Bm = hi ? Bm : m0; }
;         const f32x2 H = MODE == 0 ? (f32x2){(A.x + Bm.x) * SC, (A.y - Bm.y) * SC} : (f32x2){(A.y + Bm.y) * SC, (Bm.x - A.x) * SC};
;         v[k] = cmul(v[k], H); }
;     dft16<true>(v);
	v_pk_add_f32 v[110:111], v[110:111], v[126:127] neg_hi:[0,1]
	v_pk_mul_f32 v[180:181], v[108:109], v[110:111] op_sel:[1,1] op_sel_hi:[0,1]
	v_pk_fma_f32 v[108:109], v[108:109], v[110:111], v[180:181] op_sel_hi:[1,0,1] neg_lo:[0,0,1]
	s_waitcnt lgkmcnt(4)
	v_pk_add_f32 v[102:103], v[102:103], v[118:119] neg_hi:[0,1]
	v_pk_mul_f32 v[182:183], v[176:177], v[102:103] op_sel:[1,1] op_sel_hi:[0,1]
	v_pk_fma_f32 v[176:177], v[176:177], v[102:103], v[182:183] op_sel_hi:[1,0,1] neg_lo:[0,0,1]
	s_waitcnt lgkmcnt(2)
	v_pk_add_f32 v[184:185], v[184:185], v[186:187] neg_hi:[0,1]
	v_pk_mul_f32 v[180:181], v[112:113], v[184:185] op_sel:[1,1] op_sel_hi:[0,1]
	v_pk_fma_f32 v[112:113], v[112:113], v[184:185], v[180:181] op_sel_hi:[1,0,1] neg_lo:[0,0,1]
	s_waitcnt lgkmcnt(0)
	v_pk_add_f32 v[168:169], v[168:169], v[188:189] neg_hi:[0,1]
	v_pk_mul_f32 v[182:183], v[114:115], v[168:169] op_sel:[1,1] op_sel_hi:[0,1]
	v_pk_fma_f32 v[114:115], v[114:115], v[168:169], v[182:183] op_sel_hi:[1,0,1] neg_lo:[0,0,1]
	ds_read_b64 v[180:181], v200 offset:128
	ds_read_b64 v[184:185], v202 offset:120
	ds_read_b64 v[182:183], v200 offset:144
	ds_read_b64 v[168:169], v202 offset:104
	ds_read_b64 v[110:111], v200 offset:160
	ds_read_b64 v[126:127], v202 offset:88
	ds_read_b64 v[102:103], v200 offset:176
	ds_read_b64 v[118:119], v202 offset:72
	s_waitcnt lgkmcnt(6)
	v_pk_add_f32 v[180:181], v[180:181], v[184:185] neg_hi:[0,1]
	v_pk_mul_f32 v[186:187], v[116:117], v[180:181] op_sel:[1,1] op_sel_hi:[0,1]
	v_pk_fma_f32 v[116:117], v[116:117], v[180:181], v[186:187] op_sel_hi:[1,0,1] neg_lo:[0,0,1]
	s_waitcnt lgkmcnt(4)
	v_pk_add_f32 v[182:183], v[182:183], v[168:169] neg_hi:[0,1]
	v_pk_mul_f32 v[188:189], v[166:167], v[182:183] op_sel:[1,1] op_sel_hi:[0,1]
	v_pk_fma_f32 v[166:167], v[166:167], v[182:183], v[188:189] op_sel_hi:[1,0,1] neg_lo:[0,0,1]
	s_waitcnt lgkmcnt(2)
	v_pk_add_f32 v[110:111], v[110:111], v[126:127] neg_hi:[0,1]
	v_pk_mul_f32 v[186:187], v[120:121], v[110:111] op_sel:[1,1] op_sel_hi:[0,1]
	v_pk_fma_f32 v[120:121], v[120:121], v[110:111], v[186:187] op_sel_hi:[1,0,1] neg_lo:[0,0,1]
	s_waitcnt lgkmcnt(0)
	v_pk_add_f32 v[102:103], v[102:103], v[118:119] neg_hi:[0,1]
	v_pk_mul_f32 v[188:189], v[122:123], v[102:103] op_sel:[1,1] op_sel_hi:[0,1]
	v_pk_fma_f32 v[122:123], v[122:123], v[102:103], v[188:189] op_sel_hi:[1,0,1] neg_lo:[0,0,1]
	ds_read_b64 v[186:187], v200 offset:192
	ds_read_b64 v[110:111], v202 offset:56
	ds_read_b64 v[188:189], v200 offset:208
	ds_read_b64 v[102:103], v202 offset:40
	ds_read_b64 v[180:181], v200 offset:224
	ds_read_b64 v[184:185], v202 offset:24
	ds_read_b64 v[182:183], v200 offset:240
	ds_read_b64 v[168:169], v202 offset:8
	s_waitcnt lgkmcnt(6)
	v_pk_add_f32 v[186:187], v[186:187], v[110:111] neg_hi:[0,1]
	v_pk_mul_f32 v[126:127], v[124:125], v[186:187] op_sel:[1,1] op_sel_hi:[0,1]
	v_pk_fma_f32 v[124:125], v[124:125], v[186:187], v[126:127] op_sel_hi:[1,0,1] neg_lo:[0,0,1]
	s_waitcnt lgkmcnt(4)
	v_pk_add_f32 v[188:189], v[188:189], v[102:103] neg_hi:[0,1]
	v_pk_mul_f32 v[118:119], v[174:175], v[188:189] op_sel:[1,1] op_sel_hi:[0,1]
	v_pk_fma_f32 v[174:175], v[174:175], v[188:189], v[118:119] op_sel_hi:[1,0,1] neg_lo:[0,0,1]
	s_waitcnt lgkmcnt(2)
	v_pk_add_f32 v[180:181], v[180:181], v[184:185] neg_hi:[0,1]
	v_pk_mul_f32 v[126:127], v[128:129], v[180:181] op_sel:[1,1] op_sel_hi:[0,1]
	v_pk_fma_f32 v[128:129], v[128:129], v[180:181], v[126:127] op_sel_hi:[1,0,1] neg_lo:[0,0,1]
	s_waitcnt lgkmcnt(0)
	v_pk_add_f32 v[182:183], v[182:183], v[168:169] neg_hi:[0,1]
	v_pk_mul_f32 v[118:119], v[130:131], v[182:183] op_sel:[1,1] op_sel_hi:[0,1]
	v_pk_fma_f32 v[130:131], v[130:131], v[182:183], v[118:119] op_sel_hi:[1,0,1] neg_lo:[0,0,1]
	v_pk_add_f32 v[126:127], v[100:101], v[116:117]
	v_pk_add_f32 v[118:119], v[100:101], v[116:117] neg_lo:[0,1] neg_hi:[0,1]
	v_pk_add_f32 v[186:187], v[108:109], v[124:125]
	v_pk_add_f32 v[188:189], v[108:109], v[124:125] neg_lo:[0,1] neg_hi:[0,1]
	v_pk_add_f32 v[100:101], v[126:127], v[186:187]
	v_pk_add_f32 v[116:117], v[126:127], v[186:187] neg_lo:[0,1] neg_hi:[0,1]
	v_pk_add_f32 v[108:109], v[118:119], v[188:189] op_sel:[0,1] op_sel_hi:[1,0] neg_lo:[0,1]
	v_pk_add_f32 v[124:125], v[118:119], v[188:189] op_sel:[0,1] op_sel_hi:[1,0] neg_hi:[0,1]
	v_pk_add_f32 v[180:181], v[178:179], v[166:167]
	v_pk_add_f32 v[182:183], v[178:179], v[166:167] neg_lo:[0,1] neg_hi:[0,1]
	v_pk_add_f32 v[110:111], v[176:177], v[174:175]
	v_pk_add_f32 v[102:103], v[176:177], v[174:175] neg_lo:[0,1] neg_hi:[0,1]
	v_pk_add_f32 v[178:179], v[180:181], v[110:111]
	v_pk_add_f32 v[166:167], v[180:181], v[110:111] neg_lo:[0,1] neg_hi:[0,1]
	v_pk_add_f32 v[176:177], v[182:183], v[102:103] op_sel:[0,1] op_sel_hi:[1,0] neg_lo:[0,1]
	v_pk_add_f32 v[174:175], v[182:183], v[102:103] op_sel:[0,1] op_sel_hi:[1,0] neg_hi:[0,1]
	v_pk_add_f32 v[184:185], v[104:105], v[120:121]
	v_pk_add_f32 v[168:169], v[104:105], v[120:121] neg_lo:[0,1] neg_hi:[0,1]
	v_pk_add_f32 v[126:127], v[112:113], v[128:129]
	v_pk_add_f32 v[118:119], v[112:113], v[128:129] neg_lo:[0,1] neg_hi:[0,1]
	v_pk_add_f32 v[104:105], v[184:185], v[126:127]
	v_pk_add_f32 v[120:121], v[184:185], v[126:127] neg_lo:[0,1] neg_hi:[0,1]
	v_pk_add_f32 v[112:113], v[168:169], v[118:119] op_sel:[0,1] op_sel_hi:[1,0] neg_lo:[0,1]
	v_pk_add_f32 v[128:129], v[168:169], v[118:119] op_sel:[0,1] op_sel_hi:[1,0] neg_hi:[0,1]
	v_pk_add_f32 v[186:187], v[106:107], v[122:123]
	v_pk_add_f32 v[188:189], v[106:107], v[122:123] neg_lo:[0,1] neg_hi:[0,1]
	v_pk_add_f32 v[180:181], v[114:115], v[130:131]
	v_pk_add_f32 v[182:183], v[114:115], v[130:131] neg_lo:[0,1] neg_hi:[0,1]
	v_pk_add_f32 v[106:107], v[186:187], v[180:181]
; __device__ __forceinline__ f32x2 cmulc(f32x2 a, f32x2 b) { return (f32x2){a.x * b.x + a.y * b.y, a.y * b.x - a.x * b.y}; }
; template <bool INV> __device__ __forceinline__ f32x2 cmul_tw(f32x2 a, f32x2 w) { return INV ? cmulc(a, w) : cmul(a, w); }
; template <bool INV> __device__ __forceinline__ void dft16(f32x2 (&x)[16]) {
;     constexpr float C1 = 0.92387953251128674f, S1 = 0.38268343236508977f, C2 = 0.70710678118654752f;
; #pragma unroll
;     for (int b = 0; b < 4; ++b) dft4<INV>(x[b], x[4 + b], x[8 + b], x[12 + b]);
;     const f32x2 w1 = {C1, -S1}, w2 = {C2, -C2}, w3 = {S1, -C1}, w4 = {0.f, -1.f}, w6 = {-C2, -C2}, w9 = {-C1, S1};
;     x[4 * 1 + 1] = cmul_tw<INV>(x[5], w1); x[4 * 1 + 2] = cmul_tw<INV>(x[6], w2); x[4 * 1 + 3] = cmul_tw<INV>(x[7], w3);
;     x[4 * 2 + 1] = cmul_tw<INV>(x[9], w2); x[4 * 2 + 2] = cmul_tw<INV>(x[10], w4); x[4 * 2 + 3] = cmul_tw<INV>(x[11], w6);
;     x[4 * 3 + 1] = cmul_tw<INV>(x[13], w3); x[4 * 3 + 2] = cmul_tw<INV>(x[14], w6); x[4 * 3 + 3] = cmul_tw<INV>(x[15], w9);
; #pragma unroll
;     for (int c = 0; c < 4; ++c) dft4<INV>(x[4 * c], x[4 * c + 1], x[4 * c + 2], x[4 * c + 3]);
;     f32x2 y[16];
; #pragma unroll
;     for (int k = 0; k < 16; ++k) y[k] = x[4 * (k & 3) + (k >> 2)];
; #pragma unroll
;     for (int k = 0; k < 16; ++k) x[k] = y[k];
; }
; template <int MODE> __device__ __forceinline__ void fft_pair32(LAS f32x2* B, const LAS f32x2* F, int wave, int lane) {
;     ...
;     dft16<true>(v);
; #pragma unroll
;     for (int j = 0; j < 16; ++j) { const f32x2 w = {hi ? CS[j] : 1.f, hi ? -SN[j] : 0.f}; const f32x2 u = j == 0 ? v[j] : cmulc(v[j], w);
;         const auto rx = __builtin_amdgcn_permlane32_swap(__float_as_uint(u.x), __float_as_uint(u.x), false, false);
;         const auto ry = __builtin_amdgcn_permlane32_swap(__float_as_uint(u.y), __float_as_uint(u.y), false, false);
;         const f32x2 a = {__uint_as_float(rx[0]), __uint_as_float(ry[0])}, b = {__uint_as_float(rx[1]), __uint_as_float(ry[1])};
;         p[16 * hi + j] = a + b * sg; }
	v_pk_add_f32 v[122:123], v[186:187], v[180:181] neg_lo:[0,1] neg_hi:[0,1]
	v_pk_add_f32 v[114:115], v[188:189], v[182:183] op_sel:[0,1] op_sel_hi:[1,0] neg_lo:[0,1]
	v_pk_add_f32 v[130:131], v[188:189], v[182:183] op_sel:[0,1] op_sel_hi:[1,0] neg_hi:[0,1]
	v_pk_mul_f32 v[110:111], v[176:177], s[68:69] op_sel:[1,1] op_sel_hi:[0,1]
	v_pk_fma_f32 v[176:177], v[176:177], s[68:69], v[110:111] op_sel_hi:[1,0,1] neg_hi:[0,0,1]
	v_pk_mul_f32 v[102:103], v[112:113], s[84:85] op_sel:[1,1] op_sel_hi:[0,1]
	v_pk_fma_f32 v[112:113], v[112:113], s[84:85], v[102:103] op_sel_hi:[1,0,1] neg_hi:[0,0,1]
	v_pk_mul_f32 v[184:185], v[114:115], s[88:89] op_sel:[1,1] op_sel_hi:[0,1]
	v_pk_fma_f32 v[114:115], v[114:115], s[88:89], v[184:185] op_sel_hi:[1,0,1] neg_hi:[0,0,1]
	v_pk_mul_f32 v[168:169], v[166:167], s[84:85] op_sel:[1,1] op_sel_hi:[0,1]
	v_pk_fma_f32 v[166:167], v[166:167], s[84:85], v[168:169] op_sel_hi:[1,0,1] neg_hi:[0,0,1]
	v_pk_mul_f32 v[126:127], v[122:123], s[90:91] op_sel:[1,1] op_sel_hi:[0,1]
	v_pk_fma_f32 v[122:123], v[122:123], s[90:91], v[126:127] op_sel_hi:[1,0,1] neg_hi:[0,0,1]
	v_pk_mul_f32 v[118:119], v[174:175], s[88:89] op_sel:[1,1] op_sel_hi:[0,1]
	v_pk_fma_f32 v[174:175], v[174:175], s[88:89], v[118:119] op_sel_hi:[1,0,1] neg_hi:[0,0,1]
	v_pk_mul_f32 v[186:187], v[128:129], s[90:91] op_sel:[1,1] op_sel_hi:[0,1]
	v_pk_fma_f32 v[128:129], v[128:129], s[90:91], v[186:187] op_sel_hi:[1,0,1] neg_hi:[0,0,1]
	v_pk_mul_f32 v[188:189], v[130:131], s[98:99] op_sel:[1,1] op_sel_hi:[0,1]
	v_pk_fma_f32 v[130:131], v[130:131], s[98:99], v[188:189] op_sel_hi:[1,0,1] neg_hi:[0,0,1]
	v_pk_add_f32 v[180:181], v[100:101], v[104:105]
	v_pk_add_f32 v[182:183], v[100:101], v[104:105] neg_lo:[0,1] neg_hi:[0,1]
	v_pk_add_f32 v[110:111], v[178:179], v[106:107]
	v_pk_add_f32 v[102:103], v[178:179], v[106:107] neg_lo:[0,1] neg_hi:[0,1]
	v_pk_add_f32 v[100:101], v[180:181], v[110:111]
	v_pk_add_f32 v[104:105], v[180:181], v[110:111] neg_lo:[0,1] neg_hi:[0,1]
	v_pk_add_f32 v[178:179], v[182:183], v[102:103] op_sel:[0,1] op_sel_hi:[1,0] neg_lo:[0,1]
	v_pk_add_f32 v[106:107], v[182:183], v[102:103] op_sel:[0,1] op_sel_hi:[1,0] neg_hi:[0,1]
	v_pk_add_f32 v[184:185], v[108:109], v[112:113]
	v_pk_add_f32 v[168:169], v[108:109], v[112:113] neg_lo:[0,1] neg_hi:[0,1]
	v_pk_add_f32 v[126:127], v[176:177], v[114:115]
	v_pk_add_f32 v[118:119], v[176:177], v[114:115] neg_lo:[0,1] neg_hi:[0,1]
	v_pk_add_f32 v[108:109], v[184:185], v[126:127]
	v_pk_add_f32 v[112:113], v[184:185], v[126:127] neg_lo:[0,1] neg_hi:[0,1]
	v_pk_add_f32 v[176:177], v[168:169], v[118:119] op_sel:[0,1] op_sel_hi:[1,0] neg_lo:[0,1]
	v_pk_add_f32 v[114:115], v[168:169], v[118:119] op_sel:[0,1] op_sel_hi:[1,0] neg_hi:[0,1]
	v_pk_add_f32 v[186:187], v[116:117], v[120:121] op_sel:[0,1] op_sel_hi:[1,0] neg_lo:[0,1]
	v_pk_add_f32 v[188:189], v[116:117], v[120:121] op_sel:[0,1] op_sel_hi:[1,0] neg_hi:[0,1]
	v_pk_add_f32 v[180:181], v[166:167], v[122:123]
	v_pk_add_f32 v[182:183], v[166:167], v[122:123] neg_lo:[0,1] neg_hi:[0,1]
	v_pk_add_f32 v[116:117], v[186:187], v[180:181]
	v_pk_add_f32 v[120:121], v[186:187], v[180:181] neg_lo:[0,1] neg_hi:[0,1]
	v_pk_add_f32 v[166:167], v[188:189], v[182:183] op_sel:[0,1] op_sel_hi:[1,0] neg_lo:[0,1]
	v_pk_add_f32 v[122:123], v[188:189], v[182:183] op_sel:[0,1] op_sel_hi:[1,0] neg_hi:[0,1]
	v_pk_add_f32 v[110:111], v[124:125], v[128:129]
	v_pk_add_f32 v[102:103], v[124:125], v[128:129] neg_lo:[0,1] neg_hi:[0,1]
	v_pk_add_f32 v[184:185], v[174:175], v[130:131]
	v_pk_add_f32 v[168:169], v[174:175], v[130:131] neg_lo:[0,1] neg_hi:[0,1]
	v_pk_add_f32 v[124:125], v[110:111], v[184:185]
	v_pk_add_f32 v[128:129], v[110:111], v[184:185] neg_lo:[0,1] neg_hi:[0,1]
	v_pk_add_f32 v[174:175], v[102:103], v[168:169] op_sel:[0,1] op_sel_hi:[1,0] neg_lo:[0,1]
	v_pk_add_f32 v[130:131], v[102:103], v[168:169] op_sel:[0,1] op_sel_hi:[1,0] neg_hi:[0,1]
	v_mov_b32_e32 v126, v100
	v_mov_b32_e32 v127, v101
	v_pk_mul_f32 v[180:181], v[108:109], v[36:37] op_sel:[1,1] op_sel_hi:[0,1]
	v_pk_fma_f32 v[118:119], v[108:109], v[36:37], v[180:181] op_sel_hi:[1,0,1] neg_hi:[0,0,1]
	v_pk_fma_f32 v[108:109], v[108:109], v[36:37], v[180:181] op_sel_hi:[1,0,1] neg_hi:[0,0,1]
	v_pk_mul_f32 v[182:183], v[116:117], v[38:39] op_sel:[1,1] op_sel_hi:[0,1]
	v_pk_fma_f32 v[186:187], v[116:117], v[38:39], v[182:183] op_sel_hi:[1,0,1] neg_hi:[0,0,1]
	v_pk_fma_f32 v[116:117], v[116:117], v[38:39], v[182:183] op_sel_hi:[1,0,1] neg_hi:[0,0,1]
	v_pk_mul_f32 v[110:111], v[124:125], v[40:41] op_sel:[1,1] op_sel_hi:[0,1]
	v_pk_fma_f32 v[188:189], v[124:125], v[40:41], v[110:111] op_sel_hi:[1,0,1] neg_hi:[0,0,1]
	v_pk_fma_f32 v[124:125], v[124:125], v[40:41], v[110:111] op_sel_hi:[1,0,1] neg_hi:[0,0,1]
	s_nop 1
	v_permlane32_swap_b32_e32 v100, v126
	v_permlane32_swap_b32_e32 v101, v127
	v_permlane32_swap_b32_e32 v108, v118
	v_permlane32_swap_b32_e32 v109, v119
	v_permlane32_swap_b32_e32 v116, v186
	v_permlane32_swap_b32_e32 v117, v187
	v_permlane32_swap_b32_e32 v124, v188
	v_permlane32_swap_b32_e32 v125, v189
	v_pk_fma_f32 v[100:101], v[126:127], v[190:191], v[100:101] op_sel_hi:[1,0,1]
	ds_write_b64 v198, v[100:101]
	v_pk_fma_f32 v[108:109], v[118:119], v[190:191], v[108:109] op_sel_hi:[1,0,1]
	ds_write_b64 v198, v[108:109] offset:8
	v_pk_fma_f32 v[116:117], v[186:187], v[190:191], v[116:117] op_sel_hi:[1,0,1]
	ds_write_b64 v198, v[116:117] offset:16
	v_pk_fma_f32 v[124:125], v[188:189], v[190:191], v[124:125] op_sel_hi:[1,0,1]
	ds_write_b64 v198, v[124:125] offset:24
	v_pk_mul_f32 v[182:183], v[178:179], v[42:43] op_sel:[1,1] op_sel_hi:[0,1]
	v_pk_fma_f32 v[102:103], v[178:179], v[42:43], v[182:183] op_sel_hi:[1,0,1] neg_hi:[0,0,1]
; #define LAS __attribute__((address_space(3)))
; __device__ __forceinline__ f32x2 cmulc(f32x2 a, f32x2 b) { return (f32x2){a.x * b.x + a.y * b.y, a.y * b.x - a.x * b.y}; }
; __device__ __forceinline__ void fft_inv2(LAS f32x2* B, const LAS f32x2* TW2, int tid) {
;     asm volatile("" : "+v"(tid));
;     const int b = tid >> 5, n2 = tid & 31, base = 512 * b + n2; f32x2 x[16];
;     x[0] = B[fpad(base)];
; #pragma unroll
;     for (int k = 1; k < 16; ++k) x[k] = cmulc(B[fpad(base + 32 * k)], TW2[k * 32 + n2]);
;     dft16<true>(x);
; #pragma unroll
;     for (int r = 0; r < 16; ++r) B[fpad(base + 32 * r)] = x[r];
; }
; template <int MODE> __device__ __forceinline__ void fft_pair32(LAS f32x2* B, const LAS f32x2* F, int wave, int lane) {
;     ...
;     for (int j = 0; j < 16; ++j) { const f32x2 w = {hi ? CS[j] : 1.f, hi ? -SN[j] : 0.f}; const f32x2 u = j == 0 ? v[j] : cmulc(v[j], w);
;         const auto rx = __builtin_amdgcn_permlane32_swap(__float_as_uint(u.x), __float_as_uint(u.x), false, false);
;         const auto ry = __builtin_amdgcn_permlane32_swap(__float_as_uint(u.y), __float_as_uint(u.y), false, false);
;         const f32x2 a = {__uint_as_float(rx[0]), __uint_as_float(ry[0])}, b = {__uint_as_float(rx[1]), __uint_as_float(ry[1])};
;         p[16 * hi + j] = a + b * sg; }
	v_pk_fma_f32 v[178:179], v[178:179], v[42:43], v[182:183] op_sel_hi:[1,0,1] neg_hi:[0,0,1]
	v_pk_mul_f32 v[110:111], v[176:177], v[44:45] op_sel:[1,1] op_sel_hi:[0,1]
	v_pk_fma_f32 v[184:185], v[176:177], v[44:45], v[110:111] op_sel_hi:[1,0,1] neg_hi:[0,0,1]
	v_pk_fma_f32 v[176:177], v[176:177], v[44:45], v[110:111] op_sel_hi:[1,0,1] neg_hi:[0,0,1]
	v_pk_mul_f32 v[126:127], v[166:167], v[46:47] op_sel:[1,1] op_sel_hi:[0,1]
	v_pk_fma_f32 v[168:169], v[166:167], v[46:47], v[126:127] op_sel_hi:[1,0,1] neg_hi:[0,0,1]
	v_pk_fma_f32 v[166:167], v[166:167], v[46:47], v[126:127] op_sel_hi:[1,0,1] neg_hi:[0,0,1]
	v_pk_mul_f32 v[118:119], v[174:175], v[48:49] op_sel:[1,1] op_sel_hi:[0,1]
	v_pk_fma_f32 v[180:181], v[174:175], v[48:49], v[118:119] op_sel_hi:[1,0,1] neg_hi:[0,0,1]
	v_pk_fma_f32 v[174:175], v[174:175], v[48:49], v[118:119] op_sel_hi:[1,0,1] neg_hi:[0,0,1]
	s_nop 1
	v_permlane32_swap_b32_e32 v178, v102
	v_permlane32_swap_b32_e32 v179, v103
	v_permlane32_swap_b32_e32 v176, v184
	v_permlane32_swap_b32_e32 v177, v185
	v_permlane32_swap_b32_e32 v166, v168
	v_permlane32_swap_b32_e32 v167, v169
	v_permlane32_swap_b32_e32 v174, v180
	v_permlane32_swap_b32_e32 v175, v181
	v_pk_fma_f32 v[178:179], v[102:103], v[190:191], v[178:179] op_sel_hi:[1,0,1]
	ds_write_b64 v198, v[178:179] offset:32
	v_pk_fma_f32 v[176:177], v[184:185], v[190:191], v[176:177] op_sel_hi:[1,0,1]
	ds_write_b64 v198, v[176:177] offset:40
	v_pk_fma_f32 v[166:167], v[168:169], v[190:191], v[166:167] op_sel_hi:[1,0,1]
	ds_write_b64 v198, v[166:167] offset:48
	v_pk_fma_f32 v[174:175], v[180:181], v[190:191], v[174:175] op_sel_hi:[1,0,1]
	ds_write_b64 v198, v[174:175] offset:56
	v_pk_mul_f32 v[126:127], v[104:105], v[50:51] op_sel:[1,1] op_sel_hi:[0,1]
	v_pk_fma_f32 v[186:187], v[104:105], v[50:51], v[126:127] op_sel_hi:[1,0,1] neg_hi:[0,0,1]
	v_pk_fma_f32 v[104:105], v[104:105], v[50:51], v[126:127] op_sel_hi:[1,0,1] neg_hi:[0,0,1]
	v_pk_mul_f32 v[118:119], v[112:113], v[52:53] op_sel:[1,1] op_sel_hi:[0,1]
	v_pk_fma_f32 v[188:189], v[112:113], v[52:53], v[118:119] op_sel_hi:[1,0,1] neg_hi:[0,0,1]
	v_pk_fma_f32 v[112:113], v[112:113], v[52:53], v[118:119] op_sel_hi:[1,0,1] neg_hi:[0,0,1]
	v_pk_mul_f32 v[102:103], v[120:121], v[54:55] op_sel:[1,1] op_sel_hi:[0,1]
	v_pk_fma_f32 v[182:183], v[120:121], v[54:55], v[102:103] op_sel_hi:[1,0,1] neg_hi:[0,0,1]
	v_pk_fma_f32 v[120:121], v[120:121], v[54:55], v[102:103] op_sel_hi:[1,0,1] neg_hi:[0,0,1]
	v_pk_mul_f32 v[184:185], v[128:129], v[90:91] op_sel:[1,1] op_sel_hi:[0,1]
	v_pk_fma_f32 v[110:111], v[128:129], v[90:91], v[184:185] op_sel_hi:[1,0,1] neg_hi:[0,0,1]
	v_pk_fma_f32 v[128:129], v[128:129], v[90:91], v[184:185] op_sel_hi:[1,0,1] neg_hi:[0,0,1]
	s_nop 1
	v_permlane32_swap_b32_e32 v104, v186
	v_permlane32_swap_b32_e32 v105, v187
	v_permlane32_swap_b32_e32 v112, v188
	v_permlane32_swap_b32_e32 v113, v189
	v_permlane32_swap_b32_e32 v120, v182
	v_permlane32_swap_b32_e32 v121, v183
	v_permlane32_swap_b32_e32 v128, v110
	v_permlane32_swap_b32_e32 v129, v111
	v_pk_fma_f32 v[104:105], v[186:187], v[190:191], v[104:105] op_sel_hi:[1,0,1]
	ds_write_b64 v198, v[104:105] offset:64
	v_pk_fma_f32 v[112:113], v[188:189], v[190:191], v[112:113] op_sel_hi:[1,0,1]
	ds_write_b64 v198, v[112:113] offset:72
	v_pk_fma_f32 v[120:121], v[182:183], v[190:191], v[120:121] op_sel_hi:[1,0,1]
	ds_write_b64 v198, v[120:121] offset:80
	v_pk_fma_f32 v[128:129], v[110:111], v[190:191], v[128:129] op_sel_hi:[1,0,1]
	ds_write_b64 v198, v[128:129] offset:88
	v_pk_mul_f32 v[102:103], v[106:107], v[92:93] op_sel:[1,1] op_sel_hi:[0,1]
	v_pk_fma_f32 v[168:169], v[106:107], v[92:93], v[102:103] op_sel_hi:[1,0,1] neg_hi:[0,0,1]
	v_pk_fma_f32 v[106:107], v[106:107], v[92:93], v[102:103] op_sel_hi:[1,0,1] neg_hi:[0,0,1]
	v_pk_mul_f32 v[184:185], v[114:115], v[94:95] op_sel:[1,1] op_sel_hi:[0,1]
	v_pk_fma_f32 v[180:181], v[114:115], v[94:95], v[184:185] op_sel_hi:[1,0,1] neg_hi:[0,0,1]
	v_pk_fma_f32 v[114:115], v[114:115], v[94:95], v[184:185] op_sel_hi:[1,0,1] neg_hi:[0,0,1]
	v_pk_mul_f32 v[186:187], v[122:123], v[96:97] op_sel:[1,1] op_sel_hi:[0,1]
	v_pk_fma_f32 v[126:127], v[122:123], v[96:97], v[186:187] op_sel_hi:[1,0,1] neg_hi:[0,0,1]
	v_pk_fma_f32 v[122:123], v[122:123], v[96:97], v[186:187] op_sel_hi:[1,0,1] neg_hi:[0,0,1]
	v_pk_mul_f32 v[188:189], v[130:131], v[98:99] op_sel:[1,1] op_sel_hi:[0,1]
	v_pk_fma_f32 v[118:119], v[130:131], v[98:99], v[188:189] op_sel_hi:[1,0,1] neg_hi:[0,0,1]
	v_pk_fma_f32 v[130:131], v[130:131], v[98:99], v[188:189] op_sel_hi:[1,0,1] neg_hi:[0,0,1]
	s_nop 1
	v_permlane32_swap_b32_e32 v106, v168
	v_permlane32_swap_b32_e32 v107, v169
	v_permlane32_swap_b32_e32 v114, v180
	v_permlane32_swap_b32_e32 v115, v181
	v_permlane32_swap_b32_e32 v122, v126
	v_permlane32_swap_b32_e32 v123, v127
	v_permlane32_swap_b32_e32 v130, v118
	v_permlane32_swap_b32_e32 v131, v119
	v_pk_fma_f32 v[106:107], v[168:169], v[190:191], v[106:107] op_sel_hi:[1,0,1]
	ds_write_b64 v198, v[106:107] offset:96
	v_pk_fma_f32 v[114:115], v[180:181], v[190:191], v[114:115] op_sel_hi:[1,0,1]
	ds_write_b64 v198, v[114:115] offset:104
	v_pk_fma_f32 v[122:123], v[126:127], v[190:191], v[122:123] op_sel_hi:[1,0,1]
	ds_write_b64 v198, v[122:123] offset:112
	v_pk_fma_f32 v[130:131], v[118:119], v[190:191], v[130:131] op_sel_hi:[1,0,1]
	ds_write_b64 v198, v[130:131] offset:120
	s_waitcnt lgkmcnt(0)
	ds_read_b64 v[100:101], v5
	ds_read_b64 v[108:109], v5 offset:264
	ds_read_b64 v[182:183], v56 offset:256
	ds_read_b64 v[116:117], v5 offset:528
	ds_read_b64 v[110:111], v56 offset:512
	ds_read_b64 v[124:125], v5 offset:792
	ds_read_b64 v[102:103], v56 offset:768
	ds_read_b64 v[178:179], v5 offset:1056
	ds_read_b64 v[184:185], v56 offset:1024
	ds_read_b64 v[176:177], v5 offset:1320
	ds_read_b64 v[186:187], v56 offset:1280
	s_waitcnt lgkmcnt(8)
; #define LAS __attribute__((address_space(3)))
; __device__ __forceinline__ f32x2 cmulc(f32x2 a, f32x2 b) { return (f32x2){a.x * b.x + a.y * b.y, a.y * b.x - a.x * b.y}; }
; template <bool INV> __device__ __forceinline__ f32x2 cmul_tw(f32x2 a, f32x2 w) { return INV ? cmulc(a, w) : cmul(a, w); }
; template <bool INV> __device__ __forceinline__ void dft16(f32x2 (&x)[16]) {
;     constexpr float C1 = 0.92387953251128674f, S1 = 0.38268343236508977f, C2 = 0.70710678118654752f;
; #pragma unroll
;     for (int b = 0; b < 4; ++b) dft4<INV>(x[b], x[4 + b], x[8 + b], x[12 + b]);
;     const f32x2 w1 = {C1, -S1}, w2 = {C2, -C2}, w3 = {S1, -C1}, w4 = {0.f, -1.f}, w6 = {-C2, -C2}, w9 = {-C1, S1};
;     x[4 * 1 + 1] = cmul_tw<INV>(x[5], w1); x[4 * 1 + 2] = cmul_tw<INV>(x[6], w2); x[4 * 1 + 3] = cmul_tw<INV>(x[7], w3);
;     x[4 * 2 + 1] = cmul_tw<INV>(x[9], w2); x[4 * 2 + 2] = cmul_tw<INV>(x[10], w4); x[4 * 2 + 3] = cmul_tw<INV>(x[11], w6);
;     x[4 * 3 + 1] = cmul_tw<INV>(x[13], w3); x[4 * 3 + 2] = cmul_tw<INV>(x[14], w6); x[4 * 3 + 3] = cmul_tw<INV>(x[15], w9);
; #pragma unroll
;     for (int c = 0; c < 4; ++c) dft4<INV>(x[4 * c], x[4 * c + 1], x[4 * c + 2], x[4 * c + 3]);
;     f32x2 y[16];
; #pragma unroll
;     for (int k = 0; k < 16; ++k) y[k] = x[4 * (k & 3) + (k >> 2)];
; #pragma unroll
;     for (int k = 0; k < 16; ++k) x[k] = y[k];
; }
; __device__ __forceinline__ void fft_inv2(LAS f32x2* B, const LAS f32x2* TW2, int tid) {
;     asm volatile("" : "+v"(tid));
;     const int b = tid >> 5, n2 = tid & 31, base = 512 * b + n2; f32x2 x[16];
;     x[0] = B[fpad(base)];
; #pragma unroll
;     for (int k = 1; k < 16; ++k) x[k] = cmulc(B[fpad(base + 32 * k)], TW2[k * 32 + n2]);
;     dft16<true>(x);
; #pragma unroll
;     for (int r = 0; r < 16; ++r) B[fpad(base + 32 * r)] = x[r];
; }
	v_pk_mul_f32 v[188:189], v[108:109], v[182:183] op_sel:[1,1] op_sel_hi:[0,1]
	v_pk_fma_f32 v[108:109], v[108:109], v[182:183], v[188:189] op_sel_hi:[1,0,1] neg_hi:[0,0,1]
	s_waitcnt lgkmcnt(6)
	v_pk_mul_f32 v[168:169], v[116:117], v[110:111] op_sel:[1,1] op_sel_hi:[0,1]
	v_pk_fma_f32 v[116:117], v[116:117], v[110:111], v[168:169] op_sel_hi:[1,0,1] neg_hi:[0,0,1]
	s_waitcnt lgkmcnt(4)
	v_pk_mul_f32 v[180:181], v[124:125], v[102:103] op_sel:[1,1] op_sel_hi:[0,1]
	v_pk_fma_f32 v[124:125], v[124:125], v[102:103], v[180:181] op_sel_hi:[1,0,1] neg_hi:[0,0,1]
	s_waitcnt lgkmcnt(2)
	v_pk_mul_f32 v[126:127], v[178:179], v[184:185] op_sel:[1,1] op_sel_hi:[0,1]
	v_pk_fma_f32 v[178:179], v[178:179], v[184:185], v[126:127] op_sel_hi:[1,0,1] neg_hi:[0,0,1]
	s_waitcnt lgkmcnt(0)
	v_pk_mul_f32 v[118:119], v[176:177], v[186:187] op_sel:[1,1] op_sel_hi:[0,1]
	v_pk_fma_f32 v[176:177], v[176:177], v[186:187], v[118:119] op_sel_hi:[1,0,1] neg_hi:[0,0,1]
	ds_read_b64 v[166:167], v5 offset:1584
	ds_read_b64 v[188:189], v56 offset:1536
	ds_read_b64 v[174:175], v5 offset:1848
	ds_read_b64 v[168:169], v56 offset:1792
	ds_read_b64 v[104:105], v5 offset:2112
	ds_read_b64 v[180:181], v56 offset:2048
	ds_read_b64 v[112:113], v5 offset:2376
	ds_read_b64 v[126:127], v56 offset:2304
	ds_read_b64 v[120:121], v5 offset:2640
	ds_read_b64 v[118:119], v56 offset:2560
	s_waitcnt lgkmcnt(8)
	v_pk_mul_f32 v[182:183], v[166:167], v[188:189] op_sel:[1,1] op_sel_hi:[0,1]
	v_pk_fma_f32 v[166:167], v[166:167], v[188:189], v[182:183] op_sel_hi:[1,0,1] neg_hi:[0,0,1]
	s_waitcnt lgkmcnt(6)
	v_pk_mul_f32 v[110:111], v[174:175], v[168:169] op_sel:[1,1] op_sel_hi:[0,1]
	v_pk_fma_f32 v[174:175], v[174:175], v[168:169], v[110:111] op_sel_hi:[1,0,1] neg_hi:[0,0,1]
	s_waitcnt lgkmcnt(4)
	v_pk_mul_f32 v[102:103], v[104:105], v[180:181] op_sel:[1,1] op_sel_hi:[0,1]
	v_pk_fma_f32 v[104:105], v[104:105], v[180:181], v[102:103] op_sel_hi:[1,0,1] neg_hi:[0,0,1]
	s_waitcnt lgkmcnt(2)
	v_pk_mul_f32 v[184:185], v[112:113], v[126:127] op_sel:[1,1] op_sel_hi:[0,1]
	v_pk_fma_f32 v[112:113], v[112:113], v[126:127], v[184:185] op_sel_hi:[1,0,1] neg_hi:[0,0,1]
	s_waitcnt lgkmcnt(0)
	v_pk_mul_f32 v[186:187], v[120:121], v[118:119] op_sel:[1,1] op_sel_hi:[0,1]
	v_pk_fma_f32 v[120:121], v[120:121], v[118:119], v[186:187] op_sel_hi:[1,0,1] neg_hi:[0,0,1]
	ds_read_b64 v[128:129], v5 offset:2904
	ds_read_b64 v[182:183], v56 offset:2816
	ds_read_b64 v[106:107], v5 offset:3168
	ds_read_b64 v[110:111], v56 offset:3072
	ds_read_b64 v[114:115], v5 offset:3432
	ds_read_b64 v[102:103], v56 offset:3328
	ds_read_b64 v[122:123], v5 offset:3696
	ds_read_b64 v[184:185], v56 offset:3584
	ds_read_b64 v[130:131], v5 offset:3960
	ds_read_b64 v[186:187], v56 offset:3840
	s_waitcnt lgkmcnt(8)
	v_pk_mul_f32 v[188:189], v[128:129], v[182:183] op_sel:[1,1] op_sel_hi:[0,1]
	v_pk_fma_f32 v[128:129], v[128:129], v[182:183], v[188:189] op_sel_hi:[1,0,1] neg_hi:[0,0,1]
	s_waitcnt lgkmcnt(6)
	v_pk_mul_f32 v[168:169], v[106:107], v[110:111] op_sel:[1,1] op_sel_hi:[0,1]
	v_pk_fma_f32 v[106:107], v[106:107], v[110:111], v[168:169] op_sel_hi:[1,0,1] neg_hi:[0,0,1]
	s_waitcnt lgkmcnt(4)
	v_pk_mul_f32 v[180:181], v[114:115], v[102:103] op_sel:[1,1] op_sel_hi:[0,1]
	v_pk_fma_f32 v[114:115], v[114:115], v[102:103], v[180:181] op_sel_hi:[1,0,1] neg_hi:[0,0,1]
	s_waitcnt lgkmcnt(2)
	v_pk_mul_f32 v[126:127], v[122:123], v[184:185] op_sel:[1,1] op_sel_hi:[0,1]
	v_pk_fma_f32 v[122:123], v[122:123], v[184:185], v[126:127] op_sel_hi:[1,0,1] neg_hi:[0,0,1]
	s_waitcnt lgkmcnt(0)
	v_pk_mul_f32 v[118:119], v[130:131], v[186:187] op_sel:[1,1] op_sel_hi:[0,1]
	v_pk_fma_f32 v[130:131], v[130:131], v[186:187], v[118:119] op_sel_hi:[1,0,1] neg_hi:[0,0,1]
	v_pk_add_f32 v[188:189], v[100:101], v[104:105]
	v_pk_add_f32 v[168:169], v[100:101], v[104:105] neg_lo:[0,1] neg_hi:[0,1]
	v_pk_add_f32 v[180:181], v[178:179], v[106:107]
	v_pk_add_f32 v[126:127], v[178:179], v[106:107] neg_lo:[0,1] neg_hi:[0,1]
	v_pk_add_f32 v[100:101], v[188:189], v[180:181]
	v_pk_add_f32 v[104:105], v[188:189], v[180:181] neg_lo:[0,1] neg_hi:[0,1]
	v_pk_add_f32 v[178:179], v[168:169], v[126:127] op_sel:[0,1] op_sel_hi:[1,0] neg_lo:[0,1]
	v_pk_add_f32 v[106:107], v[168:169], v[126:127] op_sel:[0,1] op_sel_hi:[1,0] neg_hi:[0,1]
	v_pk_add_f32 v[118:119], v[108:109], v[112:113]
	v_pk_add_f32 v[182:183], v[108:109], v[112:113] neg_lo:[0,1] neg_hi:[0,1]
	v_pk_add_f32 v[110:111], v[176:177], v[114:115]
	v_pk_add_f32 v[102:103], v[176:177], v[114:115] neg_lo:[0,1] neg_hi:[0,1]
	v_pk_add_f32 v[108:109], v[118:119], v[110:111]
	v_pk_add_f32 v[112:113], v[118:119], v[110:111] neg_lo:[0,1] neg_hi:[0,1]
	v_pk_add_f32 v[176:177], v[182:183], v[102:103] op_sel:[0,1] op_sel_hi:[1,0] neg_lo:[0,1]
	v_pk_add_f32 v[114:115], v[182:183], v[102:103] op_sel:[0,1] op_sel_hi:[1,0] neg_hi:[0,1]
	v_pk_add_f32 v[184:185], v[116:117], v[120:121]
	v_pk_add_f32 v[186:187], v[116:117], v[120:121] neg_lo:[0,1] neg_hi:[0,1]
	v_pk_add_f32 v[188:189], v[166:167], v[122:123]
	v_pk_add_f32 v[168:169], v[166:167], v[122:123] neg_lo:[0,1] neg_hi:[0,1]
	v_pk_add_f32 v[116:117], v[184:185], v[188:189]
	v_pk_add_f32 v[120:121], v[184:185], v[188:189] neg_lo:[0,1] neg_hi:[0,1]
	v_pk_add_f32 v[166:167], v[186:187], v[168:169] op_sel:[0,1] op_sel_hi:[1,0] neg_lo:[0,1]
	v_pk_add_f32 v[122:123], v[186:187], v[168:169] op_sel:[0,1] op_sel_hi:[1,0] neg_hi:[0,1]
	v_pk_add_f32 v[180:181], v[124:125], v[128:129]
	v_pk_add_f32 v[126:127], v[124:125], v[128:129] neg_lo:[0,1] neg_hi:[0,1]
	v_pk_add_f32 v[118:119], v[174:175], v[130:131]
	v_pk_add_f32 v[182:183], v[174:175], v[130:131] neg_lo:[0,1] neg_hi:[0,1]
	v_pk_add_f32 v[124:125], v[180:181], v[118:119]
; #define LAS __attribute__((address_space(3)))
; __device__ __forceinline__ f32x2 cmulc(f32x2 a, f32x2 b) { return (f32x2){a.x * b.x + a.y * b.y, a.y * b.x - a.x * b.y}; }
; template <bool INV> __device__ __forceinline__ f32x2 cmul_tw(f32x2 a, f32x2 w) { return INV ? cmulc(a, w) : cmul(a, w); }
; template <bool INV> __device__ __forceinline__ void dft16(f32x2 (&x)[16]) {
;     constexpr float C1 = 0.92387953251128674f, S1 = 0.38268343236508977f, C2 = 0.70710678118654752f;
; #pragma unroll
;     for (int b = 0; b < 4; ++b) dft4<INV>(x[b], x[4 + b], x[8 + b], x[12 + b]);
;     const f32x2 w1 = {C1, -S1}, w2 = {C2, -C2}, w3 = {S1, -C1}, w4 = {0.f, -1.f}, w6 = {-C2, -C2}, w9 = {-C1, S1};
;     x[4 * 1 + 1] = cmul_tw<INV>(x[5], w1); x[4 * 1 + 2] = cmul_tw<INV>(x[6], w2); x[4 * 1 + 3] = cmul_tw<INV>(x[7], w3);
;     x[4 * 2 + 1] = cmul_tw<INV>(x[9], w2); x[4 * 2 + 2] = cmul_tw<INV>(x[10], w4); x[4 * 2 + 3] = cmul_tw<INV>(x[11], w6);
;     x[4 * 3 + 1] = cmul_tw<INV>(x[13], w3); x[4 * 3 + 2] = cmul_tw<INV>(x[14], w6); x[4 * 3 + 3] = cmul_tw<INV>(x[15], w9);
; #pragma unroll
;     for (int c = 0; c < 4; ++c) dft4<INV>(x[4 * c], x[4 * c + 1], x[4 * c + 2], x[4 * c + 3]);
;     f32x2 y[16];
; #pragma unroll
;     for (int k = 0; k < 16; ++k) y[k] = x[4 * (k & 3) + (k >> 2)];
; #pragma unroll
;     for (int k = 0; k < 16; ++k) x[k] = y[k];
; }
; __device__ __forceinline__ void fft_inv2(LAS f32x2* B, const LAS f32x2* TW2, int tid) {
;     asm volatile("" : "+v"(tid));
;     const int b = tid >> 5, n2 = tid & 31, base = 512 * b + n2; f32x2 x[16];
;     x[0] = B[fpad(base)];
; #pragma unroll
;     for (int k = 1; k < 16; ++k) x[k] = cmulc(B[fpad(base + 32 * k)], TW2[k * 32 + n2]);
;     dft16<true>(x);
; #pragma unroll
;     for (int r = 0; r < 16; ++r) B[fpad(base + 32 * r)] = x[r];
; }
	v_pk_add_f32 v[128:129], v[180:181], v[118:119] neg_lo:[0,1] neg_hi:[0,1]
	v_pk_add_f32 v[174:175], v[126:127], v[182:183] op_sel:[0,1] op_sel_hi:[1,0] neg_lo:[0,1]
	v_pk_add_f32 v[130:131], v[126:127], v[182:183] op_sel:[0,1] op_sel_hi:[1,0] neg_hi:[0,1]
	v_pk_mul_f32 v[110:111], v[176:177], s[68:69] op_sel:[1,1] op_sel_hi:[0,1]
	v_pk_fma_f32 v[176:177], v[176:177], s[68:69], v[110:111] op_sel_hi:[1,0,1] neg_hi:[0,0,1]
	v_pk_mul_f32 v[102:103], v[166:167], s[84:85] op_sel:[1,1] op_sel_hi:[0,1]
	v_pk_fma_f32 v[166:167], v[166:167], s[84:85], v[102:103] op_sel_hi:[1,0,1] neg_hi:[0,0,1]
	v_pk_mul_f32 v[184:185], v[174:175], s[88:89] op_sel:[1,1] op_sel_hi:[0,1]
	v_pk_fma_f32 v[174:175], v[174:175], s[88:89], v[184:185] op_sel_hi:[1,0,1] neg_hi:[0,0,1]
	v_pk_mul_f32 v[186:187], v[112:113], s[84:85] op_sel:[1,1] op_sel_hi:[0,1]
	v_pk_fma_f32 v[112:113], v[112:113], s[84:85], v[186:187] op_sel_hi:[1,0,1] neg_hi:[0,0,1]
	v_pk_mul_f32 v[188:189], v[128:129], s[90:91] op_sel:[1,1] op_sel_hi:[0,1]
	v_pk_fma_f32 v[128:129], v[128:129], s[90:91], v[188:189] op_sel_hi:[1,0,1] neg_hi:[0,0,1]
	v_pk_mul_f32 v[168:169], v[114:115], s[88:89] op_sel:[1,1] op_sel_hi:[0,1]
	v_pk_fma_f32 v[114:115], v[114:115], s[88:89], v[168:169] op_sel_hi:[1,0,1] neg_hi:[0,0,1]
	v_pk_mul_f32 v[180:181], v[122:123], s[90:91] op_sel:[1,1] op_sel_hi:[0,1]
	v_pk_fma_f32 v[122:123], v[122:123], s[90:91], v[180:181] op_sel_hi:[1,0,1] neg_hi:[0,0,1]
	v_pk_mul_f32 v[126:127], v[130:131], s[98:99] op_sel:[1,1] op_sel_hi:[0,1]
	v_pk_fma_f32 v[130:131], v[130:131], s[98:99], v[126:127] op_sel_hi:[1,0,1] neg_hi:[0,0,1]
	v_pk_add_f32 v[118:119], v[100:101], v[116:117]
	v_pk_add_f32 v[182:183], v[100:101], v[116:117] neg_lo:[0,1] neg_hi:[0,1]
	v_pk_add_f32 v[110:111], v[108:109], v[124:125]
	v_pk_add_f32 v[102:103], v[108:109], v[124:125] neg_lo:[0,1] neg_hi:[0,1]
	v_pk_add_f32 v[100:101], v[118:119], v[110:111]
	v_pk_add_f32 v[116:117], v[118:119], v[110:111] neg_lo:[0,1] neg_hi:[0,1]
	v_pk_add_f32 v[108:109], v[182:183], v[102:103] op_sel:[0,1] op_sel_hi:[1,0] neg_lo:[0,1]
	v_pk_add_f32 v[124:125], v[182:183], v[102:103] op_sel:[0,1] op_sel_hi:[1,0] neg_hi:[0,1]
	v_pk_add_f32 v[184:185], v[178:179], v[166:167]
	v_pk_add_f32 v[186:187], v[178:179], v[166:167] neg_lo:[0,1] neg_hi:[0,1]
	v_pk_add_f32 v[188:189], v[176:177], v[174:175]
	v_pk_add_f32 v[168:169], v[176:177], v[174:175] neg_lo:[0,1] neg_hi:[0,1]
	v_pk_add_f32 v[178:179], v[184:185], v[188:189]
	v_pk_add_f32 v[166:167], v[184:185], v[188:189] neg_lo:[0,1] neg_hi:[0,1]
	v_pk_add_f32 v[176:177], v[186:187], v[168:169] op_sel:[0,1] op_sel_hi:[1,0] neg_lo:[0,1]
	v_pk_add_f32 v[174:175], v[186:187], v[168:169] op_sel:[0,1] op_sel_hi:[1,0] neg_hi:[0,1]
	v_pk_add_f32 v[180:181], v[104:105], v[120:121] op_sel:[0,1] op_sel_hi:[1,0] neg_lo:[0,1]
	v_pk_add_f32 v[126:127], v[104:105], v[120:121] op_sel:[0,1] op_sel_hi:[1,0] neg_hi:[0,1]
	v_pk_add_f32 v[118:119], v[112:113], v[128:129]
	v_pk_add_f32 v[182:183], v[112:113], v[128:129] neg_lo:[0,1] neg_hi:[0,1]
	v_pk_add_f32 v[104:105], v[180:181], v[118:119]
	v_pk_add_f32 v[120:121], v[180:181], v[118:119] neg_lo:[0,1] neg_hi:[0,1]
	v_pk_add_f32 v[112:113], v[126:127], v[182:183] op_sel:[0,1] op_sel_hi:[1,0] neg_lo:[0,1]
	v_pk_add_f32 v[128:129], v[126:127], v[182:183] op_sel:[0,1] op_sel_hi:[1,0] neg_hi:[0,1]
	v_pk_add_f32 v[110:111], v[106:107], v[122:123]
	v_pk_add_f32 v[102:103], v[106:107], v[122:123] neg_lo:[0,1] neg_hi:[0,1]
	v_pk_add_f32 v[184:185], v[114:115], v[130:131]
	v_pk_add_f32 v[186:187], v[114:115], v[130:131] neg_lo:[0,1] neg_hi:[0,1]
	v_pk_add_f32 v[106:107], v[110:111], v[184:185]
	v_pk_add_f32 v[122:123], v[110:111], v[184:185] neg_lo:[0,1] neg_hi:[0,1]
	v_pk_add_f32 v[114:115], v[102:103], v[186:187] op_sel:[0,1] op_sel_hi:[1,0] neg_lo:[0,1]
	v_pk_add_f32 v[130:131], v[102:103], v[186:187] op_sel:[0,1] op_sel_hi:[1,0] neg_hi:[0,1]
	ds_write_b64 v5, v[100:101]
	ds_write_b64 v5, v[178:179] offset:264
	ds_write_b64 v5, v[104:105] offset:528
	ds_write_b64 v5, v[106:107] offset:792
	ds_write_b64 v5, v[108:109] offset:1056
	ds_write_b64 v5, v[176:177] offset:1320
	ds_write_b64 v5, v[112:113] offset:1584
	ds_write_b64 v5, v[114:115] offset:1848
	ds_write_b64 v5, v[116:117] offset:2112
	ds_write_b64 v5, v[166:167] offset:2376
	ds_write_b64 v5, v[120:121] offset:2640
	ds_write_b64 v5, v[122:123] offset:2904
	ds_write_b64 v5, v[124:125] offset:3168
	ds_write_b64 v5, v[174:175] offset:3432
	ds_write_b64 v5, v[128:129] offset:3696
	ds_write_b64 v5, v[130:131] offset:3960
	s_waitcnt lgkmcnt(0)
	s_barrier
; #define LAS __attribute__((address_space(3)))
; __device__ __forceinline__ f32x2 cmulc(f32x2 a, f32x2 b) { return (f32x2){a.x * b.x + a.y * b.y, a.y * b.x - a.x * b.y}; }
; __device__ __forceinline__ void dft16_inv_lo(f32x2 (&x)[16]) {
;     constexpr float C1 = 0.92387953251128674f, S1 = 0.38268343236508977f, C2 = 0.70710678118654752f;
; #pragma unroll
;     for (int b = 0; b < 4; ++b) dft4<true>(x[b], x[4 + b], x[8 + b], x[12 + b]);
;     const f32x2 w1 = {C1, -S1}, w2 = {C2, -C2}, w3 = {S1, -C1}, w4 = {0.f, -1.f}, w6 = {-C2, -C2}, w9 = {-C1, S1};
;     x[5] = cmulc(x[5], w1); x[6] = cmulc(x[6], w2); x[7] = cmulc(x[7], w3);
;     x[9] = cmulc(x[9], w2); x[10] = cmulc(x[10], w4); x[11] = cmulc(x[11], w6);
;     x[13] = cmulc(x[13], w3); x[14] = cmulc(x[14], w6); x[15] = cmulc(x[15], w9);
;     f32x2 y[8];
; #pragma unroll
;     for (int c = 0; c < 4; ++c) { const f32x2 t0 = x[4 * c] + x[4 * c + 2], t1 = x[4 * c] - x[4 * c + 2], t2 = x[4 * c + 1] + x[4 * c + 3], t3 = x[4 * c + 1] - x[4 * c + 3];
;         y[c] = t0 + t2; y[4 + c] = t1 + (f32x2){-t3.y, t3.x}; }
; #pragma unroll
;     for (int k = 0; k < 8; ++k) x[k] = y[k];
; }
; __device__ __forceinline__ void fft_inv1(f32x2 (&x)[16], const LAS f32x2* B, int n2, const f32x2 (&w)[16]) {
;     asm volatile("" : "+v"(n2));
;     x[0] = B[fpad(n2)];
; #pragma unroll
;     for (int k = 1; k < 16; ++k) x[k] = cmulc(B[fpad(512 * k + n2)], w[k]);
;     dft16_inv_lo(x);
; }
	ds_read_b64 v[100:101], v3
	ds_read_b64 v[108:109], v3 offset:16896
	ds_read_b64 v[116:117], v3 offset:33792
	ds_read_b64 v[124:125], v3 offset:50688
	ds_read_b64 v[178:179], v3 offset:4224
	ds_read_b64 v[176:177], v3 offset:21120
	ds_read_b64 v[166:167], v3 offset:38016
	ds_read_b64 v[174:175], v3 offset:54912
	ds_read_b64 v[104:105], v3 offset:8448
	ds_read_b64 v[112:113], v3 offset:25344
	ds_read_b64 v[120:121], v3 offset:42240
	ds_read_b64 v[128:129], v3 offset:59136
	ds_read_b64 v[106:107], v3 offset:12672
	ds_read_b64 v[114:115], v3 offset:29568
	ds_read_b64 v[122:123], v3 offset:46464
	ds_read_b64 v[130:131], v3 offset:63360
	s_waitcnt lgkmcnt(14)
	v_pk_mul_f32 v[188:189], v[108:109], v[12:13] op_sel:[1,1] op_sel_hi:[0,1]
	v_pk_fma_f32 v[108:109], v[108:109], v[12:13], v[188:189] op_sel_hi:[1,0,1] neg_hi:[0,0,1]
	s_waitcnt lgkmcnt(13)
	v_pk_mul_f32 v[168:169], v[116:117], v[20:21] op_sel:[1,1] op_sel_hi:[0,1]
	v_pk_fma_f32 v[116:117], v[116:117], v[20:21], v[168:169] op_sel_hi:[1,0,1] neg_hi:[0,0,1]
	s_waitcnt lgkmcnt(12)
	v_pk_mul_f32 v[180:181], v[124:125], v[28:29] op_sel:[1,1] op_sel_hi:[0,1]
	v_pk_fma_f32 v[124:125], v[124:125], v[28:29], v[180:181] op_sel_hi:[1,0,1] neg_hi:[0,0,1]
	s_waitcnt lgkmcnt(11)
	v_pk_mul_f32 v[126:127], v[178:179], v[6:7] op_sel:[1,1] op_sel_hi:[0,1]
	v_pk_fma_f32 v[178:179], v[178:179], v[6:7], v[126:127] op_sel_hi:[1,0,1] neg_hi:[0,0,1]
	s_waitcnt lgkmcnt(10)
	v_pk_mul_f32 v[118:119], v[176:177], v[14:15] op_sel:[1,1] op_sel_hi:[0,1]
	v_pk_fma_f32 v[176:177], v[176:177], v[14:15], v[118:119] op_sel_hi:[1,0,1] neg_hi:[0,0,1]
	s_waitcnt lgkmcnt(9)
	v_pk_mul_f32 v[182:183], v[166:167], v[22:23] op_sel:[1,1] op_sel_hi:[0,1]
	v_pk_fma_f32 v[166:167], v[166:167], v[22:23], v[182:183] op_sel_hi:[1,0,1] neg_hi:[0,0,1]
	s_waitcnt lgkmcnt(8)
	v_pk_mul_f32 v[110:111], v[174:175], v[30:31] op_sel:[1,1] op_sel_hi:[0,1]
	v_pk_fma_f32 v[174:175], v[174:175], v[30:31], v[110:111] op_sel_hi:[1,0,1] neg_hi:[0,0,1]
	s_waitcnt lgkmcnt(7)
	v_pk_mul_f32 v[102:103], v[104:105], v[8:9] op_sel:[1,1] op_sel_hi:[0,1]
	v_pk_fma_f32 v[104:105], v[104:105], v[8:9], v[102:103] op_sel_hi:[1,0,1] neg_hi:[0,0,1]
	s_waitcnt lgkmcnt(6)
	v_pk_mul_f32 v[184:185], v[112:113], v[16:17] op_sel:[1,1] op_sel_hi:[0,1]
	v_pk_fma_f32 v[112:113], v[112:113], v[16:17], v[184:185] op_sel_hi:[1,0,1] neg_hi:[0,0,1]
	s_waitcnt lgkmcnt(5)
	v_pk_mul_f32 v[186:187], v[120:121], v[24:25] op_sel:[1,1] op_sel_hi:[0,1]
	v_pk_fma_f32 v[120:121], v[120:121], v[24:25], v[186:187] op_sel_hi:[1,0,1] neg_hi:[0,0,1]
	s_waitcnt lgkmcnt(4)
	v_pk_mul_f32 v[188:189], v[128:129], v[32:33] op_sel:[1,1] op_sel_hi:[0,1]
	v_pk_fma_f32 v[128:129], v[128:129], v[32:33], v[188:189] op_sel_hi:[1,0,1] neg_hi:[0,0,1]
	s_waitcnt lgkmcnt(3)
	v_pk_mul_f32 v[168:169], v[106:107], v[10:11] op_sel:[1,1] op_sel_hi:[0,1]
	v_pk_fma_f32 v[106:107], v[106:107], v[10:11], v[168:169] op_sel_hi:[1,0,1] neg_hi:[0,0,1]
	s_waitcnt lgkmcnt(2)
	v_pk_mul_f32 v[180:181], v[114:115], v[18:19] op_sel:[1,1] op_sel_hi:[0,1]
	v_pk_fma_f32 v[114:115], v[114:115], v[18:19], v[180:181] op_sel_hi:[1,0,1] neg_hi:[0,0,1]
	s_waitcnt lgkmcnt(1)
	v_pk_mul_f32 v[126:127], v[122:123], v[26:27] op_sel:[1,1] op_sel_hi:[0,1]
	v_pk_fma_f32 v[122:123], v[122:123], v[26:27], v[126:127] op_sel_hi:[1,0,1] neg_hi:[0,0,1]
	s_waitcnt lgkmcnt(0)
	v_pk_mul_f32 v[118:119], v[130:131], v[34:35] op_sel:[1,1] op_sel_hi:[0,1]
	v_pk_fma_f32 v[130:131], v[130:131], v[34:35], v[118:119] op_sel_hi:[1,0,1] neg_hi:[0,0,1]
	v_pk_add_f32 v[182:183], v[100:101], v[116:117]
	v_pk_add_f32 v[110:111], v[100:101], v[116:117] neg_lo:[0,1] neg_hi:[0,1]
	v_pk_add_f32 v[102:103], v[108:109], v[124:125]
	v_pk_add_f32 v[184:185], v[108:109], v[124:125] neg_lo:[0,1] neg_hi:[0,1]
	v_pk_add_f32 v[100:101], v[182:183], v[102:103]
	v_pk_add_f32 v[116:117], v[182:183], v[102:103] neg_lo:[0,1] neg_hi:[0,1]
	v_pk_add_f32 v[108:109], v[110:111], v[184:185] op_sel:[0,1] op_sel_hi:[1,0] neg_lo:[0,1]
	v_pk_add_f32 v[124:125], v[110:111], v[184:185] op_sel:[0,1] op_sel_hi:[1,0] neg_hi:[0,1]
	v_pk_add_f32 v[186:187], v[178:179], v[166:167]
	v_pk_add_f32 v[188:189], v[178:179], v[166:167] neg_lo:[0,1] neg_hi:[0,1]
	v_pk_add_f32 v[168:169], v[176:177], v[174:175]
	v_pk_add_f32 v[180:181], v[176:177], v[174:175] neg_lo:[0,1] neg_hi:[0,1]
	v_pk_add_f32 v[178:179], v[186:187], v[168:169]
	v_pk_add_f32 v[166:167], v[186:187], v[168:169] neg_lo:[0,1] neg_hi:[0,1]
	v_pk_add_f32 v[176:177], v[188:189], v[180:181] op_sel:[0,1] op_sel_hi:[1,0] neg_lo:[0,1]
	v_pk_add_f32 v[174:175], v[188:189], v[180:181] op_sel:[0,1] op_sel_hi:[1,0] neg_hi:[0,1]
	v_pk_add_f32 v[126:127], v[104:105], v[120:121]
	v_pk_add_f32 v[118:119], v[104:105], v[120:121] neg_lo:[0,1] neg_hi:[0,1]
	v_pk_add_f32 v[182:183], v[112:113], v[128:129]
	v_pk_add_f32 v[110:111], v[112:113], v[128:129] neg_lo:[0,1] neg_hi:[0,1]
	v_pk_add_f32 v[104:105], v[126:127], v[182:183]
	v_pk_add_f32 v[120:121], v[126:127], v[182:183] neg_lo:[0,1] neg_hi:[0,1]
	v_pk_add_f32 v[112:113], v[118:119], v[110:111] op_sel:[0,1] op_sel_hi:[1,0] neg_lo:[0,1]
	v_pk_add_f32 v[128:129], v[118:119], v[110:111] op_sel:[0,1] op_sel_hi:[1,0] neg_hi:[0,1]
	v_pk_add_f32 v[102:103], v[106:107], v[122:123]
	v_pk_add_f32 v[184:185], v[106:107], v[122:123] neg_lo:[0,1] neg_hi:[0,1]
	v_pk_add_f32 v[186:187], v[114:115], v[130:131]
	v_pk_add_f32 v[188:189], v[114:115], v[130:131] neg_lo:[0,1] neg_hi:[0,1]
	v_pk_add_f32 v[106:107], v[102:103], v[186:187]
	v_pk_add_f32 v[122:123], v[102:103], v[186:187] neg_lo:[0,1] neg_hi:[0,1]
	v_pk_add_f32 v[114:115], v[184:185], v[188:189] op_sel:[0,1] op_sel_hi:[1,0] neg_lo:[0,1]
; #define LAS __attribute__((address_space(3)))
; __device__ __forceinline__ f32x2 cmulc(f32x2 a, f32x2 b) { return (f32x2){a.x * b.x + a.y * b.y, a.y * b.x - a.x * b.y}; }
; __device__ __forceinline__ void dft16_inv_lo(f32x2 (&x)[16]) {
;     constexpr float C1 = 0.92387953251128674f, S1 = 0.38268343236508977f, C2 = 0.70710678118654752f;
; #pragma unroll
;     for (int b = 0; b < 4; ++b) dft4<true>(x[b], x[4 + b], x[8 + b], x[12 + b]);
;     const f32x2 w1 = {C1, -S1}, w2 = {C2, -C2}, w3 = {S1, -C1}, w4 = {0.f, -1.f}, w6 = {-C2, -C2}, w9 = {-C1, S1};
;     x[5] = cmulc(x[5], w1); x[6] = cmulc(x[6], w2); x[7] = cmulc(x[7], w3);
;     x[9] = cmulc(x[9], w2); x[10] = cmulc(x[10], w4); x[11] = cmulc(x[11], w6);
;     x[13] = cmulc(x[13], w3); x[14] = cmulc(x[14], w6); x[15] = cmulc(x[15], w9);
;     f32x2 y[8];
; #pragma unroll
;     for (int c = 0; c < 4; ++c) { const f32x2 t0 = x[4 * c] + x[4 * c + 2], t1 = x[4 * c] - x[4 * c + 2], t2 = x[4 * c + 1] + x[4 * c + 3], t3 = x[4 * c + 1] - x[4 * c + 3];
;         y[c] = t0 + t2; y[4 + c] = t1 + (f32x2){-t3.y, t3.x}; }
; #pragma unroll
;     for (int k = 0; k < 8; ++k) x[k] = y[k];
; }
; __device__ __forceinline__ void hy_stage(LAS float* plane, const bf16_t* PHY, int cg, int jc, int tid) {
;     asm volatile("" : "+v"(tid));
;     const u32x4* src = (const u32x4*)(PHY + (size_t)cg * MT * 4);
; #pragma unroll
;     for (int k = 0; k < 8; ++k) { const int i = tid + 512 * k; const u32x4 v = src[i];
;         const unsigned w0 = (jc & 2) ? v.y : v.x, w1 = (jc & 2) ? v.w : v.z;
;         f32x2 o; o.x = (jc & 1) ? bf_hi(w0) : bf_lo(w0); o.y = (jc & 1) ? bf_hi(w1) : bf_lo(w1);
;         *(LAS f32x2*)(plane + 2 * i) = o; }
; }
	v_pk_add_f32 v[130:131], v[184:185], v[188:189] op_sel:[0,1] op_sel_hi:[1,0] neg_hi:[0,1]
	v_pk_mul_f32 v[168:169], v[176:177], s[68:69] op_sel:[1,1] op_sel_hi:[0,1]
	v_pk_fma_f32 v[176:177], v[176:177], s[68:69], v[168:169] op_sel_hi:[1,0,1] neg_hi:[0,0,1]
	v_pk_mul_f32 v[180:181], v[112:113], s[84:85] op_sel:[1,1] op_sel_hi:[0,1]
	v_pk_fma_f32 v[112:113], v[112:113], s[84:85], v[180:181] op_sel_hi:[1,0,1] neg_hi:[0,0,1]
	v_pk_mul_f32 v[126:127], v[114:115], s[88:89] op_sel:[1,1] op_sel_hi:[0,1]
	v_pk_fma_f32 v[114:115], v[114:115], s[88:89], v[126:127] op_sel_hi:[1,0,1] neg_hi:[0,0,1]
	v_pk_mul_f32 v[118:119], v[166:167], s[84:85] op_sel:[1,1] op_sel_hi:[0,1]
	v_pk_fma_f32 v[166:167], v[166:167], s[84:85], v[118:119] op_sel_hi:[1,0,1] neg_hi:[0,0,1]
	v_pk_mul_f32 v[182:183], v[122:123], s[90:91] op_sel:[1,1] op_sel_hi:[0,1]
	v_pk_fma_f32 v[122:123], v[122:123], s[90:91], v[182:183] op_sel_hi:[1,0,1] neg_hi:[0,0,1]
	v_pk_mul_f32 v[110:111], v[174:175], s[88:89] op_sel:[1,1] op_sel_hi:[0,1]
	v_pk_fma_f32 v[174:175], v[174:175], s[88:89], v[110:111] op_sel_hi:[1,0,1] neg_hi:[0,0,1]
	v_pk_mul_f32 v[102:103], v[128:129], s[90:91] op_sel:[1,1] op_sel_hi:[0,1]
	v_pk_fma_f32 v[128:129], v[128:129], s[90:91], v[102:103] op_sel_hi:[1,0,1] neg_hi:[0,0,1]
	v_pk_mul_f32 v[184:185], v[130:131], s[98:99] op_sel:[1,1] op_sel_hi:[0,1]
	v_pk_fma_f32 v[130:131], v[130:131], s[98:99], v[184:185] op_sel_hi:[1,0,1] neg_hi:[0,0,1]
	v_pk_add_f32 v[186:187], v[100:101], v[104:105]
	v_pk_add_f32 v[188:189], v[100:101], v[104:105] neg_lo:[0,1] neg_hi:[0,1]
	v_pk_add_f32 v[168:169], v[178:179], v[106:107]
	v_pk_add_f32 v[180:181], v[178:179], v[106:107] neg_lo:[0,1] neg_hi:[0,1]
	v_pk_add_f32 v[100:101], v[186:187], v[168:169]
	v_pk_add_f32 v[178:179], v[188:189], v[180:181] op_sel:[0,1] op_sel_hi:[1,0] neg_lo:[0,1]
	v_pk_add_f32 v[126:127], v[108:109], v[112:113]
	v_pk_add_f32 v[118:119], v[108:109], v[112:113] neg_lo:[0,1] neg_hi:[0,1]
	v_pk_add_f32 v[182:183], v[176:177], v[114:115]
	v_pk_add_f32 v[110:111], v[176:177], v[114:115] neg_lo:[0,1] neg_hi:[0,1]
	v_pk_add_f32 v[108:109], v[126:127], v[182:183]
	v_pk_add_f32 v[176:177], v[118:119], v[110:111] op_sel:[0,1] op_sel_hi:[1,0] neg_lo:[0,1]
	v_pk_add_f32 v[102:103], v[116:117], v[120:121] op_sel:[0,1] op_sel_hi:[1,0] neg_lo:[0,1]
	v_pk_add_f32 v[184:185], v[116:117], v[120:121] op_sel:[0,1] op_sel_hi:[1,0] neg_hi:[0,1]
	v_pk_add_f32 v[186:187], v[166:167], v[122:123]
	v_pk_add_f32 v[188:189], v[166:167], v[122:123] neg_lo:[0,1] neg_hi:[0,1]
	v_pk_add_f32 v[116:117], v[102:103], v[186:187]
	v_pk_add_f32 v[166:167], v[184:185], v[188:189] op_sel:[0,1] op_sel_hi:[1,0] neg_lo:[0,1]
	v_pk_add_f32 v[168:169], v[124:125], v[128:129]
	v_pk_add_f32 v[180:181], v[124:125], v[128:129] neg_lo:[0,1] neg_hi:[0,1]
	v_pk_add_f32 v[126:127], v[174:175], v[130:131]
	v_pk_add_f32 v[118:119], v[174:175], v[130:131] neg_lo:[0,1] neg_hi:[0,1]
	v_pk_add_f32 v[124:125], v[168:169], v[126:127]
	v_pk_add_f32 v[174:175], v[180:181], v[118:119] op_sel:[0,1] op_sel_hi:[1,0] neg_lo:[0,1]
	s_load_dword s35, s[50:51], 0x0
	s_waitcnt lgkmcnt(0)
	v_mov_b32_e32 v194, s35
	v_pk_fma_f32 v[182:183], v[132:133], v[194:195], v[100:101] op_sel_hi:[1,0,1]
	v_pk_mul_f32 v[132:133], v[148:149], v[182:183]
	v_pk_fma_f32 v[110:111], v[134:135], v[194:195], v[108:109] op_sel_hi:[1,0,1]
	v_pk_mul_f32 v[134:135], v[150:151], v[110:111]
	v_pk_fma_f32 v[102:103], v[136:137], v[194:195], v[116:117] op_sel_hi:[1,0,1]
	v_pk_mul_f32 v[136:137], v[152:153], v[102:103]
	v_pk_fma_f32 v[184:185], v[138:139], v[194:195], v[124:125] op_sel_hi:[1,0,1]
	v_pk_mul_f32 v[138:139], v[154:155], v[184:185]
	v_pk_fma_f32 v[186:187], v[140:141], v[194:195], v[178:179] op_sel_hi:[1,0,1]
	v_pk_mul_f32 v[140:141], v[158:159], v[186:187]
	v_pk_fma_f32 v[188:189], v[142:143], v[194:195], v[176:177] op_sel_hi:[1,0,1]
	v_pk_mul_f32 v[142:143], v[160:161], v[188:189]
	v_pk_fma_f32 v[168:169], v[144:145], v[194:195], v[166:167] op_sel_hi:[1,0,1]
	v_pk_mul_f32 v[144:145], v[162:163], v[168:169]
	v_pk_fma_f32 v[180:181], v[146:147], v[194:195], v[174:175] op_sel_hi:[1,0,1]
	v_pk_mul_f32 v[146:147], v[164:165], v[180:181]
	s_waitcnt lgkmcnt(0)
	s_barrier
	s_waitcnt vmcnt(7)
	v_perm_b32 v126, 0, v58, s15
	v_perm_b32 v127, 0, v60, s15
	ds_write_b64 v206, v[126:127]
	s_waitcnt vmcnt(6)
	v_perm_b32 v118, 0, v62, s15
	v_perm_b32 v119, 0, v64, s15
	ds_write_b64 v206, v[118:119] offset:4096
	s_waitcnt vmcnt(5)
	v_perm_b32 v182, 0, v66, s15
	v_perm_b32 v183, 0, v68, s15
	ds_write_b64 v206, v[182:183] offset:8192
	s_waitcnt vmcnt(4)
	v_perm_b32 v110, 0, v70, s15
	v_perm_b32 v111, 0, v72, s15
	ds_write_b64 v206, v[110:111] offset:12288
	s_waitcnt vmcnt(3)
	v_perm_b32 v102, 0, v74, s15
	v_perm_b32 v103, 0, v76, s15
	ds_write_b64 v206, v[102:103] offset:16384
	s_waitcnt vmcnt(2)
	v_perm_b32 v184, 0, v78, s15
	v_perm_b32 v185, 0, v80, s15
	ds_write_b64 v206, v[184:185] offset:20480
	s_waitcnt vmcnt(1)
	v_perm_b32 v186, 0, v82, s15
	v_perm_b32 v187, 0, v84, s15
	ds_write_b64 v206, v[186:187] offset:24576
	s_waitcnt vmcnt(0)
	v_perm_b32 v188, 0, v86, s15
	v_perm_b32 v189, 0, v88, s15
	ds_write_b64 v206, v[188:189] offset:28672
	s_waitcnt lgkmcnt(0)
	s_barrier
; #define LAS __attribute__((address_space(3)))
; __device__ __forceinline__ void hy_sconv(const LAS float* plane, float w0, float w1, float w2, float cb, int n2, float (&u)[8][2]) {
;     asm volatile("" : "+v"(n2));
; #pragma unroll
;     for (int r = 0; r < 8; ++r)
; #pragma unroll
;         for (int b = 0; b < 2; ++b) { const int t = n2 + 512 * r, row = b * SEQ + t;
;             float a = cb + w1 * plane[row];
;             if (t > 0) a += w0 * plane[row - 1];
;             if (t < SEQ - 1) a += w2 * plane[row + 1];
;             u[r][b] = a; }
; }
	v_mov_b32_e32 v168, s17
	v_mov_b32_e32 v169, s23
	v_mov_b32_e32 v180, s25
	v_mov_b32_e32 v181, s26
	ds_read_b32 v126, v208
	ds_read_b32 v118, v210
	ds_read_b32 v182, v208 offset:4
	ds_read_b32 v127, v208 offset:16384
	ds_read_b32 v119, v210 offset:16384
	ds_read_b32 v183, v208 offset:16388
	ds_read_b32 v110, v208 offset:2048
	ds_read_b32 v102, v208 offset:2044
	ds_read_b32 v184, v208 offset:2052
	ds_read_b32 v111, v208 offset:18432
	ds_read_b32 v103, v208 offset:18428
	ds_read_b32 v185, v208 offset:18436
	s_waitcnt lgkmcnt(10)
	v_cndmask_b32_e64 v118, v118, 0, s[10:11]
	s_waitcnt lgkmcnt(7)
	v_cndmask_b32_e64 v119, v119, 0, s[10:11]
	v_pk_fma_f32 v[148:149], v[168:169], v[126:127], v[180:181] op_sel:[1,0,1]
	v_pk_fma_f32 v[148:149], v[168:169], v[118:119], v[148:149] op_sel_hi:[0,1,1]
	s_waitcnt lgkmcnt(6)
	v_pk_fma_f32 v[148:149], v[180:181], v[182:183], v[148:149] op_sel_hi:[0,1,1]
	s_waitcnt lgkmcnt(2)
	v_pk_fma_f32 v[150:151], v[168:169], v[110:111], v[180:181] op_sel:[1,0,1]
	s_waitcnt lgkmcnt(1)
	v_pk_fma_f32 v[150:151], v[168:169], v[102:103], v[150:151] op_sel_hi:[0,1,1]
	s_waitcnt lgkmcnt(0)
	v_pk_fma_f32 v[150:151], v[180:181], v[184:185], v[150:151] op_sel_hi:[0,1,1]
	ds_read_b32 v186, v208 offset:4096
	ds_read_b32 v188, v208 offset:4092
	ds_read_b32 v126, v208 offset:4100
	ds_read_b32 v187, v208 offset:20480
	ds_read_b32 v189, v208 offset:20476
	ds_read_b32 v127, v208 offset:20484
	ds_read_b32 v118, v208 offset:6144
	ds_read_b32 v182, v208 offset:6140
	ds_read_b32 v110, v208 offset:6148
	ds_read_b32 v119, v208 offset:22528
	ds_read_b32 v183, v208 offset:22524
	ds_read_b32 v111, v208 offset:22532
	s_waitcnt lgkmcnt(8)
	v_pk_fma_f32 v[152:153], v[168:169], v[186:187], v[180:181] op_sel:[1,0,1]
	s_waitcnt lgkmcnt(7)
	v_pk_fma_f32 v[152:153], v[168:169], v[188:189], v[152:153] op_sel_hi:[0,1,1]
	s_waitcnt lgkmcnt(6)
	v_pk_fma_f32 v[152:153], v[180:181], v[126:127], v[152:153] op_sel_hi:[0,1,1]
	s_waitcnt lgkmcnt(2)
	v_pk_fma_f32 v[154:155], v[168:169], v[118:119], v[180:181] op_sel:[1,0,1]
	s_waitcnt lgkmcnt(1)
	v_pk_fma_f32 v[154:155], v[168:169], v[182:183], v[154:155] op_sel_hi:[0,1,1]
	s_waitcnt lgkmcnt(0)
	v_pk_fma_f32 v[154:155], v[180:181], v[110:111], v[154:155] op_sel_hi:[0,1,1]
	ds_read_b32 v102, v208 offset:8192
	ds_read_b32 v184, v208 offset:8188
	ds_read_b32 v186, v208 offset:8196
	ds_read_b32 v103, v208 offset:24576
	ds_read_b32 v185, v208 offset:24572
	ds_read_b32 v187, v208 offset:24580
	ds_read_b32 v188, v208 offset:10240
	ds_read_b32 v126, v208 offset:10236
	ds_read_b32 v118, v208 offset:10244
	ds_read_b32 v189, v208 offset:26624
	ds_read_b32 v127, v208 offset:26620
	ds_read_b32 v119, v208 offset:26628
	s_waitcnt lgkmcnt(8)
	v_pk_fma_f32 v[158:159], v[168:169], v[102:103], v[180:181] op_sel:[1,0,1]
	s_waitcnt lgkmcnt(7)
	v_pk_fma_f32 v[158:159], v[168:169], v[184:185], v[158:159] op_sel_hi:[0,1,1]
	s_waitcnt lgkmcnt(6)
	v_pk_fma_f32 v[158:159], v[180:181], v[186:187], v[158:159] op_sel_hi:[0,1,1]
	s_waitcnt lgkmcnt(2)
	v_pk_fma_f32 v[160:161], v[168:169], v[188:189], v[180:181] op_sel:[1,0,1]
	s_waitcnt lgkmcnt(1)
	v_pk_fma_f32 v[160:161], v[168:169], v[126:127], v[160:161] op_sel_hi:[0,1,1]
	s_waitcnt lgkmcnt(0)
	v_pk_fma_f32 v[160:161], v[180:181], v[118:119], v[160:161] op_sel_hi:[0,1,1]
	ds_read_b32 v182, v208 offset:12288
	ds_read_b32 v110, v208 offset:12284
	ds_read_b32 v102, v208 offset:12292
	ds_read_b32 v183, v208 offset:28672
	ds_read_b32 v111, v208 offset:28668
	ds_read_b32 v103, v208 offset:28676
	ds_read_b32 v184, v208 offset:14336
	ds_read_b32 v186, v208 offset:14332
	ds_read_b32 v188, v208 offset:14340
	ds_read_b32 v185, v208 offset:30720
	ds_read_b32 v187, v208 offset:30716
	ds_read_b32 v189, v208 offset:30724
	s_waitcnt lgkmcnt(8)
	v_pk_fma_f32 v[162:163], v[168:169], v[182:183], v[180:181] op_sel:[1,0,1]
	s_waitcnt lgkmcnt(7)
	v_pk_fma_f32 v[162:163], v[168:169], v[110:111], v[162:163] op_sel_hi:[0,1,1]
	s_waitcnt lgkmcnt(6)
	v_pk_fma_f32 v[162:163], v[180:181], v[102:103], v[162:163] op_sel_hi:[0,1,1]
	s_waitcnt lgkmcnt(3)
	v_cndmask_b32_e64 v188, v188, 0, s[28:29]
	s_waitcnt lgkmcnt(0)
	v_cndmask_b32_e64 v189, v189, 0, s[28:29]
	v_pk_fma_f32 v[164:165], v[168:169], v[184:185], v[180:181] op_sel:[1,0,1]
	v_pk_fma_f32 v[164:165], v[168:169], v[186:187], v[164:165] op_sel_hi:[0,1,1]
	v_pk_fma_f32 v[164:165], v[180:181], v[188:189], v[164:165] op_sel_hi:[0,1,1]
	s_waitcnt lgkmcnt(0)
	s_barrier
; __device__ __forceinline__ f32x2 cmul(f32x2 a, f32x2 b) { return (f32x2){a.x * b.x - a.y * b.y, a.x * b.y + a.y * b.x}; }
; __device__ __forceinline__ void dft16_fwd_lo(f32x2 (&x)[16]) {
;     constexpr float C1 = 0.92387953251128674f, S1 = 0.38268343236508977f, C2 = 0.70710678118654752f;
; #pragma unroll
;     for (int b = 0; b < 4; ++b) { const f32x2 x0 = x[b], x1 = x[4 + b]; const f32x2 j1 = {x1.y, -x1.x};
;         x[b] = x0 + x1; x[4 + b] = x0 + j1; x[8 + b] = x0 - x1; x[12 + b] = x0 - j1; }
;     const f32x2 w1 = {C1, -S1}, w2 = {C2, -C2}, w3 = {S1, -C1}, w4 = {0.f, -1.f}, w6 = {-C2, -C2}, w9 = {-C1, S1};
;     x[5] = cmul(x[5], w1); x[6] = cmul(x[6], w2); x[7] = cmul(x[7], w3);
;     x[9] = cmul(x[9], w2); x[10] = cmul(x[10], w4); x[11] = cmul(x[11], w6);
;     x[13] = cmul(x[13], w3); x[14] = cmul(x[14], w6); x[15] = cmul(x[15], w9);
; #pragma unroll
;     for (int c = 0; c < 4; ++c) dft4<false>(x[4 * c], x[4 * c + 1], x[4 * c + 2], x[4 * c + 3]);
;     f32x2 y[16];
; #pragma unroll
;     for (int k = 0; k < 16; ++k) y[k] = x[4 * (k & 3) + (k >> 2)];
; #pragma unroll
;     for (int k = 0; k < 16; ++k) x[k] = y[k];
; }
; __device__ __forceinline__ void dft16_inv_lo(f32x2 (&x)[16]) {
;     constexpr float C1 = 0.92387953251128674f, S1 = 0.38268343236508977f, C2 = 0.70710678118654752f;
; #pragma unroll
;     for (int b = 0; b < 4; ++b) dft4<true>(x[b], x[4 + b], x[8 + b], x[12 + b]);
;     const f32x2 w1 = {C1, -S1}, w2 = {C2, -C2}, w3 = {S1, -C1}, w4 = {0.f, -1.f}, w6 = {-C2, -C2}, w9 = {-C1, S1};
;     x[5] = cmulc(x[5], w1); x[6] = cmulc(x[6], w2); x[7] = cmulc(x[7], w3);
;     x[9] = cmulc(x[9], w2); x[10] = cmulc(x[10], w4); x[11] = cmulc(x[11], w6);
;     x[13] = cmulc(x[13], w3); x[14] = cmulc(x[14], w6); x[15] = cmulc(x[15], w9);
;     f32x2 y[8];
; #pragma unroll
;     for (int c = 0; c < 4; ++c) { const f32x2 t0 = x[4 * c] + x[4 * c + 2], t1 = x[4 * c] - x[4 * c + 2], t2 = x[4 * c + 1] + x[4 * c + 3], t3 = x[4 * c + 1] - x[4 * c + 3];
;         y[c] = t0 + t2; y[4 + c] = t1 + (f32x2){-t3.y, t3.x}; }
; #pragma unroll
;     for (int k = 0; k < 8; ++k) x[k] = y[k];
; }
; template <bool INV> __device__ __forceinline__ void dft32(f32x2 (&x)[32]) {
;     constexpr float CS[16] = {1.f, 0.98078528040323043f, 0.92387953251128674f, 0.83146961230254524f, 0.70710678118654752f, 0.55557023301960218f, 0.38268343236508977f, 0.19509032201612825f,
	v_pk_add_f32 v[104:105], v[132:133], v[140:141] neg_lo:[0,1] neg_hi:[0,1]
	v_pk_add_f32 v[106:107], v[132:133], v[140:141] op_sel:[0,1] op_sel_hi:[1,0] neg_lo:[0,1]
	v_pk_add_f32 v[126:127], v[132:133], v[140:141] op_sel:[0,1] op_sel_hi:[1,0] neg_hi:[0,1]
	v_pk_add_f32 v[100:101], v[132:133], v[140:141]
	v_pk_add_f32 v[112:113], v[134:135], v[142:143] neg_lo:[0,1] neg_hi:[0,1]
	v_pk_add_f32 v[114:115], v[134:135], v[142:143] op_sel:[0,1] op_sel_hi:[1,0] neg_lo:[0,1]
	v_pk_add_f32 v[118:119], v[134:135], v[142:143] op_sel:[0,1] op_sel_hi:[1,0] neg_hi:[0,1]
	v_pk_add_f32 v[108:109], v[134:135], v[142:143]
	v_pk_add_f32 v[120:121], v[136:137], v[144:145] neg_lo:[0,1] neg_hi:[0,1]
	v_pk_add_f32 v[122:123], v[136:137], v[144:145] op_sel:[0,1] op_sel_hi:[1,0] neg_lo:[0,1]
	v_pk_add_f32 v[182:183], v[136:137], v[144:145] op_sel:[0,1] op_sel_hi:[1,0] neg_hi:[0,1]
	v_pk_add_f32 v[116:117], v[136:137], v[144:145]
	v_pk_add_f32 v[128:129], v[138:139], v[146:147] neg_lo:[0,1] neg_hi:[0,1]
	v_pk_add_f32 v[130:131], v[138:139], v[146:147] op_sel:[0,1] op_sel_hi:[1,0] neg_lo:[0,1]
	v_pk_add_f32 v[110:111], v[138:139], v[146:147] op_sel:[0,1] op_sel_hi:[1,0] neg_hi:[0,1]
	v_pk_add_f32 v[124:125], v[138:139], v[146:147]
	v_pk_mul_f32 v[102:103], v[118:119], s[68:69] op_sel:[1,1] op_sel_hi:[0,1]
	v_pk_fma_f32 v[118:119], v[118:119], s[68:69], v[102:103] op_sel_hi:[1,0,1] neg_lo:[0,0,1]
	v_pk_mul_f32 v[184:185], v[182:183], s[84:85] op_sel:[1,1] op_sel_hi:[0,1]
	v_pk_fma_f32 v[182:183], v[182:183], s[84:85], v[184:185] op_sel_hi:[1,0,1] neg_lo:[0,0,1]
	v_pk_mul_f32 v[186:187], v[110:111], s[88:89] op_sel:[1,1] op_sel_hi:[0,1]
	v_pk_fma_f32 v[110:111], v[110:111], s[88:89], v[186:187] op_sel_hi:[1,0,1] neg_lo:[0,0,1]
	v_pk_mul_f32 v[188:189], v[112:113], s[84:85] op_sel:[1,1] op_sel_hi:[0,1]
	v_pk_fma_f32 v[112:113], v[112:113], s[84:85], v[188:189] op_sel_hi:[1,0,1] neg_lo:[0,0,1]
	v_pk_mul_f32 v[168:169], v[128:129], s[90:91] op_sel:[1,1] op_sel_hi:[0,1]
	v_pk_fma_f32 v[128:129], v[128:129], s[90:91], v[168:169] op_sel_hi:[1,0,1] neg_lo:[0,0,1]
	v_pk_mul_f32 v[180:181], v[114:115], s[88:89] op_sel:[1,1] op_sel_hi:[0,1]
	v_pk_fma_f32 v[114:115], v[114:115], s[88:89], v[180:181] op_sel_hi:[1,0,1] neg_lo:[0,0,1]
	v_pk_mul_f32 v[178:179], v[122:123], s[90:91] op_sel:[1,1] op_sel_hi:[0,1]
	v_pk_fma_f32 v[122:123], v[122:123], s[90:91], v[178:179] op_sel_hi:[1,0,1] neg_lo:[0,0,1]
	v_pk_mul_f32 v[176:177], v[130:131], s[98:99] op_sel:[1,1] op_sel_hi:[0,1]
	v_pk_fma_f32 v[130:131], v[130:131], s[98:99], v[176:177] op_sel_hi:[1,0,1] neg_lo:[0,0,1]
	v_pk_add_f32 v[166:167], v[100:101], v[116:117]
	v_pk_add_f32 v[174:175], v[100:101], v[116:117] neg_lo:[0,1] neg_hi:[0,1]
	v_pk_add_f32 v[102:103], v[108:109], v[124:125]
	v_pk_add_f32 v[184:185], v[108:109], v[124:125] neg_lo:[0,1] neg_hi:[0,1]
	v_pk_add_f32 v[100:101], v[166:167], v[102:103]
	v_pk_add_f32 v[116:117], v[166:167], v[102:103] neg_lo:[0,1] neg_hi:[0,1]
	v_pk_add_f32 v[108:109], v[174:175], v[184:185] op_sel:[0,1] op_sel_hi:[1,0] neg_hi:[0,1]
	v_pk_add_f32 v[124:125], v[174:175], v[184:185] op_sel:[0,1] op_sel_hi:[1,0] neg_lo:[0,1]
	v_pk_add_f32 v[186:187], v[126:127], v[182:183]
	v_pk_add_f32 v[188:189], v[126:127], v[182:183] neg_lo:[0,1] neg_hi:[0,1]
	v_pk_add_f32 v[168:169], v[118:119], v[110:111]
	v_pk_add_f32 v[180:181], v[118:119], v[110:111] neg_lo:[0,1] neg_hi:[0,1]
	v_pk_add_f32 v[126:127], v[186:187], v[168:169]
	v_pk_add_f32 v[182:183], v[186:187], v[168:169] neg_lo:[0,1] neg_hi:[0,1]
	v_pk_add_f32 v[118:119], v[188:189], v[180:181] op_sel:[0,1] op_sel_hi:[1,0] neg_hi:[0,1]
	v_pk_add_f32 v[110:111], v[188:189], v[180:181] op_sel:[0,1] op_sel_hi:[1,0] neg_lo:[0,1]
	v_pk_add_f32 v[178:179], v[104:105], v[120:121] op_sel:[0,1] op_sel_hi:[1,0] neg_hi:[0,1]
	v_pk_add_f32 v[176:177], v[104:105], v[120:121] op_sel:[0,1] op_sel_hi:[1,0] neg_lo:[0,1]
	v_pk_add_f32 v[166:167], v[112:113], v[128:129]
	v_pk_add_f32 v[174:175], v[112:113], v[128:129] neg_lo:[0,1] neg_hi:[0,1]
	v_pk_add_f32 v[104:105], v[178:179], v[166:167]
	v_pk_add_f32 v[120:121], v[178:179], v[166:167] neg_lo:[0,1] neg_hi:[0,1]
	v_pk_add_f32 v[112:113], v[176:177], v[174:175] op_sel:[0,1] op_sel_hi:[1,0] neg_hi:[0,1]
	v_pk_add_f32 v[128:129], v[176:177], v[174:175] op_sel:[0,1] op_sel_hi:[1,0] neg_lo:[0,1]
	v_pk_add_f32 v[102:103], v[106:107], v[122:123]
	v_pk_add_f32 v[184:185], v[106:107], v[122:123] neg_lo:[0,1] neg_hi:[0,1]
	v_pk_add_f32 v[186:187], v[114:115], v[130:131]
	v_pk_add_f32 v[188:189], v[114:115], v[130:131] neg_lo:[0,1] neg_hi:[0,1]
	v_pk_add_f32 v[106:107], v[102:103], v[186:187]
	v_pk_add_f32 v[122:123], v[102:103], v[186:187] neg_lo:[0,1] neg_hi:[0,1]
	v_pk_add_f32 v[114:115], v[184:185], v[188:189] op_sel:[0,1] op_sel_hi:[1,0] neg_hi:[0,1]
	v_pk_add_f32 v[130:131], v[184:185], v[188:189] op_sel:[0,1] op_sel_hi:[1,0] neg_lo:[0,1]
	ds_write_b64 v3, v[100:101]
	v_pk_mul_f32 v[180:181], v[126:127], v[6:7] op_sel:[1,1] op_sel_hi:[0,1]
	v_pk_fma_f32 v[168:169], v[126:127], v[6:7], v[180:181] op_sel_hi:[1,0,1] neg_lo:[0,0,1]
	ds_write_b64 v3, v[168:169] offset:4224
	v_pk_mul_f32 v[176:177], v[104:105], v[8:9] op_sel:[1,1] op_sel_hi:[0,1]
	v_pk_fma_f32 v[178:179], v[104:105], v[8:9], v[176:177] op_sel_hi:[1,0,1] neg_lo:[0,0,1]
	ds_write_b64 v3, v[178:179] offset:8448
	v_pk_mul_f32 v[174:175], v[106:107], v[10:11] op_sel:[1,1] op_sel_hi:[0,1]
	v_pk_fma_f32 v[166:167], v[106:107], v[10:11], v[174:175] op_sel_hi:[1,0,1] neg_lo:[0,0,1]
	ds_write_b64 v3, v[166:167] offset:12672
	v_pk_mul_f32 v[184:185], v[108:109], v[12:13] op_sel:[1,1] op_sel_hi:[0,1]
	v_pk_fma_f32 v[102:103], v[108:109], v[12:13], v[184:185] op_sel_hi:[1,0,1] neg_lo:[0,0,1]
; #define LAS __attribute__((address_space(3)))
; __device__ __forceinline__ f32x2 cmul(f32x2 a, f32x2 b) { return (f32x2){a.x * b.x - a.y * b.y, a.x * b.y + a.y * b.x}; }
; template <bool INV> __device__ __forceinline__ f32x2 cmul_tw(f32x2 a, f32x2 w) { return INV ? cmulc(a, w) : cmul(a, w); }
; template <bool INV> __device__ __forceinline__ void dft16(f32x2 (&x)[16]) {
;     constexpr float C1 = 0.92387953251128674f, S1 = 0.38268343236508977f, C2 = 0.70710678118654752f;
; #pragma unroll
;     for (int b = 0; b < 4; ++b) dft4<INV>(x[b], x[4 + b], x[8 + b], x[12 + b]);
;     const f32x2 w1 = {C1, -S1}, w2 = {C2, -C2}, w3 = {S1, -C1}, w4 = {0.f, -1.f}, w6 = {-C2, -C2}, w9 = {-C1, S1};
;     x[4 * 1 + 1] = cmul_tw<INV>(x[5], w1); x[4 * 1 + 2] = cmul_tw<INV>(x[6], w2); x[4 * 1 + 3] = cmul_tw<INV>(x[7], w3);
;     x[4 * 2 + 1] = cmul_tw<INV>(x[9], w2); x[4 * 2 + 2] = cmul_tw<INV>(x[10], w4); x[4 * 2 + 3] = cmul_tw<INV>(x[11], w6);
;     x[4 * 3 + 1] = cmul_tw<INV>(x[13], w3); x[4 * 3 + 2] = cmul_tw<INV>(x[14], w6); x[4 * 3 + 3] = cmul_tw<INV>(x[15], w9);
; #pragma unroll
;     for (int c = 0; c < 4; ++c) dft4<INV>(x[4 * c], x[4 * c + 1], x[4 * c + 2], x[4 * c + 3]);
;     f32x2 y[16];
; #pragma unroll
;     for (int k = 0; k < 16; ++k) y[k] = x[4 * (k & 3) + (k >> 2)];
; #pragma unroll
;     for (int k = 0; k < 16; ++k) x[k] = y[k];
; }
; template <bool LO> __device__ __forceinline__ void fft_fwd1(f32x2 (&x)[16], LAS f32x2* B, int n2, const f32x2 (&w)[16]) {
;     asm volatile("" : "+v"(n2));
;     if (LO) dft16_fwd_lo(x); else dft16<false>(x);
;     B[fpad(n2)] = x[0];
; #pragma unroll
;     for (int k = 1; k < 16; ++k) B[fpad(512 * k + n2)] = cmul(x[k], w[k]);
; }
; __device__ __forceinline__ void fft_fwd2(LAS f32x2* B, const LAS f32x2* TW2, int tid) {
;     asm volatile("" : "+v"(tid));
;     const int b = tid >> 5, n2 = tid & 31, base = 512 * b + n2; f32x2 x[16];
; #pragma unroll
;     for (int r = 0; r < 16; ++r) x[r] = B[fpad(base + 32 * r)];
;     dft16<false>(x);
;     B[fpad(base)] = x[0];
; #pragma unroll
;     for (int k = 1; k < 16; ++k) B[fpad(base + 32 * k)] = cmul(x[k], TW2[k * 32 + n2]);
; }
	ds_write_b64 v3, v[102:103] offset:16896
	v_pk_mul_f32 v[188:189], v[118:119], v[14:15] op_sel:[1,1] op_sel_hi:[0,1]
	v_pk_fma_f32 v[186:187], v[118:119], v[14:15], v[188:189] op_sel_hi:[1,0,1] neg_lo:[0,0,1]
	ds_write_b64 v3, v[186:187] offset:21120
	v_pk_mul_f32 v[168:169], v[112:113], v[16:17] op_sel:[1,1] op_sel_hi:[0,1]
	v_pk_fma_f32 v[180:181], v[112:113], v[16:17], v[168:169] op_sel_hi:[1,0,1] neg_lo:[0,0,1]
	ds_write_b64 v3, v[180:181] offset:25344
	v_pk_mul_f32 v[178:179], v[114:115], v[18:19] op_sel:[1,1] op_sel_hi:[0,1]
	v_pk_fma_f32 v[176:177], v[114:115], v[18:19], v[178:179] op_sel_hi:[1,0,1] neg_lo:[0,0,1]
	ds_write_b64 v3, v[176:177] offset:29568
	v_pk_mul_f32 v[166:167], v[116:117], v[20:21] op_sel:[1,1] op_sel_hi:[0,1]
	v_pk_fma_f32 v[174:175], v[116:117], v[20:21], v[166:167] op_sel_hi:[1,0,1] neg_lo:[0,0,1]
	ds_write_b64 v3, v[174:175] offset:33792
	v_pk_mul_f32 v[102:103], v[182:183], v[22:23] op_sel:[1,1] op_sel_hi:[0,1]
	v_pk_fma_f32 v[184:185], v[182:183], v[22:23], v[102:103] op_sel_hi:[1,0,1] neg_lo:[0,0,1]
	ds_write_b64 v3, v[184:185] offset:38016
	v_pk_mul_f32 v[186:187], v[120:121], v[24:25] op_sel:[1,1] op_sel_hi:[0,1]
	v_pk_fma_f32 v[188:189], v[120:121], v[24:25], v[186:187] op_sel_hi:[1,0,1] neg_lo:[0,0,1]
	ds_write_b64 v3, v[188:189] offset:42240
	v_pk_mul_f32 v[180:181], v[122:123], v[26:27] op_sel:[1,1] op_sel_hi:[0,1]
	v_pk_fma_f32 v[168:169], v[122:123], v[26:27], v[180:181] op_sel_hi:[1,0,1] neg_lo:[0,0,1]
	ds_write_b64 v3, v[168:169] offset:46464
	v_pk_mul_f32 v[176:177], v[124:125], v[28:29] op_sel:[1,1] op_sel_hi:[0,1]
	v_pk_fma_f32 v[178:179], v[124:125], v[28:29], v[176:177] op_sel_hi:[1,0,1] neg_lo:[0,0,1]
	ds_write_b64 v3, v[178:179] offset:50688
	v_pk_mul_f32 v[174:175], v[110:111], v[30:31] op_sel:[1,1] op_sel_hi:[0,1]
	v_pk_fma_f32 v[166:167], v[110:111], v[30:31], v[174:175] op_sel_hi:[1,0,1] neg_lo:[0,0,1]
	ds_write_b64 v3, v[166:167] offset:54912
	v_pk_mul_f32 v[184:185], v[128:129], v[32:33] op_sel:[1,1] op_sel_hi:[0,1]
	v_pk_fma_f32 v[102:103], v[128:129], v[32:33], v[184:185] op_sel_hi:[1,0,1] neg_lo:[0,0,1]
	ds_write_b64 v3, v[102:103] offset:59136
	v_pk_mul_f32 v[188:189], v[130:131], v[34:35] op_sel:[1,1] op_sel_hi:[0,1]
	v_pk_fma_f32 v[186:187], v[130:131], v[34:35], v[188:189] op_sel_hi:[1,0,1] neg_lo:[0,0,1]
	ds_write_b64 v3, v[186:187] offset:63360
	s_waitcnt lgkmcnt(0)
	s_barrier
	ds_read_b64 v[100:101], v5
	ds_read_b64 v[108:109], v5 offset:1056
	ds_read_b64 v[116:117], v5 offset:2112
	ds_read_b64 v[124:125], v5 offset:3168
	ds_read_b64 v[126:127], v5 offset:264
	ds_read_b64 v[118:119], v5 offset:1320
	ds_read_b64 v[182:183], v5 offset:2376
	ds_read_b64 v[110:111], v5 offset:3432
	ds_read_b64 v[104:105], v5 offset:528
	ds_read_b64 v[112:113], v5 offset:1584
	ds_read_b64 v[120:121], v5 offset:2640
	ds_read_b64 v[128:129], v5 offset:3696
	s_waitcnt lgkmcnt(8)
	ds_read_b64 v[106:107], v5 offset:792
	ds_read_b64 v[114:115], v5 offset:1848
	ds_read_b64 v[122:123], v5 offset:2904
	ds_read_b64 v[130:131], v5 offset:3960
	v_pk_add_f32 v[180:181], v[100:101], v[116:117]
	v_pk_add_f32 v[168:169], v[100:101], v[116:117] neg_lo:[0,1] neg_hi:[0,1]
	v_pk_add_f32 v[176:177], v[108:109], v[124:125]
	v_pk_add_f32 v[178:179], v[108:109], v[124:125] neg_lo:[0,1] neg_hi:[0,1]
	v_pk_add_f32 v[100:101], v[180:181], v[176:177]
	v_pk_add_f32 v[116:117], v[180:181], v[176:177] neg_lo:[0,1] neg_hi:[0,1]
	v_pk_add_f32 v[108:109], v[168:169], v[178:179] op_sel:[0,1] op_sel_hi:[1,0] neg_hi:[0,1]
	v_pk_add_f32 v[124:125], v[168:169], v[178:179] op_sel:[0,1] op_sel_hi:[1,0] neg_lo:[0,1]
	s_waitcnt lgkmcnt(9)
	v_pk_add_f32 v[174:175], v[126:127], v[182:183]
	v_pk_add_f32 v[166:167], v[126:127], v[182:183] neg_lo:[0,1] neg_hi:[0,1]
	s_waitcnt lgkmcnt(8)
	v_pk_add_f32 v[184:185], v[118:119], v[110:111]
	v_pk_add_f32 v[102:103], v[118:119], v[110:111] neg_lo:[0,1] neg_hi:[0,1]
	v_pk_add_f32 v[126:127], v[174:175], v[184:185]
	v_pk_add_f32 v[182:183], v[174:175], v[184:185] neg_lo:[0,1] neg_hi:[0,1]
	v_pk_add_f32 v[118:119], v[166:167], v[102:103] op_sel:[0,1] op_sel_hi:[1,0] neg_hi:[0,1]
	v_pk_add_f32 v[110:111], v[166:167], v[102:103] op_sel:[0,1] op_sel_hi:[1,0] neg_lo:[0,1]
	s_waitcnt lgkmcnt(5)
	v_pk_add_f32 v[188:189], v[104:105], v[120:121]
	v_pk_add_f32 v[186:187], v[104:105], v[120:121] neg_lo:[0,1] neg_hi:[0,1]
	s_waitcnt lgkmcnt(4)
	v_pk_add_f32 v[180:181], v[112:113], v[128:129]
	v_pk_add_f32 v[168:169], v[112:113], v[128:129] neg_lo:[0,1] neg_hi:[0,1]
	v_pk_add_f32 v[104:105], v[188:189], v[180:181]
	v_pk_add_f32 v[120:121], v[188:189], v[180:181] neg_lo:[0,1] neg_hi:[0,1]
	v_pk_add_f32 v[112:113], v[186:187], v[168:169] op_sel:[0,1] op_sel_hi:[1,0] neg_hi:[0,1]
	v_pk_add_f32 v[128:129], v[186:187], v[168:169] op_sel:[0,1] op_sel_hi:[1,0] neg_lo:[0,1]
	s_waitcnt lgkmcnt(1)
	v_pk_add_f32 v[176:177], v[106:107], v[122:123]
	v_pk_add_f32 v[178:179], v[106:107], v[122:123] neg_lo:[0,1] neg_hi:[0,1]
	s_waitcnt lgkmcnt(0)
; #define LAS __attribute__((address_space(3)))
; __device__ __forceinline__ f32x2 cmul(f32x2 a, f32x2 b) { return (f32x2){a.x * b.x - a.y * b.y, a.x * b.y + a.y * b.x}; }
; template <bool INV> __device__ __forceinline__ f32x2 cmul_tw(f32x2 a, f32x2 w) { return INV ? cmulc(a, w) : cmul(a, w); }
; template <bool INV> __device__ __forceinline__ void dft16(f32x2 (&x)[16]) {
;     constexpr float C1 = 0.92387953251128674f, S1 = 0.38268343236508977f, C2 = 0.70710678118654752f;
; #pragma unroll
;     for (int b = 0; b < 4; ++b) dft4<INV>(x[b], x[4 + b], x[8 + b], x[12 + b]);
;     const f32x2 w1 = {C1, -S1}, w2 = {C2, -C2}, w3 = {S1, -C1}, w4 = {0.f, -1.f}, w6 = {-C2, -C2}, w9 = {-C1, S1};
;     x[4 * 1 + 1] = cmul_tw<INV>(x[5], w1); x[4 * 1 + 2] = cmul_tw<INV>(x[6], w2); x[4 * 1 + 3] = cmul_tw<INV>(x[7], w3);
;     x[4 * 2 + 1] = cmul_tw<INV>(x[9], w2); x[4 * 2 + 2] = cmul_tw<INV>(x[10], w4); x[4 * 2 + 3] = cmul_tw<INV>(x[11], w6);
;     x[4 * 3 + 1] = cmul_tw<INV>(x[13], w3); x[4 * 3 + 2] = cmul_tw<INV>(x[14], w6); x[4 * 3 + 3] = cmul_tw<INV>(x[15], w9);
; #pragma unroll
;     for (int c = 0; c < 4; ++c) dft4<INV>(x[4 * c], x[4 * c + 1], x[4 * c + 2], x[4 * c + 3]);
;     f32x2 y[16];
; #pragma unroll
;     for (int k = 0; k < 16; ++k) y[k] = x[4 * (k & 3) + (k >> 2)];
; #pragma unroll
;     for (int k = 0; k < 16; ++k) x[k] = y[k];
; }
; __device__ __forceinline__ void fft_fwd2(LAS f32x2* B, const LAS f32x2* TW2, int tid) {
;     asm volatile("" : "+v"(tid));
;     const int b = tid >> 5, n2 = tid & 31, base = 512 * b + n2; f32x2 x[16];
; #pragma unroll
;     for (int r = 0; r < 16; ++r) x[r] = B[fpad(base + 32 * r)];
;     dft16<false>(x);
;     B[fpad(base)] = x[0];
; #pragma unroll
;     for (int k = 1; k < 16; ++k) B[fpad(base + 32 * k)] = cmul(x[k], TW2[k * 32 + n2]);
; }
	v_pk_add_f32 v[174:175], v[114:115], v[130:131]
	v_pk_add_f32 v[166:167], v[114:115], v[130:131] neg_lo:[0,1] neg_hi:[0,1]
	v_pk_add_f32 v[106:107], v[176:177], v[174:175]
	v_pk_add_f32 v[122:123], v[176:177], v[174:175] neg_lo:[0,1] neg_hi:[0,1]
	v_pk_add_f32 v[114:115], v[178:179], v[166:167] op_sel:[0,1] op_sel_hi:[1,0] neg_hi:[0,1]
	v_pk_add_f32 v[130:131], v[178:179], v[166:167] op_sel:[0,1] op_sel_hi:[1,0] neg_lo:[0,1]
	v_pk_mul_f32 v[184:185], v[118:119], s[68:69] op_sel:[1,1] op_sel_hi:[0,1]
	v_pk_fma_f32 v[118:119], v[118:119], s[68:69], v[184:185] op_sel_hi:[1,0,1] neg_lo:[0,0,1]
	v_pk_mul_f32 v[102:103], v[112:113], s[84:85] op_sel:[1,1] op_sel_hi:[0,1]
	v_pk_fma_f32 v[112:113], v[112:113], s[84:85], v[102:103] op_sel_hi:[1,0,1] neg_lo:[0,0,1]
	v_pk_mul_f32 v[188:189], v[114:115], s[88:89] op_sel:[1,1] op_sel_hi:[0,1]
	v_pk_fma_f32 v[114:115], v[114:115], s[88:89], v[188:189] op_sel_hi:[1,0,1] neg_lo:[0,0,1]
	v_pk_mul_f32 v[186:187], v[182:183], s[84:85] op_sel:[1,1] op_sel_hi:[0,1]
	v_pk_fma_f32 v[182:183], v[182:183], s[84:85], v[186:187] op_sel_hi:[1,0,1] neg_lo:[0,0,1]
	v_pk_mul_f32 v[180:181], v[122:123], s[90:91] op_sel:[1,1] op_sel_hi:[0,1]
	v_pk_fma_f32 v[122:123], v[122:123], s[90:91], v[180:181] op_sel_hi:[1,0,1] neg_lo:[0,0,1]
	v_pk_mul_f32 v[168:169], v[110:111], s[88:89] op_sel:[1,1] op_sel_hi:[0,1]
	v_pk_fma_f32 v[110:111], v[110:111], s[88:89], v[168:169] op_sel_hi:[1,0,1] neg_lo:[0,0,1]
	v_pk_mul_f32 v[176:177], v[128:129], s[90:91] op_sel:[1,1] op_sel_hi:[0,1]
	v_pk_fma_f32 v[128:129], v[128:129], s[90:91], v[176:177] op_sel_hi:[1,0,1] neg_lo:[0,0,1]
	v_pk_mul_f32 v[178:179], v[130:131], s[98:99] op_sel:[1,1] op_sel_hi:[0,1]
	v_pk_fma_f32 v[130:131], v[130:131], s[98:99], v[178:179] op_sel_hi:[1,0,1] neg_lo:[0,0,1]
	v_pk_add_f32 v[174:175], v[100:101], v[104:105]
	v_pk_add_f32 v[166:167], v[100:101], v[104:105] neg_lo:[0,1] neg_hi:[0,1]
	v_pk_add_f32 v[184:185], v[126:127], v[106:107]
	v_pk_add_f32 v[102:103], v[126:127], v[106:107] neg_lo:[0,1] neg_hi:[0,1]
	v_pk_add_f32 v[100:101], v[174:175], v[184:185]
	v_pk_add_f32 v[104:105], v[174:175], v[184:185] neg_lo:[0,1] neg_hi:[0,1]
	v_pk_add_f32 v[126:127], v[166:167], v[102:103] op_sel:[0,1] op_sel_hi:[1,0] neg_hi:[0,1]
	v_pk_add_f32 v[106:107], v[166:167], v[102:103] op_sel:[0,1] op_sel_hi:[1,0] neg_lo:[0,1]
	v_pk_add_f32 v[188:189], v[108:109], v[112:113]
	v_pk_add_f32 v[186:187], v[108:109], v[112:113] neg_lo:[0,1] neg_hi:[0,1]
	v_pk_add_f32 v[180:181], v[118:119], v[114:115]
	v_pk_add_f32 v[168:169], v[118:119], v[114:115] neg_lo:[0,1] neg_hi:[0,1]
	v_pk_add_f32 v[108:109], v[188:189], v[180:181]
	v_pk_add_f32 v[112:113], v[188:189], v[180:181] neg_lo:[0,1] neg_hi:[0,1]
	v_pk_add_f32 v[118:119], v[186:187], v[168:169] op_sel:[0,1] op_sel_hi:[1,0] neg_hi:[0,1]
	v_pk_add_f32 v[114:115], v[186:187], v[168:169] op_sel:[0,1] op_sel_hi:[1,0] neg_lo:[0,1]
	v_pk_add_f32 v[176:177], v[116:117], v[120:121] op_sel:[0,1] op_sel_hi:[1,0] neg_hi:[0,1]
	v_pk_add_f32 v[178:179], v[116:117], v[120:121] op_sel:[0,1] op_sel_hi:[1,0] neg_lo:[0,1]
	v_pk_add_f32 v[174:175], v[182:183], v[122:123]
	v_pk_add_f32 v[166:167], v[182:183], v[122:123] neg_lo:[0,1] neg_hi:[0,1]
	v_pk_add_f32 v[116:117], v[176:177], v[174:175]
	v_pk_add_f32 v[120:121], v[176:177], v[174:175] neg_lo:[0,1] neg_hi:[0,1]
	v_pk_add_f32 v[182:183], v[178:179], v[166:167] op_sel:[0,1] op_sel_hi:[1,0] neg_hi:[0,1]
	v_pk_add_f32 v[122:123], v[178:179], v[166:167] op_sel:[0,1] op_sel_hi:[1,0] neg_lo:[0,1]
	v_pk_add_f32 v[184:185], v[124:125], v[128:129]
	v_pk_add_f32 v[102:103], v[124:125], v[128:129] neg_lo:[0,1] neg_hi:[0,1]
	v_pk_add_f32 v[188:189], v[110:111], v[130:131]
	v_pk_add_f32 v[186:187], v[110:111], v[130:131] neg_lo:[0,1] neg_hi:[0,1]
	v_pk_add_f32 v[124:125], v[184:185], v[188:189]
	v_pk_add_f32 v[128:129], v[184:185], v[188:189] neg_lo:[0,1] neg_hi:[0,1]
	v_pk_add_f32 v[110:111], v[102:103], v[186:187] op_sel:[0,1] op_sel_hi:[1,0] neg_hi:[0,1]
	v_pk_add_f32 v[130:131], v[102:103], v[186:187] op_sel:[0,1] op_sel_hi:[1,0] neg_lo:[0,1]
	ds_write_b64 v5, v[100:101]
	ds_read_b64 v[180:181], v56 offset:256
	ds_read_b64 v[168:169], v56 offset:512
	ds_read_b64 v[176:177], v56 offset:768
	ds_read_b64 v[178:179], v56 offset:1024
	s_waitcnt lgkmcnt(3)
	v_pk_mul_f32 v[174:175], v[108:109], v[180:181] op_sel:[1,1] op_sel_hi:[0,1]
	v_pk_fma_f32 v[108:109], v[108:109], v[180:181], v[174:175] op_sel_hi:[1,0,1] neg_lo:[0,0,1]
	ds_write_b64 v5, v[108:109] offset:264
	s_waitcnt lgkmcnt(3)
	v_pk_mul_f32 v[166:167], v[116:117], v[168:169] op_sel:[1,1] op_sel_hi:[0,1]
	v_pk_fma_f32 v[116:117], v[116:117], v[168:169], v[166:167] op_sel_hi:[1,0,1] neg_lo:[0,0,1]
	ds_write_b64 v5, v[116:117] offset:528
	s_waitcnt lgkmcnt(3)
	v_pk_mul_f32 v[184:185], v[124:125], v[176:177] op_sel:[1,1] op_sel_hi:[0,1]
	v_pk_fma_f32 v[124:125], v[124:125], v[176:177], v[184:185] op_sel_hi:[1,0,1] neg_lo:[0,0,1]
	ds_write_b64 v5, v[124:125] offset:792
	s_waitcnt lgkmcnt(3)
	v_pk_mul_f32 v[102:103], v[126:127], v[178:179] op_sel:[1,1] op_sel_hi:[0,1]
	v_pk_fma_f32 v[126:127], v[126:127], v[178:179], v[102:103] op_sel_hi:[1,0,1] neg_lo:[0,0,1]
	ds_write_b64 v5, v[126:127] offset:1056
	ds_read_b64 v[188:189], v56 offset:1280
	ds_read_b64 v[186:187], v56 offset:1536
	ds_read_b64 v[174:175], v56 offset:1792
	ds_read_b64 v[166:167], v56 offset:2048
	s_waitcnt lgkmcnt(3)
	v_pk_mul_f32 v[184:185], v[118:119], v[188:189] op_sel:[1,1] op_sel_hi:[0,1]
	v_pk_fma_f32 v[118:119], v[118:119], v[188:189], v[184:185] op_sel_hi:[1,0,1] neg_lo:[0,0,1]
	ds_write_b64 v5, v[118:119] offset:1320
	s_waitcnt lgkmcnt(3)
; #define LAS __attribute__((address_space(3)))
; __device__ __forceinline__ f32x2 cmul(f32x2 a, f32x2 b) { return (f32x2){a.x * b.x - a.y * b.y, a.x * b.y + a.y * b.x}; }
; __device__ __forceinline__ void fft_fwd2(LAS f32x2* B, const LAS f32x2* TW2, int tid) {
;     asm volatile("" : "+v"(tid));
;     const int b = tid >> 5, n2 = tid & 31, base = 512 * b + n2; f32x2 x[16];
; #pragma unroll
;     for (int r = 0; r < 16; ++r) x[r] = B[fpad(base + 32 * r)];
;     dft16<false>(x);
;     B[fpad(base)] = x[0];
; #pragma unroll
;     for (int k = 1; k < 16; ++k) B[fpad(base + 32 * k)] = cmul(x[k], TW2[k * 32 + n2]);
; }
; template <int MODE> __device__ __forceinline__ void fft_pair32(LAS f32x2* B, const LAS f32x2* F, int wave, int lane) {
;     asm volatile("" : "+v"(lane));
;     constexpr float CS[16] = {1.f, 0.98078528040323043f, 0.92387953251128674f, 0.83146961230254524f, 0.70710678118654752f, 0.55557023301960218f, 0.38268343236508977f, 0.19509032201612825f,
;                               0.f, -0.19509032201612825f, -0.38268343236508977f, -0.55557023301960218f, -0.70710678118654752f, -0.83146961230254524f, -0.92387953251128674f, -0.98078528040323043f};
;     constexpr float SN[16] = {0.f, 0.19509032201612825f, 0.38268343236508977f, 0.55557023301960218f, 0.70710678118654752f, 0.83146961230254524f, 0.92387953251128674f, 0.98078528040323043f,
;                               1.f, 0.98078528040323043f, 0.92387953251128674f, 0.83146961230254524f, 0.70710678118654752f, 0.55557023301960218f, 0.38268343236508977f, 0.19509032201612825f};
;     const int hi = lane >> 5, blk = 32 * wave + (lane & 31); const float sg = hi ? -1.f : 1.f;
;     LAS f32x2* p = B + 33 * blk; f32x2 v[16];
; #pragma unroll
;     for (int j = 0; j < 16; ++j) { const f32x2 d = p[j] + p[j + 16] * sg;
;         const f32x2 w = {hi ? CS[j] : 1.f, hi ? -SN[j] : 0.f}; v[j] = j == 0 ? d : cmul(d, w); }
;     dft16<false>(v);
	v_pk_mul_f32 v[102:103], v[182:183], v[186:187] op_sel:[1,1] op_sel_hi:[0,1]
	v_pk_fma_f32 v[182:183], v[182:183], v[186:187], v[102:103] op_sel_hi:[1,0,1] neg_lo:[0,0,1]
	ds_write_b64 v5, v[182:183] offset:1584
	s_waitcnt lgkmcnt(3)
	v_pk_mul_f32 v[180:181], v[110:111], v[174:175] op_sel:[1,1] op_sel_hi:[0,1]
	v_pk_fma_f32 v[110:111], v[110:111], v[174:175], v[180:181] op_sel_hi:[1,0,1] neg_lo:[0,0,1]
	ds_write_b64 v5, v[110:111] offset:1848
	s_waitcnt lgkmcnt(3)
	v_pk_mul_f32 v[168:169], v[104:105], v[166:167] op_sel:[1,1] op_sel_hi:[0,1]
	v_pk_fma_f32 v[104:105], v[104:105], v[166:167], v[168:169] op_sel_hi:[1,0,1] neg_lo:[0,0,1]
	ds_write_b64 v5, v[104:105] offset:2112
	ds_read_b64 v[176:177], v56 offset:2304
	ds_read_b64 v[178:179], v56 offset:2560
	ds_read_b64 v[184:185], v56 offset:2816
	ds_read_b64 v[102:103], v56 offset:3072
	s_waitcnt lgkmcnt(3)
	v_pk_mul_f32 v[180:181], v[112:113], v[176:177] op_sel:[1,1] op_sel_hi:[0,1]
	v_pk_fma_f32 v[112:113], v[112:113], v[176:177], v[180:181] op_sel_hi:[1,0,1] neg_lo:[0,0,1]
	ds_write_b64 v5, v[112:113] offset:2376
	s_waitcnt lgkmcnt(3)
	v_pk_mul_f32 v[168:169], v[120:121], v[178:179] op_sel:[1,1] op_sel_hi:[0,1]
	v_pk_fma_f32 v[120:121], v[120:121], v[178:179], v[168:169] op_sel_hi:[1,0,1] neg_lo:[0,0,1]
	ds_write_b64 v5, v[120:121] offset:2640
	s_waitcnt lgkmcnt(3)
	v_pk_mul_f32 v[188:189], v[128:129], v[184:185] op_sel:[1,1] op_sel_hi:[0,1]
	v_pk_fma_f32 v[128:129], v[128:129], v[184:185], v[188:189] op_sel_hi:[1,0,1] neg_lo:[0,0,1]
	ds_write_b64 v5, v[128:129] offset:2904
	s_waitcnt lgkmcnt(3)
	v_pk_mul_f32 v[186:187], v[106:107], v[102:103] op_sel:[1,1] op_sel_hi:[0,1]
	v_pk_fma_f32 v[106:107], v[106:107], v[102:103], v[186:187] op_sel_hi:[1,0,1] neg_lo:[0,0,1]
	ds_write_b64 v5, v[106:107] offset:3168
	ds_read_b64 v[174:175], v56 offset:3328
	ds_read_b64 v[166:167], v56 offset:3584
	ds_read_b64 v[180:181], v56 offset:3840
	s_waitcnt lgkmcnt(2)
	v_pk_mul_f32 v[168:169], v[114:115], v[174:175] op_sel:[1,1] op_sel_hi:[0,1]
	v_pk_fma_f32 v[114:115], v[114:115], v[174:175], v[168:169] op_sel_hi:[1,0,1] neg_lo:[0,0,1]
	ds_write_b64 v5, v[114:115] offset:3432
	s_waitcnt lgkmcnt(2)
	v_pk_mul_f32 v[188:189], v[122:123], v[166:167] op_sel:[1,1] op_sel_hi:[0,1]
	v_pk_fma_f32 v[122:123], v[122:123], v[166:167], v[188:189] op_sel_hi:[1,0,1] neg_lo:[0,0,1]
	ds_write_b64 v5, v[122:123] offset:3696
	s_waitcnt lgkmcnt(2)
	v_pk_mul_f32 v[186:187], v[130:131], v[180:181] op_sel:[1,1] op_sel_hi:[0,1]
	v_pk_fma_f32 v[130:131], v[130:131], v[180:181], v[186:187] op_sel_hi:[1,0,1] neg_lo:[0,0,1]
	ds_write_b64 v5, v[130:131] offset:3960
	s_waitcnt lgkmcnt(0)
	ds_read_b64 v[100:101], v156
	ds_read_b64 v[176:177], v156 offset:128
	ds_read_b64 v[108:109], v156 offset:8
	ds_read_b64 v[178:179], v156 offset:136
	ds_read_b64 v[116:117], v156 offset:16
	ds_read_b64 v[184:185], v156 offset:144
	ds_read_b64 v[124:125], v156 offset:24
	ds_read_b64 v[102:103], v156 offset:152
	s_waitcnt lgkmcnt(6)
	v_pk_fma_f32 v[100:101], v[176:177], v[190:191], v[100:101] op_sel_hi:[1,0,1]
	s_waitcnt lgkmcnt(4)
	v_pk_fma_f32 v[108:109], v[178:179], v[190:191], v[108:109] op_sel_hi:[1,0,1]
	v_pk_mul_f32 v[168:169], v[108:109], v[36:37] op_sel:[1,1] op_sel_hi:[0,1]
	v_pk_fma_f32 v[108:109], v[108:109], v[36:37], v[168:169] op_sel_hi:[1,0,1] neg_lo:[0,0,1]
	s_waitcnt lgkmcnt(2)
	v_pk_fma_f32 v[116:117], v[184:185], v[190:191], v[116:117] op_sel_hi:[1,0,1]
	v_pk_mul_f32 v[188:189], v[116:117], v[38:39] op_sel:[1,1] op_sel_hi:[0,1]
	v_pk_fma_f32 v[116:117], v[116:117], v[38:39], v[188:189] op_sel_hi:[1,0,1] neg_lo:[0,0,1]
	s_waitcnt lgkmcnt(0)
	v_pk_fma_f32 v[124:125], v[102:103], v[190:191], v[124:125] op_sel_hi:[1,0,1]
	v_pk_mul_f32 v[186:187], v[124:125], v[40:41] op_sel:[1,1] op_sel_hi:[0,1]
	v_pk_fma_f32 v[124:125], v[124:125], v[40:41], v[186:187] op_sel_hi:[1,0,1] neg_lo:[0,0,1]
	ds_read_b64 v[126:127], v156 offset:32
	ds_read_b64 v[174:175], v156 offset:160
	ds_read_b64 v[118:119], v156 offset:40
	ds_read_b64 v[166:167], v156 offset:168
	ds_read_b64 v[182:183], v156 offset:48
	ds_read_b64 v[180:181], v156 offset:176
	ds_read_b64 v[110:111], v156 offset:56
	ds_read_b64 v[168:169], v156 offset:184
	s_waitcnt lgkmcnt(6)
	v_pk_fma_f32 v[126:127], v[174:175], v[190:191], v[126:127] op_sel_hi:[1,0,1]
	v_pk_mul_f32 v[188:189], v[126:127], v[42:43] op_sel:[1,1] op_sel_hi:[0,1]
	v_pk_fma_f32 v[126:127], v[126:127], v[42:43], v[188:189] op_sel_hi:[1,0,1] neg_lo:[0,0,1]
	s_waitcnt lgkmcnt(4)
	v_pk_fma_f32 v[118:119], v[166:167], v[190:191], v[118:119] op_sel_hi:[1,0,1]
	v_pk_mul_f32 v[186:187], v[118:119], v[44:45] op_sel:[1,1] op_sel_hi:[0,1]
	v_pk_fma_f32 v[118:119], v[118:119], v[44:45], v[186:187] op_sel_hi:[1,0,1] neg_lo:[0,0,1]
	s_waitcnt lgkmcnt(2)
	v_pk_fma_f32 v[182:183], v[180:181], v[190:191], v[182:183] op_sel_hi:[1,0,1]
	v_pk_mul_f32 v[176:177], v[182:183], v[46:47] op_sel:[1,1] op_sel_hi:[0,1]
	v_pk_fma_f32 v[182:183], v[182:183], v[46:47], v[176:177] op_sel_hi:[1,0,1] neg_lo:[0,0,1]
	s_waitcnt lgkmcnt(0)
	v_pk_fma_f32 v[110:111], v[168:169], v[190:191], v[110:111] op_sel_hi:[1,0,1]
	v_pk_mul_f32 v[178:179], v[110:111], v[48:49] op_sel:[1,1] op_sel_hi:[0,1]
	v_pk_fma_f32 v[110:111], v[110:111], v[48:49], v[178:179] op_sel_hi:[1,0,1] neg_lo:[0,0,1]
	ds_read_b64 v[104:105], v156 offset:64
	ds_read_b64 v[184:185], v156 offset:192
	ds_read_b64 v[112:113], v156 offset:72
	ds_read_b64 v[102:103], v156 offset:200
	ds_read_b64 v[120:121], v156 offset:80
	ds_read_b64 v[188:189], v156 offset:208
	ds_read_b64 v[128:129], v156 offset:88
	ds_read_b64 v[186:187], v156 offset:216
	s_waitcnt lgkmcnt(6)
; __device__ __forceinline__ f32x2 cmul(f32x2 a, f32x2 b) { return (f32x2){a.x * b.x - a.y * b.y, a.x * b.y + a.y * b.x}; }
; template <bool INV> __device__ __forceinline__ f32x2 cmul_tw(f32x2 a, f32x2 w) { return INV ? cmulc(a, w) : cmul(a, w); }
; template <bool INV> __device__ __forceinline__ void dft16(f32x2 (&x)[16]) {
;     constexpr float C1 = 0.92387953251128674f, S1 = 0.38268343236508977f, C2 = 0.70710678118654752f;
; #pragma unroll
;     for (int b = 0; b < 4; ++b) dft4<INV>(x[b], x[4 + b], x[8 + b], x[12 + b]);
;     const f32x2 w1 = {C1, -S1}, w2 = {C2, -C2}, w3 = {S1, -C1}, w4 = {0.f, -1.f}, w6 = {-C2, -C2}, w9 = {-C1, S1};
;     x[4 * 1 + 1] = cmul_tw<INV>(x[5], w1); x[4 * 1 + 2] = cmul_tw<INV>(x[6], w2); x[4 * 1 + 3] = cmul_tw<INV>(x[7], w3);
;     x[4 * 2 + 1] = cmul_tw<INV>(x[9], w2); x[4 * 2 + 2] = cmul_tw<INV>(x[10], w4); x[4 * 2 + 3] = cmul_tw<INV>(x[11], w6);
;     x[4 * 3 + 1] = cmul_tw<INV>(x[13], w3); x[4 * 3 + 2] = cmul_tw<INV>(x[14], w6); x[4 * 3 + 3] = cmul_tw<INV>(x[15], w9);
; #pragma unroll
;     for (int c = 0; c < 4; ++c) dft4<INV>(x[4 * c], x[4 * c + 1], x[4 * c + 2], x[4 * c + 3]);
;     f32x2 y[16];
; #pragma unroll
;     for (int k = 0; k < 16; ++k) y[k] = x[4 * (k & 3) + (k >> 2)];
; #pragma unroll
;     for (int k = 0; k < 16; ++k) x[k] = y[k];
; }
; template <int MODE> __device__ __forceinline__ void fft_pair32(LAS f32x2* B, const LAS f32x2* F, int wave, int lane) {
;     ...
;     for (int j = 0; j < 16; ++j) { const f32x2 d = p[j] + p[j + 16] * sg;
;         const f32x2 w = {hi ? CS[j] : 1.f, hi ? -SN[j] : 0.f}; v[j] = j == 0 ? d : cmul(d, w); }
;     dft16<false>(v);
	v_pk_fma_f32 v[104:105], v[184:185], v[190:191], v[104:105] op_sel_hi:[1,0,1]
	v_pk_mul_f32 v[176:177], v[104:105], v[50:51] op_sel:[1,1] op_sel_hi:[0,1]
	v_pk_fma_f32 v[104:105], v[104:105], v[50:51], v[176:177] op_sel_hi:[1,0,1] neg_lo:[0,0,1]
	s_waitcnt lgkmcnt(4)
	v_pk_fma_f32 v[112:113], v[102:103], v[190:191], v[112:113] op_sel_hi:[1,0,1]
	v_pk_mul_f32 v[178:179], v[112:113], v[52:53] op_sel:[1,1] op_sel_hi:[0,1]
	v_pk_fma_f32 v[112:113], v[112:113], v[52:53], v[178:179] op_sel_hi:[1,0,1] neg_lo:[0,0,1]
	s_waitcnt lgkmcnt(2)
	v_pk_fma_f32 v[120:121], v[188:189], v[190:191], v[120:121] op_sel_hi:[1,0,1]
	v_pk_mul_f32 v[174:175], v[120:121], v[54:55] op_sel:[1,1] op_sel_hi:[0,1]
	v_pk_fma_f32 v[120:121], v[120:121], v[54:55], v[174:175] op_sel_hi:[1,0,1] neg_lo:[0,0,1]
	s_waitcnt lgkmcnt(0)
	v_pk_fma_f32 v[128:129], v[186:187], v[190:191], v[128:129] op_sel_hi:[1,0,1]
	v_pk_mul_f32 v[166:167], v[128:129], v[90:91] op_sel:[1,1] op_sel_hi:[0,1]
	v_pk_fma_f32 v[128:129], v[128:129], v[90:91], v[166:167] op_sel_hi:[1,0,1] neg_lo:[0,0,1]
	ds_read_b64 v[106:107], v156 offset:96
	ds_read_b64 v[180:181], v156 offset:224
	ds_read_b64 v[114:115], v156 offset:104
	ds_read_b64 v[168:169], v156 offset:232
	ds_read_b64 v[122:123], v156 offset:112
	ds_read_b64 v[176:177], v156 offset:240
	ds_read_b64 v[130:131], v156 offset:120
	ds_read_b64 v[178:179], v156 offset:248
	s_waitcnt lgkmcnt(6)
	v_pk_fma_f32 v[106:107], v[180:181], v[190:191], v[106:107] op_sel_hi:[1,0,1]
	v_pk_mul_f32 v[174:175], v[106:107], v[92:93] op_sel:[1,1] op_sel_hi:[0,1]
	v_pk_fma_f32 v[106:107], v[106:107], v[92:93], v[174:175] op_sel_hi:[1,0,1] neg_lo:[0,0,1]
	s_waitcnt lgkmcnt(4)
	v_pk_fma_f32 v[114:115], v[168:169], v[190:191], v[114:115] op_sel_hi:[1,0,1]
	v_pk_mul_f32 v[166:167], v[114:115], v[94:95] op_sel:[1,1] op_sel_hi:[0,1]
	v_pk_fma_f32 v[114:115], v[114:115], v[94:95], v[166:167] op_sel_hi:[1,0,1] neg_lo:[0,0,1]
	s_waitcnt lgkmcnt(2)
	v_pk_fma_f32 v[122:123], v[176:177], v[190:191], v[122:123] op_sel_hi:[1,0,1]
	v_pk_mul_f32 v[184:185], v[122:123], v[96:97] op_sel:[1,1] op_sel_hi:[0,1]
	v_pk_fma_f32 v[122:123], v[122:123], v[96:97], v[184:185] op_sel_hi:[1,0,1] neg_lo:[0,0,1]
	s_waitcnt lgkmcnt(0)
	v_pk_fma_f32 v[130:131], v[178:179], v[190:191], v[130:131] op_sel_hi:[1,0,1]
	v_pk_mul_f32 v[102:103], v[130:131], v[98:99] op_sel:[1,1] op_sel_hi:[0,1]
	v_pk_fma_f32 v[130:131], v[130:131], v[98:99], v[102:103] op_sel_hi:[1,0,1] neg_lo:[0,0,1]
	v_pk_add_f32 v[188:189], v[100:101], v[104:105]
	v_pk_add_f32 v[186:187], v[100:101], v[104:105] neg_lo:[0,1] neg_hi:[0,1]
	v_pk_add_f32 v[174:175], v[126:127], v[106:107]
	v_pk_add_f32 v[166:167], v[126:127], v[106:107] neg_lo:[0,1] neg_hi:[0,1]
	v_pk_add_f32 v[100:101], v[188:189], v[174:175]
	v_pk_add_f32 v[104:105], v[188:189], v[174:175] neg_lo:[0,1] neg_hi:[0,1]
	v_pk_add_f32 v[126:127], v[186:187], v[166:167] op_sel:[0,1] op_sel_hi:[1,0] neg_hi:[0,1]
	v_pk_add_f32 v[106:107], v[186:187], v[166:167] op_sel:[0,1] op_sel_hi:[1,0] neg_lo:[0,1]
	v_pk_add_f32 v[184:185], v[108:109], v[112:113]
	v_pk_add_f32 v[102:103], v[108:109], v[112:113] neg_lo:[0,1] neg_hi:[0,1]
	v_pk_add_f32 v[180:181], v[118:119], v[114:115]
	v_pk_add_f32 v[168:169], v[118:119], v[114:115] neg_lo:[0,1] neg_hi:[0,1]
	v_pk_add_f32 v[108:109], v[184:185], v[180:181]
	v_pk_add_f32 v[112:113], v[184:185], v[180:181] neg_lo:[0,1] neg_hi:[0,1]
	v_pk_add_f32 v[118:119], v[102:103], v[168:169] op_sel:[0,1] op_sel_hi:[1,0] neg_hi:[0,1]
	v_pk_add_f32 v[114:115], v[102:103], v[168:169] op_sel:[0,1] op_sel_hi:[1,0] neg_lo:[0,1]
	v_pk_add_f32 v[176:177], v[116:117], v[120:121]
	v_pk_add_f32 v[178:179], v[116:117], v[120:121] neg_lo:[0,1] neg_hi:[0,1]
	v_pk_add_f32 v[188:189], v[182:183], v[122:123]
	v_pk_add_f32 v[186:187], v[182:183], v[122:123] neg_lo:[0,1] neg_hi:[0,1]
	v_pk_add_f32 v[116:117], v[176:177], v[188:189]
	v_pk_add_f32 v[120:121], v[176:177], v[188:189] neg_lo:[0,1] neg_hi:[0,1]
	v_pk_add_f32 v[182:183], v[178:179], v[186:187] op_sel:[0,1] op_sel_hi:[1,0] neg_hi:[0,1]
	v_pk_add_f32 v[122:123], v[178:179], v[186:187] op_sel:[0,1] op_sel_hi:[1,0] neg_lo:[0,1]
	v_pk_add_f32 v[174:175], v[124:125], v[128:129]
	v_pk_add_f32 v[166:167], v[124:125], v[128:129] neg_lo:[0,1] neg_hi:[0,1]
	v_pk_add_f32 v[184:185], v[110:111], v[130:131]
	v_pk_add_f32 v[102:103], v[110:111], v[130:131] neg_lo:[0,1] neg_hi:[0,1]
	v_pk_add_f32 v[124:125], v[174:175], v[184:185]
	v_pk_add_f32 v[128:129], v[174:175], v[184:185] neg_lo:[0,1] neg_hi:[0,1]
	v_pk_add_f32 v[110:111], v[166:167], v[102:103] op_sel:[0,1] op_sel_hi:[1,0] neg_hi:[0,1]
	v_pk_add_f32 v[130:131], v[166:167], v[102:103] op_sel:[0,1] op_sel_hi:[1,0] neg_lo:[0,1]
	v_pk_mul_f32 v[180:181], v[118:119], s[68:69] op_sel:[1,1] op_sel_hi:[0,1]
	v_pk_fma_f32 v[118:119], v[118:119], s[68:69], v[180:181] op_sel_hi:[1,0,1] neg_lo:[0,0,1]
	v_pk_mul_f32 v[168:169], v[182:183], s[84:85] op_sel:[1,1] op_sel_hi:[0,1]
	v_pk_fma_f32 v[182:183], v[182:183], s[84:85], v[168:169] op_sel_hi:[1,0,1] neg_lo:[0,0,1]
	v_pk_mul_f32 v[176:177], v[110:111], s[88:89] op_sel:[1,1] op_sel_hi:[0,1]
	v_pk_fma_f32 v[110:111], v[110:111], s[88:89], v[176:177] op_sel_hi:[1,0,1] neg_lo:[0,0,1]
	v_pk_mul_f32 v[178:179], v[112:113], s[84:85] op_sel:[1,1] op_sel_hi:[0,1]
	v_pk_fma_f32 v[112:113], v[112:113], s[84:85], v[178:179] op_sel_hi:[1,0,1] neg_lo:[0,0,1]
	v_pk_mul_f32 v[188:189], v[128:129], s[90:91] op_sel:[1,1] op_sel_hi:[0,1]
	v_pk_fma_f32 v[128:129], v[128:129], s[90:91], v[188:189] op_sel_hi:[1,0,1] neg_lo:[0,0,1]
	v_pk_mul_f32 v[186:187], v[114:115], s[88:89] op_sel:[1,1] op_sel_hi:[0,1]
	v_pk_fma_f32 v[114:115], v[114:115], s[88:89], v[186:187] op_sel_hi:[1,0,1] neg_lo:[0,0,1]
; #define LAS __attribute__((address_space(3)))
; __device__ __forceinline__ f32x2 cmul(f32x2 a, f32x2 b) { return (f32x2){a.x * b.x - a.y * b.y, a.x * b.y + a.y * b.x}; }
; template <bool INV> __device__ __forceinline__ f32x2 cmul_tw(f32x2 a, f32x2 w) { return INV ? cmulc(a, w) : cmul(a, w); }
; template <bool INV> __device__ __forceinline__ void dft16(f32x2 (&x)[16]) {
;     constexpr float C1 = 0.92387953251128674f, S1 = 0.38268343236508977f, C2 = 0.70710678118654752f;
; #pragma unroll
;     for (int b = 0; b < 4; ++b) dft4<INV>(x[b], x[4 + b], x[8 + b], x[12 + b]);
;     const f32x2 w1 = {C1, -S1}, w2 = {C2, -C2}, w3 = {S1, -C1}, w4 = {0.f, -1.f}, w6 = {-C2, -C2}, w9 = {-C1, S1};
;     x[4 * 1 + 1] = cmul_tw<INV>(x[5], w1); x[4 * 1 + 2] = cmul_tw<INV>(x[6], w2); x[4 * 1 + 3] = cmul_tw<INV>(x[7], w3);
;     x[4 * 2 + 1] = cmul_tw<INV>(x[9], w2); x[4 * 2 + 2] = cmul_tw<INV>(x[10], w4); x[4 * 2 + 3] = cmul_tw<INV>(x[11], w6);
;     x[4 * 3 + 1] = cmul_tw<INV>(x[13], w3); x[4 * 3 + 2] = cmul_tw<INV>(x[14], w6); x[4 * 3 + 3] = cmul_tw<INV>(x[15], w9);
; #pragma unroll
;     for (int c = 0; c < 4; ++c) dft4<INV>(x[4 * c], x[4 * c + 1], x[4 * c + 2], x[4 * c + 3]);
;     f32x2 y[16];
; #pragma unroll
;     for (int k = 0; k < 16; ++k) y[k] = x[4 * (k & 3) + (k >> 2)];
; #pragma unroll
;     for (int k = 0; k < 16; ++k) x[k] = y[k];
; }
; template <int MODE> __device__ __forceinline__ void fft_pair32(LAS f32x2* B, const LAS f32x2* F, int wave, int lane) {
;     ...
;     const int k1 = blk >> 4, k2 = blk & 15, kb1 = (16 - k1) & 15, b1 = k1 != 0 ? 1 : 0, kb2 = (16 - k2 - b1) & 15, b2 = (k2 != 0 || b1) ? 1 : 0;
;     const LAS f32x2* fa = F + 33 * blk; const LAS f32x2* fb = F + 33 * (16 * kb1 + kb2);
;     const LAS f32x2* fah = fa + hi; const LAS f32x2* fbh = fb + (1 - b2) - hi;
;     constexpr float SC = 1.0f / (2.0f * (float)FN);
; #pragma unroll
;     for (int k = 0; k < 16; ++k) { const f32x2 A = fah[2 * k]; f32x2 Bm = fbh[31 - 2 * k];
;         if (k == 0) { const f32x2 m0 = b2 ? fb[31] : fa[0]; Bm = hi ? Bm : m0; }
;         const f32x2 H = MODE == 0 ? (f32x2){(A.x + Bm.x) * SC, (A.y - Bm.y) * SC} : (f32x2){(A.y + Bm.y) * SC, (Bm.x - A.x) * SC};
;         v[k] = cmul(v[k], H); }
	v_pk_mul_f32 v[174:175], v[122:123], s[90:91] op_sel:[1,1] op_sel_hi:[0,1]
	v_pk_fma_f32 v[122:123], v[122:123], s[90:91], v[174:175] op_sel_hi:[1,0,1] neg_lo:[0,0,1]
	v_pk_mul_f32 v[166:167], v[130:131], s[98:99] op_sel:[1,1] op_sel_hi:[0,1]
	v_pk_fma_f32 v[130:131], v[130:131], s[98:99], v[166:167] op_sel_hi:[1,0,1] neg_lo:[0,0,1]
	v_pk_add_f32 v[184:185], v[100:101], v[116:117]
	v_pk_add_f32 v[102:103], v[100:101], v[116:117] neg_lo:[0,1] neg_hi:[0,1]
	v_pk_add_f32 v[180:181], v[108:109], v[124:125]
	v_pk_add_f32 v[168:169], v[108:109], v[124:125] neg_lo:[0,1] neg_hi:[0,1]
	v_pk_add_f32 v[100:101], v[184:185], v[180:181]
	v_pk_add_f32 v[116:117], v[184:185], v[180:181] neg_lo:[0,1] neg_hi:[0,1]
	v_pk_add_f32 v[108:109], v[102:103], v[168:169] op_sel:[0,1] op_sel_hi:[1,0] neg_hi:[0,1]
	v_pk_add_f32 v[124:125], v[102:103], v[168:169] op_sel:[0,1] op_sel_hi:[1,0] neg_lo:[0,1]
	v_pk_add_f32 v[176:177], v[126:127], v[182:183]
	v_pk_add_f32 v[178:179], v[126:127], v[182:183] neg_lo:[0,1] neg_hi:[0,1]
	v_pk_add_f32 v[188:189], v[118:119], v[110:111]
	v_pk_add_f32 v[186:187], v[118:119], v[110:111] neg_lo:[0,1] neg_hi:[0,1]
	v_pk_add_f32 v[126:127], v[176:177], v[188:189]
	v_pk_add_f32 v[182:183], v[176:177], v[188:189] neg_lo:[0,1] neg_hi:[0,1]
	v_pk_add_f32 v[118:119], v[178:179], v[186:187] op_sel:[0,1] op_sel_hi:[1,0] neg_hi:[0,1]
	v_pk_add_f32 v[110:111], v[178:179], v[186:187] op_sel:[0,1] op_sel_hi:[1,0] neg_lo:[0,1]
	v_pk_add_f32 v[174:175], v[104:105], v[120:121] op_sel:[0,1] op_sel_hi:[1,0] neg_hi:[0,1]
	v_pk_add_f32 v[166:167], v[104:105], v[120:121] op_sel:[0,1] op_sel_hi:[1,0] neg_lo:[0,1]
	v_pk_add_f32 v[184:185], v[112:113], v[128:129]
	v_pk_add_f32 v[102:103], v[112:113], v[128:129] neg_lo:[0,1] neg_hi:[0,1]
	v_pk_add_f32 v[104:105], v[174:175], v[184:185]
	v_pk_add_f32 v[120:121], v[174:175], v[184:185] neg_lo:[0,1] neg_hi:[0,1]
	v_pk_add_f32 v[112:113], v[166:167], v[102:103] op_sel:[0,1] op_sel_hi:[1,0] neg_hi:[0,1]
	v_pk_add_f32 v[128:129], v[166:167], v[102:103] op_sel:[0,1] op_sel_hi:[1,0] neg_lo:[0,1]
	v_pk_add_f32 v[180:181], v[106:107], v[122:123]
	v_pk_add_f32 v[168:169], v[106:107], v[122:123] neg_lo:[0,1] neg_hi:[0,1]
	v_pk_add_f32 v[176:177], v[114:115], v[130:131]
	v_pk_add_f32 v[178:179], v[114:115], v[130:131] neg_lo:[0,1] neg_hi:[0,1]
	v_pk_add_f32 v[106:107], v[180:181], v[176:177]
	v_pk_add_f32 v[122:123], v[180:181], v[176:177] neg_lo:[0,1] neg_hi:[0,1]
	v_pk_add_f32 v[114:115], v[168:169], v[178:179] op_sel:[0,1] op_sel_hi:[1,0] neg_hi:[0,1]
	v_pk_add_f32 v[130:131], v[168:169], v[178:179] op_sel:[0,1] op_sel_hi:[1,0] neg_lo:[0,1]
	ds_read_b64 v[188:189], v200
	ds_read_b64 v[184:185], v204
	ds_read_b64 v[186:187], v200 offset:16
	ds_read_b64 v[102:103], v202 offset:232
	ds_read_b64 v[174:175], v200 offset:32
	ds_read_b64 v[180:181], v202 offset:216
	ds_read_b64 v[166:167], v200 offset:48
	ds_read_b64 v[168:169], v202 offset:200
	s_waitcnt lgkmcnt(6)
	v_pk_add_f32 v[188:189], v[188:189], v[184:185] op_sel:[1,1] op_sel_hi:[0,0] neg_hi:[1,0]
	v_pk_mul_f32 v[176:177], v[100:101], v[188:189] op_sel:[1,1] op_sel_hi:[0,1]
	v_pk_fma_f32 v[100:101], v[100:101], v[188:189], v[176:177] op_sel_hi:[1,0,1] neg_lo:[0,0,1]
	s_waitcnt lgkmcnt(4)
	v_pk_add_f32 v[186:187], v[186:187], v[102:103] op_sel:[1,1] op_sel_hi:[0,0] neg_hi:[1,0]
	v_pk_mul_f32 v[178:179], v[126:127], v[186:187] op_sel:[1,1] op_sel_hi:[0,1]
	v_pk_fma_f32 v[126:127], v[126:127], v[186:187], v[178:179] op_sel_hi:[1,0,1] neg_lo:[0,0,1]
	s_waitcnt lgkmcnt(2)
	v_pk_add_f32 v[174:175], v[174:175], v[180:181] op_sel:[1,1] op_sel_hi:[0,0] neg_hi:[1,0]
	v_pk_mul_f32 v[176:177], v[104:105], v[174:175] op_sel:[1,1] op_sel_hi:[0,1]
	v_pk_fma_f32 v[104:105], v[104:105], v[174:175], v[176:177] op_sel_hi:[1,0,1] neg_lo:[0,0,1]
	s_waitcnt lgkmcnt(0)
	v_pk_add_f32 v[166:167], v[166:167], v[168:169] op_sel:[1,1] op_sel_hi:[0,0] neg_hi:[1,0]
	v_pk_mul_f32 v[178:179], v[106:107], v[166:167] op_sel:[1,1] op_sel_hi:[0,1]
	v_pk_fma_f32 v[106:107], v[106:107], v[166:167], v[178:179] op_sel_hi:[1,0,1] neg_lo:[0,0,1]
	ds_read_b64 v[176:177], v200 offset:64
	ds_read_b64 v[174:175], v202 offset:184
	ds_read_b64 v[178:179], v200 offset:80
	ds_read_b64 v[166:167], v202 offset:168
	ds_read_b64 v[188:189], v200 offset:96
	ds_read_b64 v[184:185], v202 offset:152
	ds_read_b64 v[186:187], v200 offset:112
	ds_read_b64 v[102:103], v202 offset:136
	s_waitcnt lgkmcnt(6)
	v_pk_add_f32 v[176:177], v[176:177], v[174:175] op_sel:[1,1] op_sel_hi:[0,0] neg_hi:[1,0]
	v_pk_mul_f32 v[180:181], v[108:109], v[176:177] op_sel:[1,1] op_sel_hi:[0,1]
	v_pk_fma_f32 v[108:109], v[108:109], v[176:177], v[180:181] op_sel_hi:[1,0,1] neg_lo:[0,0,1]
	s_waitcnt lgkmcnt(4)
	v_pk_add_f32 v[178:179], v[178:179], v[166:167] op_sel:[1,1] op_sel_hi:[0,0] neg_hi:[1,0]
	v_pk_mul_f32 v[168:169], v[118:119], v[178:179] op_sel:[1,1] op_sel_hi:[0,1]
	v_pk_fma_f32 v[118:119], v[118:119], v[178:179], v[168:169] op_sel_hi:[1,0,1] neg_lo:[0,0,1]
	s_waitcnt lgkmcnt(2)
	v_pk_add_f32 v[188:189], v[188:189], v[184:185] op_sel:[1,1] op_sel_hi:[0,0] neg_hi:[1,0]
	v_pk_mul_f32 v[180:181], v[112:113], v[188:189] op_sel:[1,1] op_sel_hi:[0,1]
	v_pk_fma_f32 v[112:113], v[112:113], v[188:189], v[180:181] op_sel_hi:[1,0,1] neg_lo:[0,0,1]
	s_waitcnt lgkmcnt(0)
	v_pk_add_f32 v[186:187], v[186:187], v[102:103] op_sel:[1,1] op_sel_hi:[0,0] neg_hi:[1,0]
	v_pk_mul_f32 v[168:169], v[114:115], v[186:187] op_sel:[1,1] op_sel_hi:[0,1]
	v_pk_fma_f32 v[114:115], v[114:115], v[186:187], v[168:169] op_sel_hi:[1,0,1] neg_lo:[0,0,1]
	ds_read_b64 v[180:181], v200 offset:128
	ds_read_b64 v[188:189], v202 offset:120
	ds_read_b64 v[168:169], v200 offset:144
	ds_read_b64 v[186:187], v202 offset:104
	ds_read_b64 v[176:177], v200 offset:160
	ds_read_b64 v[174:175], v202 offset:88
	ds_read_b64 v[178:179], v200 offset:176
	ds_read_b64 v[166:167], v202 offset:72
	s_waitcnt lgkmcnt(6)
; __device__ __forceinline__ f32x2 cmul(f32x2 a, f32x2 b) { return (f32x2){a.x * b.x - a.y * b.y, a.x * b.y + a.y * b.x}; }
; template <bool INV> __device__ __forceinline__ f32x2 cmul_tw(f32x2 a, f32x2 w) { return INV ? cmulc(a, w) : cmul(a, w); }
; template <bool INV> __device__ __forceinline__ void dft16(f32x2 (&x)[16]) {
;     constexpr float C1 = 0.92387953251128674f, S1 = 0.38268343236508977f, C2 = 0.70710678118654752f;
; #pragma unroll
;     for (int b = 0; b < 4; ++b) dft4<INV>(x[b], x[4 + b], x[8 + b], x[12 + b]);
;     const f32x2 w1 = {C1, -S1}, w2 = {C2, -C2}, w3 = {S1, -C1}, w4 = {0.f, -1.f}, w6 = {-C2, -C2}, w9 = {-C1, S1};
;     x[4 * 1 + 1] = cmul_tw<INV>(x[5], w1); x[4 * 1 + 2] = cmul_tw<INV>(x[6], w2); x[4 * 1 + 3] = cmul_tw<INV>(x[7], w3);
;     x[4 * 2 + 1] = cmul_tw<INV>(x[9], w2); x[4 * 2 + 2] = cmul_tw<INV>(x[10], w4); x[4 * 2 + 3] = cmul_tw<INV>(x[11], w6);
;     x[4 * 3 + 1] = cmul_tw<INV>(x[13], w3); x[4 * 3 + 2] = cmul_tw<INV>(x[14], w6); x[4 * 3 + 3] = cmul_tw<INV>(x[15], w9);
; #pragma unroll
;     for (int c = 0; c < 4; ++c) dft4<INV>(x[4 * c], x[4 * c + 1], x[4 * c + 2], x[4 * c + 3]);
;     f32x2 y[16];
; #pragma unroll
;     for (int k = 0; k < 16; ++k) y[k] = x[4 * (k & 3) + (k >> 2)];
; #pragma unroll
;     for (int k = 0; k < 16; ++k) x[k] = y[k];
; }
; template <int MODE> __device__ __forceinline__ void fft_pair32(LAS f32x2* B, const LAS f32x2* F, int wave, int lane) {
;     ...
;     for (int k = 0; k < 16; ++k) { const f32x2 A = fah[2 * k]; f32x2 Bm = fbh[31 - 2 * k];
;         if (k == 0) { const f32x2 m0 = b2 ? fb[31] : fa[0]; Bm = hi ? Bm : m0; }
;         const f32x2 H = MODE == 0 ? (f32x2){(A.x + Bm.x) * SC, (A.y - Bm.y) * SC} : (f32x2){(A.y + Bm.y) * SC, (Bm.x - A.x) * SC};
;         v[k] = cmul(v[k], H); }
;     dft16<true>(v);
	v_pk_add_f32 v[180:181], v[180:181], v[188:189] op_sel:[1,1] op_sel_hi:[0,0] neg_hi:[1,0]
	v_pk_mul_f32 v[184:185], v[116:117], v[180:181] op_sel:[1,1] op_sel_hi:[0,1]
	v_pk_fma_f32 v[116:117], v[116:117], v[180:181], v[184:185] op_sel_hi:[1,0,1] neg_lo:[0,0,1]
	s_waitcnt lgkmcnt(4)
	v_pk_add_f32 v[168:169], v[168:169], v[186:187] op_sel:[1,1] op_sel_hi:[0,0] neg_hi:[1,0]
	v_pk_mul_f32 v[102:103], v[182:183], v[168:169] op_sel:[1,1] op_sel_hi:[0,1]
	v_pk_fma_f32 v[182:183], v[182:183], v[168:169], v[102:103] op_sel_hi:[1,0,1] neg_lo:[0,0,1]
	s_waitcnt lgkmcnt(2)
	v_pk_add_f32 v[176:177], v[176:177], v[174:175] op_sel:[1,1] op_sel_hi:[0,0] neg_hi:[1,0]
	v_pk_mul_f32 v[184:185], v[120:121], v[176:177] op_sel:[1,1] op_sel_hi:[0,1]
	v_pk_fma_f32 v[120:121], v[120:121], v[176:177], v[184:185] op_sel_hi:[1,0,1] neg_lo:[0,0,1]
	s_waitcnt lgkmcnt(0)
	v_pk_add_f32 v[178:179], v[178:179], v[166:167] op_sel:[1,1] op_sel_hi:[0,0] neg_hi:[1,0]
	v_pk_mul_f32 v[102:103], v[122:123], v[178:179] op_sel:[1,1] op_sel_hi:[0,1]
	v_pk_fma_f32 v[122:123], v[122:123], v[178:179], v[102:103] op_sel_hi:[1,0,1] neg_lo:[0,0,1]
	ds_read_b64 v[184:185], v200 offset:192
	ds_read_b64 v[176:177], v202 offset:56
	ds_read_b64 v[102:103], v200 offset:208
	ds_read_b64 v[178:179], v202 offset:40
	ds_read_b64 v[180:181], v200 offset:224
	ds_read_b64 v[188:189], v202 offset:24
	ds_read_b64 v[168:169], v200 offset:240
	ds_read_b64 v[186:187], v202 offset:8
	s_waitcnt lgkmcnt(6)
	v_pk_add_f32 v[184:185], v[184:185], v[176:177] op_sel:[1,1] op_sel_hi:[0,0] neg_hi:[1,0]
	v_pk_mul_f32 v[174:175], v[124:125], v[184:185] op_sel:[1,1] op_sel_hi:[0,1]
	v_pk_fma_f32 v[124:125], v[124:125], v[184:185], v[174:175] op_sel_hi:[1,0,1] neg_lo:[0,0,1]
	s_waitcnt lgkmcnt(4)
	v_pk_add_f32 v[102:103], v[102:103], v[178:179] op_sel:[1,1] op_sel_hi:[0,0] neg_hi:[1,0]
	v_pk_mul_f32 v[166:167], v[110:111], v[102:103] op_sel:[1,1] op_sel_hi:[0,1]
	v_pk_fma_f32 v[110:111], v[110:111], v[102:103], v[166:167] op_sel_hi:[1,0,1] neg_lo:[0,0,1]
	s_waitcnt lgkmcnt(2)
	v_pk_add_f32 v[180:181], v[180:181], v[188:189] op_sel:[1,1] op_sel_hi:[0,0] neg_hi:[1,0]
	v_pk_mul_f32 v[174:175], v[128:129], v[180:181] op_sel:[1,1] op_sel_hi:[0,1]
	v_pk_fma_f32 v[128:129], v[128:129], v[180:181], v[174:175] op_sel_hi:[1,0,1] neg_lo:[0,0,1]
	s_waitcnt lgkmcnt(0)
	v_pk_add_f32 v[168:169], v[168:169], v[186:187] op_sel:[1,1] op_sel_hi:[0,0] neg_hi:[1,0]
	v_pk_mul_f32 v[166:167], v[130:131], v[168:169] op_sel:[1,1] op_sel_hi:[0,1]
	v_pk_fma_f32 v[130:131], v[130:131], v[168:169], v[166:167] op_sel_hi:[1,0,1] neg_lo:[0,0,1]
	v_pk_add_f32 v[174:175], v[100:101], v[116:117]
	v_pk_add_f32 v[166:167], v[100:101], v[116:117] neg_lo:[0,1] neg_hi:[0,1]
	v_pk_add_f32 v[184:185], v[108:109], v[124:125]
	v_pk_add_f32 v[102:103], v[108:109], v[124:125] neg_lo:[0,1] neg_hi:[0,1]
	v_pk_add_f32 v[100:101], v[174:175], v[184:185]
	v_pk_add_f32 v[116:117], v[174:175], v[184:185] neg_lo:[0,1] neg_hi:[0,1]
	v_pk_add_f32 v[108:109], v[166:167], v[102:103] op_sel:[0,1] op_sel_hi:[1,0] neg_lo:[0,1]
	v_pk_add_f32 v[124:125], v[166:167], v[102:103] op_sel:[0,1] op_sel_hi:[1,0] neg_hi:[0,1]
	v_pk_add_f32 v[180:181], v[126:127], v[182:183]
	v_pk_add_f32 v[168:169], v[126:127], v[182:183] neg_lo:[0,1] neg_hi:[0,1]
	v_pk_add_f32 v[176:177], v[118:119], v[110:111]
	v_pk_add_f32 v[178:179], v[118:119], v[110:111] neg_lo:[0,1] neg_hi:[0,1]
	v_pk_add_f32 v[126:127], v[180:181], v[176:177]
	v_pk_add_f32 v[182:183], v[180:181], v[176:177] neg_lo:[0,1] neg_hi:[0,1]
	v_pk_add_f32 v[118:119], v[168:169], v[178:179] op_sel:[0,1] op_sel_hi:[1,0] neg_lo:[0,1]
	v_pk_add_f32 v[110:111], v[168:169], v[178:179] op_sel:[0,1] op_sel_hi:[1,0] neg_hi:[0,1]
	v_pk_add_f32 v[188:189], v[104:105], v[120:121]
	v_pk_add_f32 v[186:187], v[104:105], v[120:121] neg_lo:[0,1] neg_hi:[0,1]
	v_pk_add_f32 v[174:175], v[112:113], v[128:129]
	v_pk_add_f32 v[166:167], v[112:113], v[128:129] neg_lo:[0,1] neg_hi:[0,1]
	v_pk_add_f32 v[104:105], v[188:189], v[174:175]
	v_pk_add_f32 v[120:121], v[188:189], v[174:175] neg_lo:[0,1] neg_hi:[0,1]
	v_pk_add_f32 v[112:113], v[186:187], v[166:167] op_sel:[0,1] op_sel_hi:[1,0] neg_lo:[0,1]
	v_pk_add_f32 v[128:129], v[186:187], v[166:167] op_sel:[0,1] op_sel_hi:[1,0] neg_hi:[0,1]
	v_pk_add_f32 v[184:185], v[106:107], v[122:123]
	v_pk_add_f32 v[102:103], v[106:107], v[122:123] neg_lo:[0,1] neg_hi:[0,1]
	v_pk_add_f32 v[180:181], v[114:115], v[130:131]
	v_pk_add_f32 v[168:169], v[114:115], v[130:131] neg_lo:[0,1] neg_hi:[0,1]
	v_pk_add_f32 v[106:107], v[184:185], v[180:181]
	v_pk_add_f32 v[122:123], v[184:185], v[180:181] neg_lo:[0,1] neg_hi:[0,1]
	v_pk_add_f32 v[114:115], v[102:103], v[168:169] op_sel:[0,1] op_sel_hi:[1,0] neg_lo:[0,1]
	v_pk_add_f32 v[130:131], v[102:103], v[168:169] op_sel:[0,1] op_sel_hi:[1,0] neg_hi:[0,1]
	v_pk_mul_f32 v[176:177], v[118:119], s[68:69] op_sel:[1,1] op_sel_hi:[0,1]
	v_pk_fma_f32 v[118:119], v[118:119], s[68:69], v[176:177] op_sel_hi:[1,0,1] neg_hi:[0,0,1]
	v_pk_mul_f32 v[178:179], v[112:113], s[84:85] op_sel:[1,1] op_sel_hi:[0,1]
	v_pk_fma_f32 v[112:113], v[112:113], s[84:85], v[178:179] op_sel_hi:[1,0,1] neg_hi:[0,0,1]
	v_pk_mul_f32 v[188:189], v[114:115], s[88:89] op_sel:[1,1] op_sel_hi:[0,1]
	v_pk_fma_f32 v[114:115], v[114:115], s[88:89], v[188:189] op_sel_hi:[1,0,1] neg_hi:[0,0,1]
	v_pk_mul_f32 v[186:187], v[182:183], s[84:85] op_sel:[1,1] op_sel_hi:[0,1]
	v_pk_fma_f32 v[182:183], v[182:183], s[84:85], v[186:187] op_sel_hi:[1,0,1] neg_hi:[0,0,1]
	v_pk_mul_f32 v[174:175], v[122:123], s[90:91] op_sel:[1,1] op_sel_hi:[0,1]
	v_pk_fma_f32 v[122:123], v[122:123], s[90:91], v[174:175] op_sel_hi:[1,0,1] neg_hi:[0,0,1]
; __device__ __forceinline__ f32x2 cmulc(f32x2 a, f32x2 b) { return (f32x2){a.x * b.x + a.y * b.y, a.y * b.x - a.x * b.y}; }
; template <bool INV> __device__ __forceinline__ f32x2 cmul_tw(f32x2 a, f32x2 w) { return INV ? cmulc(a, w) : cmul(a, w); }
; template <bool INV> __device__ __forceinline__ void dft16(f32x2 (&x)[16]) {
;     constexpr float C1 = 0.92387953251128674f, S1 = 0.38268343236508977f, C2 = 0.70710678118654752f;
; #pragma unroll
;     for (int b = 0; b < 4; ++b) dft4<INV>(x[b], x[4 + b], x[8 + b], x[12 + b]);
;     const f32x2 w1 = {C1, -S1}, w2 = {C2, -C2}, w3 = {S1, -C1}, w4 = {0.f, -1.f}, w6 = {-C2, -C2}, w9 = {-C1, S1};
;     x[4 * 1 + 1] = cmul_tw<INV>(x[5], w1); x[4 * 1 + 2] = cmul_tw<INV>(x[6], w2); x[4 * 1 + 3] = cmul_tw<INV>(x[7], w3);
;     x[4 * 2 + 1] = cmul_tw<INV>(x[9], w2); x[4 * 2 + 2] = cmul_tw<INV>(x[10], w4); x[4 * 2 + 3] = cmul_tw<INV>(x[11], w6);
;     x[4 * 3 + 1] = cmul_tw<INV>(x[13], w3); x[4 * 3 + 2] = cmul_tw<INV>(x[14], w6); x[4 * 3 + 3] = cmul_tw<INV>(x[15], w9);
; #pragma unroll
;     for (int c = 0; c < 4; ++c) dft4<INV>(x[4 * c], x[4 * c + 1], x[4 * c + 2], x[4 * c + 3]);
;     f32x2 y[16];
; #pragma unroll
;     for (int k = 0; k < 16; ++k) y[k] = x[4 * (k & 3) + (k >> 2)];
; #pragma unroll
;     for (int k = 0; k < 16; ++k) x[k] = y[k];
; }
; template <int MODE> __device__ __forceinline__ void fft_pair32(LAS f32x2* B, const LAS f32x2* F, int wave, int lane) {
;     ...
;     dft16<true>(v);
; #pragma unroll
;     for (int j = 0; j < 16; ++j) { const f32x2 w = {hi ? CS[j] : 1.f, hi ? -SN[j] : 0.f}; const f32x2 u = j == 0 ? v[j] : cmulc(v[j], w);
;         const auto rx = __builtin_amdgcn_permlane32_swap(__float_as_uint(u.x), __float_as_uint(u.x), false, false);
;         const auto ry = __builtin_amdgcn_permlane32_swap(__float_as_uint(u.y), __float_as_uint(u.y), false, false);
;         const f32x2 a = {__uint_as_float(rx[0]), __uint_as_float(ry[0])}, b = {__uint_as_float(rx[1]), __uint_as_float(ry[1])};
;         p[16 * hi + j] = a + b * sg; }
	v_pk_mul_f32 v[166:167], v[110:111], s[88:89] op_sel:[1,1] op_sel_hi:[0,1]
	v_pk_fma_f32 v[110:111], v[110:111], s[88:89], v[166:167] op_sel_hi:[1,0,1] neg_hi:[0,0,1]
	v_pk_mul_f32 v[184:185], v[128:129], s[90:91] op_sel:[1,1] op_sel_hi:[0,1]
	v_pk_fma_f32 v[128:129], v[128:129], s[90:91], v[184:185] op_sel_hi:[1,0,1] neg_hi:[0,0,1]
	v_pk_mul_f32 v[102:103], v[130:131], s[98:99] op_sel:[1,1] op_sel_hi:[0,1]
	v_pk_fma_f32 v[130:131], v[130:131], s[98:99], v[102:103] op_sel_hi:[1,0,1] neg_hi:[0,0,1]
	v_pk_add_f32 v[180:181], v[100:101], v[104:105]
	v_pk_add_f32 v[168:169], v[100:101], v[104:105] neg_lo:[0,1] neg_hi:[0,1]
	v_pk_add_f32 v[176:177], v[126:127], v[106:107]
	v_pk_add_f32 v[178:179], v[126:127], v[106:107] neg_lo:[0,1] neg_hi:[0,1]
	v_pk_add_f32 v[100:101], v[180:181], v[176:177]
	v_pk_add_f32 v[104:105], v[180:181], v[176:177] neg_lo:[0,1] neg_hi:[0,1]
	v_pk_add_f32 v[126:127], v[168:169], v[178:179] op_sel:[0,1] op_sel_hi:[1,0] neg_lo:[0,1]
	v_pk_add_f32 v[106:107], v[168:169], v[178:179] op_sel:[0,1] op_sel_hi:[1,0] neg_hi:[0,1]
	v_pk_add_f32 v[188:189], v[108:109], v[112:113]
	v_pk_add_f32 v[186:187], v[108:109], v[112:113] neg_lo:[0,1] neg_hi:[0,1]
	v_pk_add_f32 v[174:175], v[118:119], v[114:115]
	v_pk_add_f32 v[166:167], v[118:119], v[114:115] neg_lo:[0,1] neg_hi:[0,1]
	v_pk_add_f32 v[108:109], v[188:189], v[174:175]
	v_pk_add_f32 v[112:113], v[188:189], v[174:175] neg_lo:[0,1] neg_hi:[0,1]
	v_pk_add_f32 v[118:119], v[186:187], v[166:167] op_sel:[0,1] op_sel_hi:[1,0] neg_lo:[0,1]
	v_pk_add_f32 v[114:115], v[186:187], v[166:167] op_sel:[0,1] op_sel_hi:[1,0] neg_hi:[0,1]
	v_pk_add_f32 v[184:185], v[116:117], v[120:121] op_sel:[0,1] op_sel_hi:[1,0] neg_lo:[0,1]
	v_pk_add_f32 v[102:103], v[116:117], v[120:121] op_sel:[0,1] op_sel_hi:[1,0] neg_hi:[0,1]
	v_pk_add_f32 v[180:181], v[182:183], v[122:123]
	v_pk_add_f32 v[168:169], v[182:183], v[122:123] neg_lo:[0,1] neg_hi:[0,1]
	v_pk_add_f32 v[116:117], v[184:185], v[180:181]
	v_pk_add_f32 v[120:121], v[184:185], v[180:181] neg_lo:[0,1] neg_hi:[0,1]
	v_pk_add_f32 v[182:183], v[102:103], v[168:169] op_sel:[0,1] op_sel_hi:[1,0] neg_lo:[0,1]
	v_pk_add_f32 v[122:123], v[102:103], v[168:169] op_sel:[0,1] op_sel_hi:[1,0] neg_hi:[0,1]
	v_pk_add_f32 v[176:177], v[124:125], v[128:129]
	v_pk_add_f32 v[178:179], v[124:125], v[128:129] neg_lo:[0,1] neg_hi:[0,1]
	v_pk_add_f32 v[188:189], v[110:111], v[130:131]
	v_pk_add_f32 v[186:187], v[110:111], v[130:131] neg_lo:[0,1] neg_hi:[0,1]
	v_pk_add_f32 v[124:125], v[176:177], v[188:189]
	v_pk_add_f32 v[128:129], v[176:177], v[188:189] neg_lo:[0,1] neg_hi:[0,1]
	v_pk_add_f32 v[110:111], v[178:179], v[186:187] op_sel:[0,1] op_sel_hi:[1,0] neg_lo:[0,1]
	v_pk_add_f32 v[130:131], v[178:179], v[186:187] op_sel:[0,1] op_sel_hi:[1,0] neg_hi:[0,1]
	v_mov_b32_e32 v174, v100
	v_mov_b32_e32 v175, v101
	v_pk_mul_f32 v[180:181], v[108:109], v[36:37] op_sel:[1,1] op_sel_hi:[0,1]
	v_pk_fma_f32 v[166:167], v[108:109], v[36:37], v[180:181] op_sel_hi:[1,0,1] neg_hi:[0,0,1]
	v_pk_fma_f32 v[108:109], v[108:109], v[36:37], v[180:181] op_sel_hi:[1,0,1] neg_hi:[0,0,1]
	v_pk_mul_f32 v[168:169], v[116:117], v[38:39] op_sel:[1,1] op_sel_hi:[0,1]
	v_pk_fma_f32 v[184:185], v[116:117], v[38:39], v[168:169] op_sel_hi:[1,0,1] neg_hi:[0,0,1]
	v_pk_fma_f32 v[116:117], v[116:117], v[38:39], v[168:169] op_sel_hi:[1,0,1] neg_hi:[0,0,1]
	v_pk_mul_f32 v[176:177], v[124:125], v[40:41] op_sel:[1,1] op_sel_hi:[0,1]
	v_pk_fma_f32 v[102:103], v[124:125], v[40:41], v[176:177] op_sel_hi:[1,0,1] neg_hi:[0,0,1]
	v_pk_fma_f32 v[124:125], v[124:125], v[40:41], v[176:177] op_sel_hi:[1,0,1] neg_hi:[0,0,1]
	s_nop 1
	v_permlane32_swap_b32_e32 v100, v174
	v_permlane32_swap_b32_e32 v101, v175
	v_permlane32_swap_b32_e32 v108, v166
	v_permlane32_swap_b32_e32 v109, v167
	v_permlane32_swap_b32_e32 v116, v184
	v_permlane32_swap_b32_e32 v117, v185
	v_permlane32_swap_b32_e32 v124, v102
	v_permlane32_swap_b32_e32 v125, v103
	v_pk_fma_f32 v[100:101], v[174:175], v[190:191], v[100:101] op_sel_hi:[1,0,1]
	ds_write_b64 v198, v[100:101]
	v_pk_fma_f32 v[108:109], v[166:167], v[190:191], v[108:109] op_sel_hi:[1,0,1]
	ds_write_b64 v198, v[108:109] offset:8
	v_pk_fma_f32 v[116:117], v[184:185], v[190:191], v[116:117] op_sel_hi:[1,0,1]
	ds_write_b64 v198, v[116:117] offset:16
	v_pk_fma_f32 v[124:125], v[102:103], v[190:191], v[124:125] op_sel_hi:[1,0,1]
	ds_write_b64 v198, v[124:125] offset:24
	v_pk_mul_f32 v[168:169], v[126:127], v[42:43] op_sel:[1,1] op_sel_hi:[0,1]
	v_pk_fma_f32 v[178:179], v[126:127], v[42:43], v[168:169] op_sel_hi:[1,0,1] neg_hi:[0,0,1]
	v_pk_fma_f32 v[126:127], v[126:127], v[42:43], v[168:169] op_sel_hi:[1,0,1] neg_hi:[0,0,1]
	v_pk_mul_f32 v[176:177], v[118:119], v[44:45] op_sel:[1,1] op_sel_hi:[0,1]
	v_pk_fma_f32 v[188:189], v[118:119], v[44:45], v[176:177] op_sel_hi:[1,0,1] neg_hi:[0,0,1]
	v_pk_fma_f32 v[118:119], v[118:119], v[44:45], v[176:177] op_sel_hi:[1,0,1] neg_hi:[0,0,1]
	v_pk_mul_f32 v[174:175], v[182:183], v[46:47] op_sel:[1,1] op_sel_hi:[0,1]
	v_pk_fma_f32 v[186:187], v[182:183], v[46:47], v[174:175] op_sel_hi:[1,0,1] neg_hi:[0,0,1]
	v_pk_fma_f32 v[182:183], v[182:183], v[46:47], v[174:175] op_sel_hi:[1,0,1] neg_hi:[0,0,1]
	v_pk_mul_f32 v[166:167], v[110:111], v[48:49] op_sel:[1,1] op_sel_hi:[0,1]
	v_pk_fma_f32 v[180:181], v[110:111], v[48:49], v[166:167] op_sel_hi:[1,0,1] neg_hi:[0,0,1]
	v_pk_fma_f32 v[110:111], v[110:111], v[48:49], v[166:167] op_sel_hi:[1,0,1] neg_hi:[0,0,1]
	s_nop 1
	v_permlane32_swap_b32_e32 v126, v178
	v_permlane32_swap_b32_e32 v127, v179
	v_permlane32_swap_b32_e32 v118, v188
	v_permlane32_swap_b32_e32 v119, v189
	v_permlane32_swap_b32_e32 v182, v186
; #define LAS __attribute__((address_space(3)))
; __device__ __forceinline__ f32x2 cmulc(f32x2 a, f32x2 b) { return (f32x2){a.x * b.x + a.y * b.y, a.y * b.x - a.x * b.y}; }
; __device__ __forceinline__ void fft_inv2(LAS f32x2* B, const LAS f32x2* TW2, int tid) {
;     asm volatile("" : "+v"(tid));
;     const int b = tid >> 5, n2 = tid & 31, base = 512 * b + n2; f32x2 x[16];
;     x[0] = B[fpad(base)];
; #pragma unroll
;     for (int k = 1; k < 16; ++k) x[k] = cmulc(B[fpad(base + 32 * k)], TW2[k * 32 + n2]);
;     dft16<true>(x);
; #pragma unroll
;     for (int r = 0; r < 16; ++r) B[fpad(base + 32 * r)] = x[r];
; }
; template <int MODE> __device__ __forceinline__ void fft_pair32(LAS f32x2* B, const LAS f32x2* F, int wave, int lane) {
;     ...
;     for (int j = 0; j < 16; ++j) { const f32x2 w = {hi ? CS[j] : 1.f, hi ? -SN[j] : 0.f}; const f32x2 u = j == 0 ? v[j] : cmulc(v[j], w);
;         const auto rx = __builtin_amdgcn_permlane32_swap(__float_as_uint(u.x), __float_as_uint(u.x), false, false);
;         const auto ry = __builtin_amdgcn_permlane32_swap(__float_as_uint(u.y), __float_as_uint(u.y), false, false);
;         const f32x2 a = {__uint_as_float(rx[0]), __uint_as_float(ry[0])}, b = {__uint_as_float(rx[1]), __uint_as_float(ry[1])};
;         p[16 * hi + j] = a + b * sg; }
	v_permlane32_swap_b32_e32 v183, v187
	v_permlane32_swap_b32_e32 v110, v180
	v_permlane32_swap_b32_e32 v111, v181
	v_pk_fma_f32 v[126:127], v[178:179], v[190:191], v[126:127] op_sel_hi:[1,0,1]
	ds_write_b64 v198, v[126:127] offset:32
	v_pk_fma_f32 v[118:119], v[188:189], v[190:191], v[118:119] op_sel_hi:[1,0,1]
	ds_write_b64 v198, v[118:119] offset:40
	v_pk_fma_f32 v[182:183], v[186:187], v[190:191], v[182:183] op_sel_hi:[1,0,1]
	ds_write_b64 v198, v[182:183] offset:48
	v_pk_fma_f32 v[110:111], v[180:181], v[190:191], v[110:111] op_sel_hi:[1,0,1]
	ds_write_b64 v198, v[110:111] offset:56
	v_pk_mul_f32 v[174:175], v[104:105], v[50:51] op_sel:[1,1] op_sel_hi:[0,1]
	v_pk_fma_f32 v[184:185], v[104:105], v[50:51], v[174:175] op_sel_hi:[1,0,1] neg_hi:[0,0,1]
	v_pk_fma_f32 v[104:105], v[104:105], v[50:51], v[174:175] op_sel_hi:[1,0,1] neg_hi:[0,0,1]
	v_pk_mul_f32 v[166:167], v[112:113], v[52:53] op_sel:[1,1] op_sel_hi:[0,1]
	v_pk_fma_f32 v[102:103], v[112:113], v[52:53], v[166:167] op_sel_hi:[1,0,1] neg_hi:[0,0,1]
	v_pk_fma_f32 v[112:113], v[112:113], v[52:53], v[166:167] op_sel_hi:[1,0,1] neg_hi:[0,0,1]
	v_pk_mul_f32 v[178:179], v[120:121], v[54:55] op_sel:[1,1] op_sel_hi:[0,1]
	v_pk_fma_f32 v[168:169], v[120:121], v[54:55], v[178:179] op_sel_hi:[1,0,1] neg_hi:[0,0,1]
	v_pk_fma_f32 v[120:121], v[120:121], v[54:55], v[178:179] op_sel_hi:[1,0,1] neg_hi:[0,0,1]
	v_pk_mul_f32 v[188:189], v[128:129], v[90:91] op_sel:[1,1] op_sel_hi:[0,1]
	v_pk_fma_f32 v[176:177], v[128:129], v[90:91], v[188:189] op_sel_hi:[1,0,1] neg_hi:[0,0,1]
	v_pk_fma_f32 v[128:129], v[128:129], v[90:91], v[188:189] op_sel_hi:[1,0,1] neg_hi:[0,0,1]
	s_nop 1
	v_permlane32_swap_b32_e32 v104, v184
	v_permlane32_swap_b32_e32 v105, v185
	v_permlane32_swap_b32_e32 v112, v102
	v_permlane32_swap_b32_e32 v113, v103
	v_permlane32_swap_b32_e32 v120, v168
	v_permlane32_swap_b32_e32 v121, v169
	v_permlane32_swap_b32_e32 v128, v176
	v_permlane32_swap_b32_e32 v129, v177
	v_pk_fma_f32 v[104:105], v[184:185], v[190:191], v[104:105] op_sel_hi:[1,0,1]
	ds_write_b64 v198, v[104:105] offset:64
	v_pk_fma_f32 v[112:113], v[102:103], v[190:191], v[112:113] op_sel_hi:[1,0,1]
	ds_write_b64 v198, v[112:113] offset:72
	v_pk_fma_f32 v[120:121], v[168:169], v[190:191], v[120:121] op_sel_hi:[1,0,1]
	ds_write_b64 v198, v[120:121] offset:80
	v_pk_fma_f32 v[128:129], v[176:177], v[190:191], v[128:129] op_sel_hi:[1,0,1]
	ds_write_b64 v198, v[128:129] offset:88
	v_pk_mul_f32 v[178:179], v[106:107], v[92:93] op_sel:[1,1] op_sel_hi:[0,1]
	v_pk_fma_f32 v[186:187], v[106:107], v[92:93], v[178:179] op_sel_hi:[1,0,1] neg_hi:[0,0,1]
	v_pk_fma_f32 v[106:107], v[106:107], v[92:93], v[178:179] op_sel_hi:[1,0,1] neg_hi:[0,0,1]
	v_pk_mul_f32 v[188:189], v[114:115], v[94:95] op_sel:[1,1] op_sel_hi:[0,1]
	v_pk_fma_f32 v[180:181], v[114:115], v[94:95], v[188:189] op_sel_hi:[1,0,1] neg_hi:[0,0,1]
	v_pk_fma_f32 v[114:115], v[114:115], v[94:95], v[188:189] op_sel_hi:[1,0,1] neg_hi:[0,0,1]
	v_pk_mul_f32 v[184:185], v[122:123], v[96:97] op_sel:[1,1] op_sel_hi:[0,1]
	v_pk_fma_f32 v[174:175], v[122:123], v[96:97], v[184:185] op_sel_hi:[1,0,1] neg_hi:[0,0,1]
	v_pk_fma_f32 v[122:123], v[122:123], v[96:97], v[184:185] op_sel_hi:[1,0,1] neg_hi:[0,0,1]
	v_pk_mul_f32 v[102:103], v[130:131], v[98:99] op_sel:[1,1] op_sel_hi:[0,1]
	v_pk_fma_f32 v[166:167], v[130:131], v[98:99], v[102:103] op_sel_hi:[1,0,1] neg_hi:[0,0,1]
	v_pk_fma_f32 v[130:131], v[130:131], v[98:99], v[102:103] op_sel_hi:[1,0,1] neg_hi:[0,0,1]
	s_nop 1
	v_permlane32_swap_b32_e32 v106, v186
	v_permlane32_swap_b32_e32 v107, v187
	v_permlane32_swap_b32_e32 v114, v180
	v_permlane32_swap_b32_e32 v115, v181
	v_permlane32_swap_b32_e32 v122, v174
	v_permlane32_swap_b32_e32 v123, v175
	v_permlane32_swap_b32_e32 v130, v166
	v_permlane32_swap_b32_e32 v131, v167
	v_pk_fma_f32 v[106:107], v[186:187], v[190:191], v[106:107] op_sel_hi:[1,0,1]
	ds_write_b64 v198, v[106:107] offset:96
	v_pk_fma_f32 v[114:115], v[180:181], v[190:191], v[114:115] op_sel_hi:[1,0,1]
	ds_write_b64 v198, v[114:115] offset:104
	v_pk_fma_f32 v[122:123], v[174:175], v[190:191], v[122:123] op_sel_hi:[1,0,1]
	ds_write_b64 v198, v[122:123] offset:112
	v_pk_fma_f32 v[130:131], v[166:167], v[190:191], v[130:131] op_sel_hi:[1,0,1]
	ds_write_b64 v198, v[130:131] offset:120
	s_waitcnt lgkmcnt(0)
	ds_read_b64 v[100:101], v5
	ds_read_b64 v[108:109], v5 offset:264
	ds_read_b64 v[168:169], v56 offset:256
	ds_read_b64 v[116:117], v5 offset:528
	ds_read_b64 v[176:177], v56 offset:512
	ds_read_b64 v[124:125], v5 offset:792
	ds_read_b64 v[178:179], v56 offset:768
	ds_read_b64 v[126:127], v5 offset:1056
	ds_read_b64 v[188:189], v56 offset:1024
	ds_read_b64 v[118:119], v5 offset:1320
	ds_read_b64 v[184:185], v56 offset:1280
	s_waitcnt lgkmcnt(8)
	v_pk_mul_f32 v[102:103], v[108:109], v[168:169] op_sel:[1,1] op_sel_hi:[0,1]
	v_pk_fma_f32 v[108:109], v[108:109], v[168:169], v[102:103] op_sel_hi:[1,0,1] neg_hi:[0,0,1]
	s_waitcnt lgkmcnt(6)
	v_pk_mul_f32 v[186:187], v[116:117], v[176:177] op_sel:[1,1] op_sel_hi:[0,1]
	v_pk_fma_f32 v[116:117], v[116:117], v[176:177], v[186:187] op_sel_hi:[1,0,1] neg_hi:[0,0,1]
	s_waitcnt lgkmcnt(4)
	v_pk_mul_f32 v[180:181], v[124:125], v[178:179] op_sel:[1,1] op_sel_hi:[0,1]
	v_pk_fma_f32 v[124:125], v[124:125], v[178:179], v[180:181] op_sel_hi:[1,0,1] neg_hi:[0,0,1]
	s_waitcnt lgkmcnt(2)
	v_pk_mul_f32 v[174:175], v[126:127], v[188:189] op_sel:[1,1] op_sel_hi:[0,1]
	v_pk_fma_f32 v[126:127], v[126:127], v[188:189], v[174:175] op_sel_hi:[1,0,1] neg_hi:[0,0,1]
	s_waitcnt lgkmcnt(0)
; #define LAS __attribute__((address_space(3)))
; __device__ __forceinline__ f32x2 cmulc(f32x2 a, f32x2 b) { return (f32x2){a.x * b.x + a.y * b.y, a.y * b.x - a.x * b.y}; }
; template <bool INV> __device__ __forceinline__ f32x2 cmul_tw(f32x2 a, f32x2 w) { return INV ? cmulc(a, w) : cmul(a, w); }
; template <bool INV> __device__ __forceinline__ void dft16(f32x2 (&x)[16]) {
;     constexpr float C1 = 0.92387953251128674f, S1 = 0.38268343236508977f, C2 = 0.70710678118654752f;
; #pragma unroll
;     for (int b = 0; b < 4; ++b) dft4<INV>(x[b], x[4 + b], x[8 + b], x[12 + b]);
;     const f32x2 w1 = {C1, -S1}, w2 = {C2, -C2}, w3 = {S1, -C1}, w4 = {0.f, -1.f}, w6 = {-C2, -C2}, w9 = {-C1, S1};
;     x[4 * 1 + 1] = cmul_tw<INV>(x[5], w1); x[4 * 1 + 2] = cmul_tw<INV>(x[6], w2); x[4 * 1 + 3] = cmul_tw<INV>(x[7], w3);
;     x[4 * 2 + 1] = cmul_tw<INV>(x[9], w2); x[4 * 2 + 2] = cmul_tw<INV>(x[10], w4); x[4 * 2 + 3] = cmul_tw<INV>(x[11], w6);
;     x[4 * 3 + 1] = cmul_tw<INV>(x[13], w3); x[4 * 3 + 2] = cmul_tw<INV>(x[14], w6); x[4 * 3 + 3] = cmul_tw<INV>(x[15], w9);
; __device__ __forceinline__ void fft_inv2(LAS f32x2* B, const LAS f32x2* TW2, int tid) {
;     asm volatile("" : "+v"(tid));
;     const int b = tid >> 5, n2 = tid & 31, base = 512 * b + n2; f32x2 x[16];
;     x[0] = B[fpad(base)];
; #pragma unroll
;     for (int k = 1; k < 16; ++k) x[k] = cmulc(B[fpad(base + 32 * k)], TW2[k * 32 + n2]);
;     dft16<true>(x);
	v_pk_mul_f32 v[166:167], v[118:119], v[184:185] op_sel:[1,1] op_sel_hi:[0,1]
	v_pk_fma_f32 v[118:119], v[118:119], v[184:185], v[166:167] op_sel_hi:[1,0,1] neg_hi:[0,0,1]
	ds_read_b64 v[182:183], v5 offset:1584
	ds_read_b64 v[102:103], v56 offset:1536
	ds_read_b64 v[110:111], v5 offset:1848
	ds_read_b64 v[186:187], v56 offset:1792
	ds_read_b64 v[104:105], v5 offset:2112
	ds_read_b64 v[180:181], v56 offset:2048
	ds_read_b64 v[112:113], v5 offset:2376
	ds_read_b64 v[174:175], v56 offset:2304
	ds_read_b64 v[120:121], v5 offset:2640
	ds_read_b64 v[166:167], v56 offset:2560
	s_waitcnt lgkmcnt(8)
	v_pk_mul_f32 v[168:169], v[182:183], v[102:103] op_sel:[1,1] op_sel_hi:[0,1]
	v_pk_fma_f32 v[182:183], v[182:183], v[102:103], v[168:169] op_sel_hi:[1,0,1] neg_hi:[0,0,1]
	s_waitcnt lgkmcnt(6)
	v_pk_mul_f32 v[176:177], v[110:111], v[186:187] op_sel:[1,1] op_sel_hi:[0,1]
	v_pk_fma_f32 v[110:111], v[110:111], v[186:187], v[176:177] op_sel_hi:[1,0,1] neg_hi:[0,0,1]
	s_waitcnt lgkmcnt(4)
	v_pk_mul_f32 v[178:179], v[104:105], v[180:181] op_sel:[1,1] op_sel_hi:[0,1]
	v_pk_fma_f32 v[104:105], v[104:105], v[180:181], v[178:179] op_sel_hi:[1,0,1] neg_hi:[0,0,1]
	s_waitcnt lgkmcnt(2)
	v_pk_mul_f32 v[188:189], v[112:113], v[174:175] op_sel:[1,1] op_sel_hi:[0,1]
	v_pk_fma_f32 v[112:113], v[112:113], v[174:175], v[188:189] op_sel_hi:[1,0,1] neg_hi:[0,0,1]
	s_waitcnt lgkmcnt(0)
	v_pk_mul_f32 v[184:185], v[120:121], v[166:167] op_sel:[1,1] op_sel_hi:[0,1]
	v_pk_fma_f32 v[120:121], v[120:121], v[166:167], v[184:185] op_sel_hi:[1,0,1] neg_hi:[0,0,1]
	ds_read_b64 v[128:129], v5 offset:2904
	ds_read_b64 v[168:169], v56 offset:2816
	ds_read_b64 v[106:107], v5 offset:3168
	ds_read_b64 v[176:177], v56 offset:3072
	ds_read_b64 v[114:115], v5 offset:3432
	ds_read_b64 v[178:179], v56 offset:3328
	ds_read_b64 v[122:123], v5 offset:3696
	ds_read_b64 v[188:189], v56 offset:3584
	ds_read_b64 v[130:131], v5 offset:3960
	ds_read_b64 v[184:185], v56 offset:3840
	s_waitcnt lgkmcnt(8)
	v_pk_mul_f32 v[102:103], v[128:129], v[168:169] op_sel:[1,1] op_sel_hi:[0,1]
	v_pk_fma_f32 v[128:129], v[128:129], v[168:169], v[102:103] op_sel_hi:[1,0,1] neg_hi:[0,0,1]
	s_waitcnt lgkmcnt(6)
	v_pk_mul_f32 v[186:187], v[106:107], v[176:177] op_sel:[1,1] op_sel_hi:[0,1]
	v_pk_fma_f32 v[106:107], v[106:107], v[176:177], v[186:187] op_sel_hi:[1,0,1] neg_hi:[0,0,1]
	s_waitcnt lgkmcnt(4)
	v_pk_mul_f32 v[180:181], v[114:115], v[178:179] op_sel:[1,1] op_sel_hi:[0,1]
	v_pk_fma_f32 v[114:115], v[114:115], v[178:179], v[180:181] op_sel_hi:[1,0,1] neg_hi:[0,0,1]
	s_waitcnt lgkmcnt(2)
	v_pk_mul_f32 v[174:175], v[122:123], v[188:189] op_sel:[1,1] op_sel_hi:[0,1]
	v_pk_fma_f32 v[122:123], v[122:123], v[188:189], v[174:175] op_sel_hi:[1,0,1] neg_hi:[0,0,1]
	s_waitcnt lgkmcnt(0)
	v_pk_mul_f32 v[166:167], v[130:131], v[184:185] op_sel:[1,1] op_sel_hi:[0,1]
	v_pk_fma_f32 v[130:131], v[130:131], v[184:185], v[166:167] op_sel_hi:[1,0,1] neg_hi:[0,0,1]
	v_pk_add_f32 v[102:103], v[100:101], v[104:105]
	v_pk_add_f32 v[186:187], v[100:101], v[104:105] neg_lo:[0,1] neg_hi:[0,1]
	v_pk_add_f32 v[180:181], v[126:127], v[106:107]
	v_pk_add_f32 v[174:175], v[126:127], v[106:107] neg_lo:[0,1] neg_hi:[0,1]
	v_pk_add_f32 v[100:101], v[102:103], v[180:181]
	v_pk_add_f32 v[104:105], v[102:103], v[180:181] neg_lo:[0,1] neg_hi:[0,1]
	v_pk_add_f32 v[126:127], v[186:187], v[174:175] op_sel:[0,1] op_sel_hi:[1,0] neg_lo:[0,1]
	v_pk_add_f32 v[106:107], v[186:187], v[174:175] op_sel:[0,1] op_sel_hi:[1,0] neg_hi:[0,1]
	v_pk_add_f32 v[166:167], v[108:109], v[112:113]
	v_pk_add_f32 v[168:169], v[108:109], v[112:113] neg_lo:[0,1] neg_hi:[0,1]
	v_pk_add_f32 v[176:177], v[118:119], v[114:115]
	v_pk_add_f32 v[178:179], v[118:119], v[114:115] neg_lo:[0,1] neg_hi:[0,1]
	v_pk_add_f32 v[108:109], v[166:167], v[176:177]
	v_pk_add_f32 v[112:113], v[166:167], v[176:177] neg_lo:[0,1] neg_hi:[0,1]
	v_pk_add_f32 v[118:119], v[168:169], v[178:179] op_sel:[0,1] op_sel_hi:[1,0] neg_lo:[0,1]
	v_pk_add_f32 v[114:115], v[168:169], v[178:179] op_sel:[0,1] op_sel_hi:[1,0] neg_hi:[0,1]
	v_pk_add_f32 v[188:189], v[116:117], v[120:121]
	v_pk_add_f32 v[184:185], v[116:117], v[120:121] neg_lo:[0,1] neg_hi:[0,1]
	v_pk_add_f32 v[102:103], v[182:183], v[122:123]
	v_pk_add_f32 v[186:187], v[182:183], v[122:123] neg_lo:[0,1] neg_hi:[0,1]
	v_pk_add_f32 v[116:117], v[188:189], v[102:103]
	v_pk_add_f32 v[120:121], v[188:189], v[102:103] neg_lo:[0,1] neg_hi:[0,1]
	v_pk_add_f32 v[182:183], v[184:185], v[186:187] op_sel:[0,1] op_sel_hi:[1,0] neg_lo:[0,1]
	v_pk_add_f32 v[122:123], v[184:185], v[186:187] op_sel:[0,1] op_sel_hi:[1,0] neg_hi:[0,1]
	v_pk_add_f32 v[180:181], v[124:125], v[128:129]
	v_pk_add_f32 v[174:175], v[124:125], v[128:129] neg_lo:[0,1] neg_hi:[0,1]
	v_pk_add_f32 v[166:167], v[110:111], v[130:131]
	v_pk_add_f32 v[168:169], v[110:111], v[130:131] neg_lo:[0,1] neg_hi:[0,1]
	v_pk_add_f32 v[124:125], v[180:181], v[166:167]
	v_pk_add_f32 v[128:129], v[180:181], v[166:167] neg_lo:[0,1] neg_hi:[0,1]
	v_pk_add_f32 v[110:111], v[174:175], v[168:169] op_sel:[0,1] op_sel_hi:[1,0] neg_lo:[0,1]
	v_pk_add_f32 v[130:131], v[174:175], v[168:169] op_sel:[0,1] op_sel_hi:[1,0] neg_hi:[0,1]
	v_pk_mul_f32 v[176:177], v[118:119], s[68:69] op_sel:[1,1] op_sel_hi:[0,1]
	v_pk_fma_f32 v[118:119], v[118:119], s[68:69], v[176:177] op_sel_hi:[1,0,1] neg_hi:[0,0,1]
	v_pk_mul_f32 v[178:179], v[182:183], s[84:85] op_sel:[1,1] op_sel_hi:[0,1]
	v_pk_fma_f32 v[182:183], v[182:183], s[84:85], v[178:179] op_sel_hi:[1,0,1] neg_hi:[0,0,1]
	v_pk_mul_f32 v[188:189], v[110:111], s[88:89] op_sel:[1,1] op_sel_hi:[0,1]
	v_pk_fma_f32 v[110:111], v[110:111], s[88:89], v[188:189] op_sel_hi:[1,0,1] neg_hi:[0,0,1]
; #define LAS __attribute__((address_space(3)))
; __device__ __forceinline__ f32x2 cmulc(f32x2 a, f32x2 b) { return (f32x2){a.x * b.x + a.y * b.y, a.y * b.x - a.x * b.y}; }
; __device__ __forceinline__ void fft_inv2(LAS f32x2* B, const LAS f32x2* TW2, int tid) {
;     ...
;     dft16<true>(x);
; #pragma unroll
;     for (int r = 0; r < 16; ++r) B[fpad(base + 32 * r)] = x[r];
; __device__ __forceinline__ void fft_inv1(f32x2 (&x)[16], const LAS f32x2* B, int n2, const f32x2 (&w)[16]) {
;     asm volatile("" : "+v"(n2));
;     x[0] = B[fpad(n2)];
; #pragma unroll
;     for (int k = 1; k < 16; ++k) x[k] = cmulc(B[fpad(512 * k + n2)], w[k]);
	v_pk_mul_f32 v[184:185], v[112:113], s[84:85] op_sel:[1,1] op_sel_hi:[0,1]
	v_pk_fma_f32 v[112:113], v[112:113], s[84:85], v[184:185] op_sel_hi:[1,0,1] neg_hi:[0,0,1]
	v_pk_mul_f32 v[102:103], v[128:129], s[90:91] op_sel:[1,1] op_sel_hi:[0,1]
	v_pk_fma_f32 v[128:129], v[128:129], s[90:91], v[102:103] op_sel_hi:[1,0,1] neg_hi:[0,0,1]
	v_pk_mul_f32 v[186:187], v[114:115], s[88:89] op_sel:[1,1] op_sel_hi:[0,1]
	v_pk_fma_f32 v[114:115], v[114:115], s[88:89], v[186:187] op_sel_hi:[1,0,1] neg_hi:[0,0,1]
	v_pk_mul_f32 v[180:181], v[122:123], s[90:91] op_sel:[1,1] op_sel_hi:[0,1]
	v_pk_fma_f32 v[122:123], v[122:123], s[90:91], v[180:181] op_sel_hi:[1,0,1] neg_hi:[0,0,1]
	v_pk_mul_f32 v[174:175], v[130:131], s[98:99] op_sel:[1,1] op_sel_hi:[0,1]
	v_pk_fma_f32 v[130:131], v[130:131], s[98:99], v[174:175] op_sel_hi:[1,0,1] neg_hi:[0,0,1]
	v_pk_add_f32 v[166:167], v[100:101], v[116:117]
	v_pk_add_f32 v[168:169], v[100:101], v[116:117] neg_lo:[0,1] neg_hi:[0,1]
	v_pk_add_f32 v[176:177], v[108:109], v[124:125]
	v_pk_add_f32 v[178:179], v[108:109], v[124:125] neg_lo:[0,1] neg_hi:[0,1]
	v_pk_add_f32 v[100:101], v[166:167], v[176:177]
	v_pk_add_f32 v[116:117], v[166:167], v[176:177] neg_lo:[0,1] neg_hi:[0,1]
	v_pk_add_f32 v[108:109], v[168:169], v[178:179] op_sel:[0,1] op_sel_hi:[1,0] neg_lo:[0,1]
	v_pk_add_f32 v[124:125], v[168:169], v[178:179] op_sel:[0,1] op_sel_hi:[1,0] neg_hi:[0,1]
	v_pk_add_f32 v[188:189], v[126:127], v[182:183]
	v_pk_add_f32 v[184:185], v[126:127], v[182:183] neg_lo:[0,1] neg_hi:[0,1]
	v_pk_add_f32 v[102:103], v[118:119], v[110:111]
	v_pk_add_f32 v[186:187], v[118:119], v[110:111] neg_lo:[0,1] neg_hi:[0,1]
	v_pk_add_f32 v[126:127], v[188:189], v[102:103]
	v_pk_add_f32 v[182:183], v[188:189], v[102:103] neg_lo:[0,1] neg_hi:[0,1]
	v_pk_add_f32 v[118:119], v[184:185], v[186:187] op_sel:[0,1] op_sel_hi:[1,0] neg_lo:[0,1]
	v_pk_add_f32 v[110:111], v[184:185], v[186:187] op_sel:[0,1] op_sel_hi:[1,0] neg_hi:[0,1]
	v_pk_add_f32 v[180:181], v[104:105], v[120:121] op_sel:[0,1] op_sel_hi:[1,0] neg_lo:[0,1]
	v_pk_add_f32 v[174:175], v[104:105], v[120:121] op_sel:[0,1] op_sel_hi:[1,0] neg_hi:[0,1]
	v_pk_add_f32 v[166:167], v[112:113], v[128:129]
	v_pk_add_f32 v[168:169], v[112:113], v[128:129] neg_lo:[0,1] neg_hi:[0,1]
	v_pk_add_f32 v[104:105], v[180:181], v[166:167]
	v_pk_add_f32 v[120:121], v[180:181], v[166:167] neg_lo:[0,1] neg_hi:[0,1]
	v_pk_add_f32 v[112:113], v[174:175], v[168:169] op_sel:[0,1] op_sel_hi:[1,0] neg_lo:[0,1]
	v_pk_add_f32 v[128:129], v[174:175], v[168:169] op_sel:[0,1] op_sel_hi:[1,0] neg_hi:[0,1]
	v_pk_add_f32 v[176:177], v[106:107], v[122:123]
	v_pk_add_f32 v[178:179], v[106:107], v[122:123] neg_lo:[0,1] neg_hi:[0,1]
	v_pk_add_f32 v[188:189], v[114:115], v[130:131]
	v_pk_add_f32 v[184:185], v[114:115], v[130:131] neg_lo:[0,1] neg_hi:[0,1]
	v_pk_add_f32 v[106:107], v[176:177], v[188:189]
	v_pk_add_f32 v[122:123], v[176:177], v[188:189] neg_lo:[0,1] neg_hi:[0,1]
	v_pk_add_f32 v[114:115], v[178:179], v[184:185] op_sel:[0,1] op_sel_hi:[1,0] neg_lo:[0,1]
	v_pk_add_f32 v[130:131], v[178:179], v[184:185] op_sel:[0,1] op_sel_hi:[1,0] neg_hi:[0,1]
	ds_write_b64 v5, v[100:101]
	ds_write_b64 v5, v[126:127] offset:264
	ds_write_b64 v5, v[104:105] offset:528
	ds_write_b64 v5, v[106:107] offset:792
	ds_write_b64 v5, v[108:109] offset:1056
	ds_write_b64 v5, v[118:119] offset:1320
	ds_write_b64 v5, v[112:113] offset:1584
	ds_write_b64 v5, v[114:115] offset:1848
	ds_write_b64 v5, v[116:117] offset:2112
	ds_write_b64 v5, v[182:183] offset:2376
	ds_write_b64 v5, v[120:121] offset:2640
	ds_write_b64 v5, v[122:123] offset:2904
	ds_write_b64 v5, v[124:125] offset:3168
	ds_write_b64 v5, v[110:111] offset:3432
	ds_write_b64 v5, v[128:129] offset:3696
	ds_write_b64 v5, v[130:131] offset:3960
	s_waitcnt lgkmcnt(0)
	s_barrier
	ds_read_b64 v[100:101], v3
	ds_read_b64 v[108:109], v3 offset:16896
	ds_read_b64 v[116:117], v3 offset:33792
	ds_read_b64 v[124:125], v3 offset:50688
	ds_read_b64 v[126:127], v3 offset:4224
	ds_read_b64 v[118:119], v3 offset:21120
	ds_read_b64 v[182:183], v3 offset:38016
	ds_read_b64 v[110:111], v3 offset:54912
	ds_read_b64 v[104:105], v3 offset:8448
	ds_read_b64 v[112:113], v3 offset:25344
	ds_read_b64 v[120:121], v3 offset:42240
	ds_read_b64 v[128:129], v3 offset:59136
	ds_read_b64 v[106:107], v3 offset:12672
	ds_read_b64 v[114:115], v3 offset:29568
	ds_read_b64 v[122:123], v3 offset:46464
	ds_read_b64 v[130:131], v3 offset:63360
	s_waitcnt lgkmcnt(14)
	v_pk_mul_f32 v[102:103], v[108:109], v[12:13] op_sel:[1,1] op_sel_hi:[0,1]
	v_pk_fma_f32 v[108:109], v[108:109], v[12:13], v[102:103] op_sel_hi:[1,0,1] neg_hi:[0,0,1]
	s_waitcnt lgkmcnt(13)
	v_pk_mul_f32 v[186:187], v[116:117], v[20:21] op_sel:[1,1] op_sel_hi:[0,1]
	v_pk_fma_f32 v[116:117], v[116:117], v[20:21], v[186:187] op_sel_hi:[1,0,1] neg_hi:[0,0,1]
	s_waitcnt lgkmcnt(12)
	v_pk_mul_f32 v[180:181], v[124:125], v[28:29] op_sel:[1,1] op_sel_hi:[0,1]
	v_pk_fma_f32 v[124:125], v[124:125], v[28:29], v[180:181] op_sel_hi:[1,0,1] neg_hi:[0,0,1]
	s_waitcnt lgkmcnt(11)
	v_pk_mul_f32 v[174:175], v[126:127], v[6:7] op_sel:[1,1] op_sel_hi:[0,1]
	v_pk_fma_f32 v[126:127], v[126:127], v[6:7], v[174:175] op_sel_hi:[1,0,1] neg_hi:[0,0,1]
	s_waitcnt lgkmcnt(10)
	v_pk_mul_f32 v[166:167], v[118:119], v[14:15] op_sel:[1,1] op_sel_hi:[0,1]
	v_pk_fma_f32 v[118:119], v[118:119], v[14:15], v[166:167] op_sel_hi:[1,0,1] neg_hi:[0,0,1]
	s_waitcnt lgkmcnt(9)
	v_pk_mul_f32 v[168:169], v[182:183], v[22:23] op_sel:[1,1] op_sel_hi:[0,1]
	v_pk_fma_f32 v[182:183], v[182:183], v[22:23], v[168:169] op_sel_hi:[1,0,1] neg_hi:[0,0,1]
	s_waitcnt lgkmcnt(8)
; #define LAS __attribute__((address_space(3)))
; __device__ __forceinline__ f32x2 cmulc(f32x2 a, f32x2 b) { return (f32x2){a.x * b.x + a.y * b.y, a.y * b.x - a.x * b.y}; }
; __device__ __forceinline__ void dft16_inv_lo(f32x2 (&x)[16]) {
;     constexpr float C1 = 0.92387953251128674f, S1 = 0.38268343236508977f, C2 = 0.70710678118654752f;
; #pragma unroll
;     for (int b = 0; b < 4; ++b) dft4<true>(x[b], x[4 + b], x[8 + b], x[12 + b]);
;     const f32x2 w1 = {C1, -S1}, w2 = {C2, -C2}, w3 = {S1, -C1}, w4 = {0.f, -1.f}, w6 = {-C2, -C2}, w9 = {-C1, S1};
;     x[5] = cmulc(x[5], w1); x[6] = cmulc(x[6], w2); x[7] = cmulc(x[7], w3);
;     x[9] = cmulc(x[9], w2); x[10] = cmulc(x[10], w4); x[11] = cmulc(x[11], w6);
;     x[13] = cmulc(x[13], w3); x[14] = cmulc(x[14], w6); x[15] = cmulc(x[15], w9);
;     f32x2 y[8];
; #pragma unroll
;     for (int c = 0; c < 4; ++c) { const f32x2 t0 = x[4 * c] + x[4 * c + 2], t1 = x[4 * c] - x[4 * c + 2], t2 = x[4 * c + 1] + x[4 * c + 3], t3 = x[4 * c + 1] - x[4 * c + 3];
;         y[c] = t0 + t2; y[4 + c] = t1 + (f32x2){-t3.y, t3.x}; }
; #pragma unroll
;     for (int k = 0; k < 8; ++k) x[k] = y[k];
; __device__ __forceinline__ void fft_inv1(f32x2 (&x)[16], const LAS f32x2* B, int n2, const f32x2 (&w)[16]) {
;     asm volatile("" : "+v"(n2));
;     x[0] = B[fpad(n2)];
; #pragma unroll
;     for (int k = 1; k < 16; ++k) x[k] = cmulc(B[fpad(512 * k + n2)], w[k]);
;     dft16_inv_lo(x);
	v_pk_mul_f32 v[176:177], v[110:111], v[30:31] op_sel:[1,1] op_sel_hi:[0,1]
	v_pk_fma_f32 v[110:111], v[110:111], v[30:31], v[176:177] op_sel_hi:[1,0,1] neg_hi:[0,0,1]
	s_waitcnt lgkmcnt(7)
	v_pk_mul_f32 v[178:179], v[104:105], v[8:9] op_sel:[1,1] op_sel_hi:[0,1]
	v_pk_fma_f32 v[104:105], v[104:105], v[8:9], v[178:179] op_sel_hi:[1,0,1] neg_hi:[0,0,1]
	s_waitcnt lgkmcnt(6)
	v_pk_mul_f32 v[188:189], v[112:113], v[16:17] op_sel:[1,1] op_sel_hi:[0,1]
	v_pk_fma_f32 v[112:113], v[112:113], v[16:17], v[188:189] op_sel_hi:[1,0,1] neg_hi:[0,0,1]
	s_waitcnt lgkmcnt(5)
	v_pk_mul_f32 v[184:185], v[120:121], v[24:25] op_sel:[1,1] op_sel_hi:[0,1]
	v_pk_fma_f32 v[120:121], v[120:121], v[24:25], v[184:185] op_sel_hi:[1,0,1] neg_hi:[0,0,1]
	s_waitcnt lgkmcnt(4)
	v_pk_mul_f32 v[102:103], v[128:129], v[32:33] op_sel:[1,1] op_sel_hi:[0,1]
	v_pk_fma_f32 v[128:129], v[128:129], v[32:33], v[102:103] op_sel_hi:[1,0,1] neg_hi:[0,0,1]
	s_waitcnt lgkmcnt(3)
	v_pk_mul_f32 v[186:187], v[106:107], v[10:11] op_sel:[1,1] op_sel_hi:[0,1]
	v_pk_fma_f32 v[106:107], v[106:107], v[10:11], v[186:187] op_sel_hi:[1,0,1] neg_hi:[0,0,1]
	s_waitcnt lgkmcnt(2)
	v_pk_mul_f32 v[180:181], v[114:115], v[18:19] op_sel:[1,1] op_sel_hi:[0,1]
	v_pk_fma_f32 v[114:115], v[114:115], v[18:19], v[180:181] op_sel_hi:[1,0,1] neg_hi:[0,0,1]
	s_waitcnt lgkmcnt(1)
	v_pk_mul_f32 v[174:175], v[122:123], v[26:27] op_sel:[1,1] op_sel_hi:[0,1]
	v_pk_fma_f32 v[122:123], v[122:123], v[26:27], v[174:175] op_sel_hi:[1,0,1] neg_hi:[0,0,1]
	s_waitcnt lgkmcnt(0)
	v_pk_mul_f32 v[166:167], v[130:131], v[34:35] op_sel:[1,1] op_sel_hi:[0,1]
	v_pk_fma_f32 v[130:131], v[130:131], v[34:35], v[166:167] op_sel_hi:[1,0,1] neg_hi:[0,0,1]
	v_pk_add_f32 v[168:169], v[100:101], v[116:117]
	v_pk_add_f32 v[176:177], v[100:101], v[116:117] neg_lo:[0,1] neg_hi:[0,1]
	v_pk_add_f32 v[178:179], v[108:109], v[124:125]
	v_pk_add_f32 v[188:189], v[108:109], v[124:125] neg_lo:[0,1] neg_hi:[0,1]
	v_pk_add_f32 v[100:101], v[168:169], v[178:179]
	v_pk_add_f32 v[116:117], v[168:169], v[178:179] neg_lo:[0,1] neg_hi:[0,1]
	v_pk_add_f32 v[108:109], v[176:177], v[188:189] op_sel:[0,1] op_sel_hi:[1,0] neg_lo:[0,1]
	v_pk_add_f32 v[124:125], v[176:177], v[188:189] op_sel:[0,1] op_sel_hi:[1,0] neg_hi:[0,1]
	v_pk_add_f32 v[184:185], v[126:127], v[182:183]
	v_pk_add_f32 v[102:103], v[126:127], v[182:183] neg_lo:[0,1] neg_hi:[0,1]
	v_pk_add_f32 v[186:187], v[118:119], v[110:111]
	v_pk_add_f32 v[180:181], v[118:119], v[110:111] neg_lo:[0,1] neg_hi:[0,1]
	v_pk_add_f32 v[126:127], v[184:185], v[186:187]
	v_pk_add_f32 v[182:183], v[184:185], v[186:187] neg_lo:[0,1] neg_hi:[0,1]
	v_pk_add_f32 v[118:119], v[102:103], v[180:181] op_sel:[0,1] op_sel_hi:[1,0] neg_lo:[0,1]
	v_pk_add_f32 v[110:111], v[102:103], v[180:181] op_sel:[0,1] op_sel_hi:[1,0] neg_hi:[0,1]
	v_pk_add_f32 v[174:175], v[104:105], v[120:121]
	v_pk_add_f32 v[166:167], v[104:105], v[120:121] neg_lo:[0,1] neg_hi:[0,1]
	v_pk_add_f32 v[168:169], v[112:113], v[128:129]
	v_pk_add_f32 v[176:177], v[112:113], v[128:129] neg_lo:[0,1] neg_hi:[0,1]
	v_pk_add_f32 v[104:105], v[174:175], v[168:169]
	v_pk_add_f32 v[120:121], v[174:175], v[168:169] neg_lo:[0,1] neg_hi:[0,1]
	v_pk_add_f32 v[112:113], v[166:167], v[176:177] op_sel:[0,1] op_sel_hi:[1,0] neg_lo:[0,1]
	v_pk_add_f32 v[128:129], v[166:167], v[176:177] op_sel:[0,1] op_sel_hi:[1,0] neg_hi:[0,1]
	v_pk_add_f32 v[178:179], v[106:107], v[122:123]
	v_pk_add_f32 v[188:189], v[106:107], v[122:123] neg_lo:[0,1] neg_hi:[0,1]
	v_pk_add_f32 v[184:185], v[114:115], v[130:131]
	v_pk_add_f32 v[102:103], v[114:115], v[130:131] neg_lo:[0,1] neg_hi:[0,1]
	v_pk_add_f32 v[106:107], v[178:179], v[184:185]
	v_pk_add_f32 v[122:123], v[178:179], v[184:185] neg_lo:[0,1] neg_hi:[0,1]
	v_pk_add_f32 v[114:115], v[188:189], v[102:103] op_sel:[0,1] op_sel_hi:[1,0] neg_lo:[0,1]
	v_pk_add_f32 v[130:131], v[188:189], v[102:103] op_sel:[0,1] op_sel_hi:[1,0] neg_hi:[0,1]
	v_pk_mul_f32 v[186:187], v[118:119], s[68:69] op_sel:[1,1] op_sel_hi:[0,1]
	v_pk_fma_f32 v[118:119], v[118:119], s[68:69], v[186:187] op_sel_hi:[1,0,1] neg_hi:[0,0,1]
	v_pk_mul_f32 v[180:181], v[112:113], s[84:85] op_sel:[1,1] op_sel_hi:[0,1]
	v_pk_fma_f32 v[112:113], v[112:113], s[84:85], v[180:181] op_sel_hi:[1,0,1] neg_hi:[0,0,1]
	v_pk_mul_f32 v[174:175], v[114:115], s[88:89] op_sel:[1,1] op_sel_hi:[0,1]
	v_pk_fma_f32 v[114:115], v[114:115], s[88:89], v[174:175] op_sel_hi:[1,0,1] neg_hi:[0,0,1]
	v_pk_mul_f32 v[166:167], v[182:183], s[84:85] op_sel:[1,1] op_sel_hi:[0,1]
	v_pk_fma_f32 v[182:183], v[182:183], s[84:85], v[166:167] op_sel_hi:[1,0,1] neg_hi:[0,0,1]
	v_pk_mul_f32 v[168:169], v[122:123], s[90:91] op_sel:[1,1] op_sel_hi:[0,1]
	v_pk_fma_f32 v[122:123], v[122:123], s[90:91], v[168:169] op_sel_hi:[1,0,1] neg_hi:[0,0,1]
	v_pk_mul_f32 v[176:177], v[110:111], s[88:89] op_sel:[1,1] op_sel_hi:[0,1]
	v_pk_fma_f32 v[110:111], v[110:111], s[88:89], v[176:177] op_sel_hi:[1,0,1] neg_hi:[0,0,1]
	v_pk_mul_f32 v[178:179], v[128:129], s[90:91] op_sel:[1,1] op_sel_hi:[0,1]
	v_pk_fma_f32 v[128:129], v[128:129], s[90:91], v[178:179] op_sel_hi:[1,0,1] neg_hi:[0,0,1]
	v_pk_mul_f32 v[188:189], v[130:131], s[98:99] op_sel:[1,1] op_sel_hi:[0,1]
	v_pk_fma_f32 v[130:131], v[130:131], s[98:99], v[188:189] op_sel_hi:[1,0,1] neg_hi:[0,0,1]
	v_pk_add_f32 v[184:185], v[100:101], v[104:105]
	v_pk_add_f32 v[102:103], v[100:101], v[104:105] neg_lo:[0,1] neg_hi:[0,1]
	v_pk_add_f32 v[186:187], v[126:127], v[106:107]
	v_pk_add_f32 v[180:181], v[126:127], v[106:107] neg_lo:[0,1] neg_hi:[0,1]
	v_pk_add_f32 v[100:101], v[184:185], v[186:187]
	v_pk_add_f32 v[126:127], v[102:103], v[180:181] op_sel:[0,1] op_sel_hi:[1,0] neg_lo:[0,1]
	v_pk_add_f32 v[174:175], v[108:109], v[112:113]
	v_pk_add_f32 v[166:167], v[108:109], v[112:113] neg_lo:[0,1] neg_hi:[0,1]
	v_pk_add_f32 v[168:169], v[118:119], v[114:115]
	v_pk_add_f32 v[176:177], v[118:119], v[114:115] neg_lo:[0,1] neg_hi:[0,1]
	v_pk_add_f32 v[108:109], v[174:175], v[168:169]
	v_pk_add_f32 v[118:119], v[166:167], v[176:177] op_sel:[0,1] op_sel_hi:[1,0] neg_lo:[0,1]
	v_pk_add_f32 v[178:179], v[116:117], v[120:121] op_sel:[0,1] op_sel_hi:[1,0] neg_lo:[0,1]
	v_pk_add_f32 v[188:189], v[116:117], v[120:121] op_sel:[0,1] op_sel_hi:[1,0] neg_hi:[0,1]
	v_pk_add_f32 v[184:185], v[182:183], v[122:123]
	v_pk_add_f32 v[102:103], v[182:183], v[122:123] neg_lo:[0,1] neg_hi:[0,1]
	v_pk_add_f32 v[116:117], v[178:179], v[184:185]
	v_pk_add_f32 v[182:183], v[188:189], v[102:103] op_sel:[0,1] op_sel_hi:[1,0] neg_lo:[0,1]
	v_pk_add_f32 v[186:187], v[124:125], v[128:129]
	v_pk_add_f32 v[180:181], v[124:125], v[128:129] neg_lo:[0,1] neg_hi:[0,1]
	v_pk_add_f32 v[174:175], v[110:111], v[130:131]
	v_pk_add_f32 v[166:167], v[110:111], v[130:131] neg_lo:[0,1] neg_hi:[0,1]
	v_pk_add_f32 v[124:125], v[186:187], v[174:175]
	v_pk_add_f32 v[110:111], v[180:181], v[166:167] op_sel:[0,1] op_sel_hi:[1,0] neg_lo:[0,1]
	s_load_dword s35, s[50:51], 0x1000
	s_mul_i32 s43, s80, 0x8800
	s_add_u32 s46, s40, s43
	s_addc_u32 s47, s41, 0
	s_waitcnt lgkmcnt(0)
; __device__ __forceinline__ void hyena_fft(LAS unsigned char* lds, int layer, int G, const int wave_s) {
;     ...
;             { const float fb1 = fbias[HY + c]; float* zo = ZT + (size_t)c * MT;
; #pragma unroll
;               for (int r = 0; r < 8; ++r) { const int t = n2 + 512 * r;
;                   zo[t] = ux[r][0] * (x[r].x + fb1 * uz[r][0]); zo[SEQ + t] = ux[r][1] * (x[r].y + fb1 * uz[r][1]); } }
;         }
	v_mov_b32_e32 v194, s35
	v_pk_fma_f32 v[168:169], v[132:133], v[194:195], v[100:101] op_sel_hi:[1,0,1]
	v_pk_mul_f32 v[168:169], v[148:149], v[168:169]
	s_add_u32 s60, s46, 0
	s_addc_u32 s61, s47, 0
	s_add_u32 s62, s60, 0x4000
	s_addc_u32 s63, s61, 0
	global_store_dword v212, v168, s[60:61]
	global_store_dword v212, v169, s[62:63]
	v_pk_fma_f32 v[176:177], v[134:135], v[194:195], v[108:109] op_sel_hi:[1,0,1]
	v_pk_mul_f32 v[176:177], v[150:151], v[176:177]
	global_store_dword v212, v176, s[60:61] offset:2048
	global_store_dword v212, v177, s[62:63] offset:2048
	v_pk_fma_f32 v[178:179], v[136:137], v[194:195], v[116:117] op_sel_hi:[1,0,1]
	v_pk_mul_f32 v[178:179], v[152:153], v[178:179]
	s_add_u32 s60, s46, 0x1000
	s_addc_u32 s61, s47, 0
	s_add_u32 s62, s60, 0x4000
	s_addc_u32 s63, s61, 0
	global_store_dword v212, v178, s[60:61]
	global_store_dword v212, v179, s[62:63]
	v_pk_fma_f32 v[188:189], v[138:139], v[194:195], v[124:125] op_sel_hi:[1,0,1]
	v_pk_mul_f32 v[188:189], v[154:155], v[188:189]
	global_store_dword v212, v188, s[60:61] offset:2048
	global_store_dword v212, v189, s[62:63] offset:2048
	v_pk_fma_f32 v[184:185], v[140:141], v[194:195], v[126:127] op_sel_hi:[1,0,1]
	v_pk_mul_f32 v[184:185], v[158:159], v[184:185]
	s_add_u32 s60, s46, 0x2000
	s_addc_u32 s61, s47, 0
	s_add_u32 s62, s60, 0x4000
	s_addc_u32 s63, s61, 0
	global_store_dword v212, v184, s[60:61]
	global_store_dword v212, v185, s[62:63]
	v_pk_fma_f32 v[102:103], v[142:143], v[194:195], v[118:119] op_sel_hi:[1,0,1]
	v_pk_mul_f32 v[102:103], v[160:161], v[102:103]
	global_store_dword v212, v102, s[60:61] offset:2048
	global_store_dword v212, v103, s[62:63] offset:2048
	v_pk_fma_f32 v[186:187], v[144:145], v[194:195], v[182:183] op_sel_hi:[1,0,1]
	v_pk_mul_f32 v[186:187], v[162:163], v[186:187]
	s_add_u32 s60, s46, 0x3000
	s_addc_u32 s61, s47, 0
	s_add_u32 s62, s60, 0x4000
	s_addc_u32 s63, s61, 0
	global_store_dword v212, v186, s[60:61]
	global_store_dword v212, v187, s[62:63]
	v_pk_fma_f32 v[180:181], v[146:147], v[194:195], v[110:111] op_sel_hi:[1,0,1]
	v_pk_mul_f32 v[180:181], v[164:165], v[180:181]
	global_store_dword v212, v180, s[60:61] offset:2048
	global_store_dword v212, v181, s[62:63] offset:2048
	s_add_u32 s80, s80, 1
	s_cmp_lt_i32 s80, s93
	s_cbranch_scc1 .Lhfft_loop
	s_waitcnt vmcnt(0) lgkmcnt(0)
